# first K iteration of each tile peeled with C=0 on first MFMA per accumulator (no 128 v_mov accumulator reset) + tile-transition barrier change
# speedup vs baseline: 1.0102x; 1.0102x over previous
.LBB0_210:
	s_ashr_i32 s41, s40, 31
	s_lshl_b64 s[12:13], s[40:41], 19
	s_add_u32 s42, s14, s12
	s_addc_u32 s43, s15, s13
	s_and_b64 s[12:13], s[4:5], exec
	s_cselect_b32 s7, s43, s51
	s_cselect_b32 s8, s42, s50
	s_ashr_i32 s29, s28, 31
	s_lshl_b64 s[12:13], s[28:29], 19
	s_add_u32 s48, s59, s12
	s_addc_u32 s49, s62, s13
	s_and_b64 s[12:13], s[4:5], exec
	s_cselect_b32 s12, s49, s53
	s_cselect_b32 s13, s48, s52
	s_add_u32 s50, s50, 0x40080
	s_addc_u32 s51, s51, 0
	s_add_u32 s29, s52, 0x100
	s_addc_u32 s41, s53, 0
	s_mov_b32 s86, -2
	s_waitcnt lgkmcnt(0)
	s_cmp_lg_u32 s84, 1
	s_cselect_b32 s100, s99, 0
	s_cmp_lg_u32 s100, 0
	s_cbranch_scc0 .Lmy_nobar2_2
	s_barrier
.Lmy_nobar2_2:
	ds_read_b128 v[152:155], v157
	ds_read_b128 v[160:163], v157 offset:1024
	ds_read_b128 v[164:167], v157 offset:2048
	ds_read_b128 v[168:171], v157 offset:3072
	ds_read_b128 v[172:175], v158
	ds_read_b128 v[176:179], v158 offset:1024
	ds_read_b128 v[180:183], v158 offset:2048
	ds_read_b128 v[184:187], v158 offset:3072
	s_add_u32 s34, s50, 0xfffc0080
	s_addc_u32 s35, s51, -1
	s_cmp_eq_u32 s86, 12
	s_cselect_b32 s55, s7, s35
	s_cselect_b32 s54, s8, s34
	s_cselect_b32 s53, s12, s41
	s_cselect_b32 s52, s13, s29
	v_lshl_add_u64 v[220:221], s[50:51], 0, v[144:145]
	s_add_i32 m0, s63, 0xc000
	ds_read_b128 v[188:191], v159
	ds_read_b128 v[192:195], v159 offset:1024
	ds_read_b128 v[196:199], v159 offset:2048
	ds_read_b128 v[200:203], v159 offset:3072
	ds_read_b128 v[204:207], v159 offset:4096
	ds_read_b128 v[208:211], v159 offset:5120
	ds_read_b128 v[212:215], v159 offset:6144
	ds_read_b128 v[216:219], v159 offset:7168
	global_load_lds_dwordx4 v[220:221], off
	v_lshl_add_u64 v[220:221], s[50:51], 0, v[146:147]
	s_add_i32 m0, s63, 0xe000
	s_nop 0
	global_load_lds_dwordx4 v[220:221], off
	s_waitcnt vmcnt(8)
	s_waitcnt lgkmcnt(0)
	s_barrier
	s_setprio 1
	s_waitcnt lgkmcnt(0)
	v_mfma_f32_16x16x32_bf16 v[124:127], v[152:155], v[188:191], 0
	v_mfma_f32_16x16x32_bf16 v[120:123], v[164:167], v[188:191], 0
	v_mfma_f32_16x16x32_bf16 v[108:111], v[152:155], v[196:199], 0
	v_mfma_f32_16x16x32_bf16 v[104:107], v[164:167], v[196:199], 0
	v_mfma_f32_16x16x32_bf16 v[92:95], v[152:155], v[204:207], 0
	v_mfma_f32_16x16x32_bf16 v[88:91], v[164:167], v[204:207], 0
	v_mfma_f32_16x16x32_bf16 v[76:79], v[152:155], v[212:215], 0
	v_mfma_f32_16x16x32_bf16 v[72:75], v[164:167], v[212:215], 0
	v_mfma_f32_16x16x32_bf16 v[124:127], v[160:163], v[192:195], v[124:127]
	v_mfma_f32_16x16x32_bf16 v[120:123], v[168:171], v[192:195], v[120:123]
	v_mfma_f32_16x16x32_bf16 v[108:111], v[160:163], v[200:203], v[108:111]
	v_mfma_f32_16x16x32_bf16 v[104:107], v[168:171], v[200:203], v[104:107]
	v_mfma_f32_16x16x32_bf16 v[92:95], v[160:163], v[208:211], v[92:95]
	v_mfma_f32_16x16x32_bf16 v[88:91], v[168:171], v[208:211], v[88:91]
	v_mfma_f32_16x16x32_bf16 v[76:79], v[160:163], v[216:219], v[76:79]
	v_mfma_f32_16x16x32_bf16 v[72:75], v[168:171], v[216:219], v[72:75]
	s_setprio 0
	s_setprio 1
	v_mfma_f32_16x16x32_bf16 v[116:119], v[172:175], v[188:191], 0
	v_mfma_f32_16x16x32_bf16 v[112:115], v[180:183], v[188:191], 0
	v_mfma_f32_16x16x32_bf16 v[100:103], v[172:175], v[196:199], 0
	v_mfma_f32_16x16x32_bf16 v[96:99], v[180:183], v[196:199], 0
	v_mfma_f32_16x16x32_bf16 v[84:87], v[172:175], v[204:207], 0
	v_mfma_f32_16x16x32_bf16 v[80:83], v[180:183], v[204:207], 0
	v_mfma_f32_16x16x32_bf16 v[68:71], v[172:175], v[212:215], 0
	v_mfma_f32_16x16x32_bf16 v[64:67], v[180:183], v[212:215], 0
	v_mfma_f32_16x16x32_bf16 v[116:119], v[176:179], v[192:195], v[116:119]
	v_mfma_f32_16x16x32_bf16 v[112:115], v[184:187], v[192:195], v[112:115]
	v_mfma_f32_16x16x32_bf16 v[100:103], v[176:179], v[200:203], v[100:103]
	v_mfma_f32_16x16x32_bf16 v[96:99], v[184:187], v[200:203], v[96:99]
	v_mfma_f32_16x16x32_bf16 v[84:87], v[176:179], v[208:211], v[84:87]
	v_mfma_f32_16x16x32_bf16 v[80:83], v[184:187], v[208:211], v[80:83]
	v_mfma_f32_16x16x32_bf16 v[68:71], v[176:179], v[216:219], v[68:71]
	v_mfma_f32_16x16x32_bf16 v[64:67], v[184:187], v[216:219], v[64:67]
	s_setprio 0
	s_barrier
	s_add_i32 s34, s82, s58
	v_lshl_add_u64 v[220:221], s[52:53], 0, v[136:137]
	s_mov_b32 m0, s34
	ds_read_b128 v[188:191], v159 offset:16384
	ds_read_b128 v[192:195], v159 offset:17408
	ds_read_b128 v[196:199], v159 offset:18432
	ds_read_b128 v[200:203], v159 offset:19456
	ds_read_b128 v[204:207], v159 offset:20480
	ds_read_b128 v[208:211], v159 offset:21504
	ds_read_b128 v[212:215], v159 offset:22528
	ds_read_b128 v[216:219], v159 offset:23552
	global_load_lds_dwordx4 v[220:221], off
	s_add_i32 m0, s34, 0x2000
	s_add_u32 s34, s52, 0x40000
	v_lshl_add_u64 v[222:223], s[52:53], 0, v[140:141]
	s_addc_u32 s35, s53, 0
	s_add_i32 s87, s83, s58
	global_load_lds_dwordx4 v[222:223], off
	v_lshl_add_u64 v[224:225], s[34:35], 0, v[136:137]
	s_mov_b32 m0, s87
	v_lshl_add_u64 v[226:227], s[54:55], 0, v[138:139]
	global_load_lds_dwordx4 v[224:225], off
	v_lshl_add_u64 v[224:225], s[34:35], 0, v[140:141]
	s_add_i32 m0, s87, 0x2000
	s_nop 0
	global_load_lds_dwordx4 v[224:225], off
	v_lshl_add_u64 v[224:225], s[54:55], 0, v[134:135]
	s_mov_b32 m0, s63
	s_nop 0
	global_load_lds_dwordx4 v[224:225], off
	s_mov_b32 m0, s64
	s_nop 0
	global_load_lds_dwordx4 v[226:227], off
	s_waitcnt vmcnt(8)
	s_waitcnt lgkmcnt(0)
	s_barrier
	s_setprio 1
	s_waitcnt lgkmcnt(0)
	v_mfma_f32_16x16x32_bf16 v[60:63], v[152:155], v[188:191], 0
	v_mfma_f32_16x16x32_bf16 v[56:59], v[164:167], v[188:191], 0
	v_mfma_f32_16x16x32_bf16 v[44:47], v[152:155], v[196:199], 0
	v_mfma_f32_16x16x32_bf16 v[40:43], v[164:167], v[196:199], 0
	v_mfma_f32_16x16x32_bf16 v[28:31], v[152:155], v[204:207], 0
	v_mfma_f32_16x16x32_bf16 v[24:27], v[164:167], v[204:207], 0
	v_mfma_f32_16x16x32_bf16 v[12:15], v[152:155], v[212:215], 0
	v_mfma_f32_16x16x32_bf16 v[8:11], v[164:167], v[212:215], 0
	v_mfma_f32_16x16x32_bf16 v[60:63], v[160:163], v[192:195], v[60:63]
	v_mfma_f32_16x16x32_bf16 v[56:59], v[168:171], v[192:195], v[56:59]
	v_mfma_f32_16x16x32_bf16 v[44:47], v[160:163], v[200:203], v[44:47]
	v_mfma_f32_16x16x32_bf16 v[40:43], v[168:171], v[200:203], v[40:43]
	v_mfma_f32_16x16x32_bf16 v[28:31], v[160:163], v[208:211], v[28:31]
	v_mfma_f32_16x16x32_bf16 v[24:27], v[168:171], v[208:211], v[24:27]
	v_mfma_f32_16x16x32_bf16 v[12:15], v[160:163], v[216:219], v[12:15]
	v_mfma_f32_16x16x32_bf16 v[8:11], v[168:171], v[216:219], v[8:11]
	s_setprio 0
	s_setprio 1
	v_mfma_f32_16x16x32_bf16 v[52:55], v[172:175], v[188:191], 0
	v_mfma_f32_16x16x32_bf16 v[48:51], v[180:183], v[188:191], 0
	v_mfma_f32_16x16x32_bf16 v[36:39], v[172:175], v[196:199], 0
	v_mfma_f32_16x16x32_bf16 v[32:35], v[180:183], v[196:199], 0
	v_mfma_f32_16x16x32_bf16 v[20:23], v[172:175], v[204:207], 0
	v_mfma_f32_16x16x32_bf16 v[16:19], v[180:183], v[204:207], 0
	v_mfma_f32_16x16x32_bf16 v[4:7], v[172:175], v[212:215], 0
	v_mfma_f32_16x16x32_bf16 v[0:3], v[180:183], v[212:215], 0
	v_mfma_f32_16x16x32_bf16 v[52:55], v[176:179], v[192:195], v[52:55]
	v_mfma_f32_16x16x32_bf16 v[48:51], v[184:187], v[192:195], v[48:51]
	v_mfma_f32_16x16x32_bf16 v[36:39], v[176:179], v[200:203], v[36:39]
	v_mfma_f32_16x16x32_bf16 v[32:35], v[184:187], v[200:203], v[32:35]
	v_mfma_f32_16x16x32_bf16 v[20:23], v[176:179], v[208:211], v[20:23]
	v_mfma_f32_16x16x32_bf16 v[16:19], v[184:187], v[208:211], v[16:19]
	v_mfma_f32_16x16x32_bf16 v[4:7], v[176:179], v[216:219], v[4:7]
	v_mfma_f32_16x16x32_bf16 v[0:3], v[184:187], v[216:219], v[0:3]
	s_setprio 0
	s_barrier
	s_add_i32 s87, 0, 0x18000
	v_add_u32_e32 v142, s87, v133
	s_add_i32 s88, 0, 0x1c000
	ds_read_b128 v[152:155], v142
	ds_read_b128 v[160:163], v142 offset:1024
	ds_read_b128 v[164:167], v142 offset:2048
	ds_read_b128 v[168:171], v142 offset:3072
	v_add_u32_e32 v142, s88, v133
	ds_read_b128 v[172:175], v142
	ds_read_b128 v[176:179], v142 offset:1024
	ds_read_b128 v[180:183], v142 offset:2048
	ds_read_b128 v[184:187], v142 offset:3072
	s_add_u32 s34, s54, 0x40000
	s_addc_u32 s35, s55, 0
	s_mov_b32 m0, s65
	v_lshl_add_u64 v[228:229], s[34:35], 0, v[134:135]
	ds_read_b128 v[188:191], v159 offset:32768
	ds_read_b128 v[192:195], v159 offset:33792
	ds_read_b128 v[196:199], v159 offset:34816
	ds_read_b128 v[200:203], v159 offset:35840
	ds_read_b128 v[204:207], v159 offset:36864
	ds_read_b128 v[208:211], v159 offset:37888
	ds_read_b128 v[212:215], v159 offset:38912
	ds_read_b128 v[216:219], v159 offset:39936
	global_load_lds_dwordx4 v[228:229], off
	v_lshl_add_u64 v[228:229], s[34:35], 0, v[138:139]
	s_mov_b32 m0, s66
	s_nop 0
	global_load_lds_dwordx4 v[228:229], off
	s_waitcnt vmcnt(8)
	s_waitcnt lgkmcnt(0)
	s_barrier
	s_setprio 1
	s_waitcnt lgkmcnt(0)
	v_mfma_f32_16x16x32_bf16 v[124:127], v[152:155], v[188:191], v[124:127]
	v_mfma_f32_16x16x32_bf16 v[120:123], v[164:167], v[188:191], v[120:123]
	v_mfma_f32_16x16x32_bf16 v[108:111], v[152:155], v[196:199], v[108:111]
	v_mfma_f32_16x16x32_bf16 v[104:107], v[164:167], v[196:199], v[104:107]
	v_mfma_f32_16x16x32_bf16 v[92:95], v[152:155], v[204:207], v[92:95]
	v_mfma_f32_16x16x32_bf16 v[88:91], v[164:167], v[204:207], v[88:91]
	v_mfma_f32_16x16x32_bf16 v[76:79], v[152:155], v[212:215], v[76:79]
	v_mfma_f32_16x16x32_bf16 v[72:75], v[164:167], v[212:215], v[72:75]
	v_mfma_f32_16x16x32_bf16 v[124:127], v[160:163], v[192:195], v[124:127]
	v_mfma_f32_16x16x32_bf16 v[120:123], v[168:171], v[192:195], v[120:123]
	v_mfma_f32_16x16x32_bf16 v[108:111], v[160:163], v[200:203], v[108:111]
	v_mfma_f32_16x16x32_bf16 v[104:107], v[168:171], v[200:203], v[104:107]
	v_mfma_f32_16x16x32_bf16 v[92:95], v[160:163], v[208:211], v[92:95]
	v_mfma_f32_16x16x32_bf16 v[88:91], v[168:171], v[208:211], v[88:91]
	v_mfma_f32_16x16x32_bf16 v[76:79], v[160:163], v[216:219], v[76:79]
	v_mfma_f32_16x16x32_bf16 v[72:75], v[168:171], v[216:219], v[72:75]
	s_setprio 0
	s_setprio 1
	v_mfma_f32_16x16x32_bf16 v[116:119], v[172:175], v[188:191], v[116:119]
	v_mfma_f32_16x16x32_bf16 v[112:115], v[180:183], v[188:191], v[112:115]
	v_mfma_f32_16x16x32_bf16 v[100:103], v[172:175], v[196:199], v[100:103]
	v_mfma_f32_16x16x32_bf16 v[96:99], v[180:183], v[196:199], v[96:99]
	v_mfma_f32_16x16x32_bf16 v[84:87], v[172:175], v[204:207], v[84:87]
	v_mfma_f32_16x16x32_bf16 v[80:83], v[180:183], v[204:207], v[80:83]
	v_mfma_f32_16x16x32_bf16 v[68:71], v[172:175], v[212:215], v[68:71]
	v_mfma_f32_16x16x32_bf16 v[64:67], v[180:183], v[212:215], v[64:67]
	v_mfma_f32_16x16x32_bf16 v[116:119], v[176:179], v[192:195], v[116:119]
	v_mfma_f32_16x16x32_bf16 v[112:115], v[184:187], v[192:195], v[112:115]
	v_mfma_f32_16x16x32_bf16 v[100:103], v[176:179], v[200:203], v[100:103]
	v_mfma_f32_16x16x32_bf16 v[96:99], v[184:187], v[200:203], v[96:99]
	v_mfma_f32_16x16x32_bf16 v[84:87], v[176:179], v[208:211], v[84:87]
	v_mfma_f32_16x16x32_bf16 v[80:83], v[184:187], v[208:211], v[80:83]
	v_mfma_f32_16x16x32_bf16 v[68:71], v[176:179], v[216:219], v[68:71]
	v_mfma_f32_16x16x32_bf16 v[64:67], v[184:187], v[216:219], v[64:67]
	s_setprio 0
	s_barrier
	s_add_i32 s34, s87, s58
	v_lshl_add_u64 v[220:221], v[220:221], 0, s[22:23]
	s_mov_b32 m0, s34
	ds_read_b128 v[188:191], v159 offset:49152
	ds_read_b128 v[192:195], v159 offset:50176
	ds_read_b128 v[196:199], v159 offset:51200
	ds_read_b128 v[200:203], v159 offset:52224
	ds_read_b128 v[204:207], v159 offset:53248
	ds_read_b128 v[208:211], v159 offset:54272
	ds_read_b128 v[212:215], v159 offset:55296
	ds_read_b128 v[216:219], v159 offset:56320
	global_load_lds_dwordx4 v[220:221], off
	s_add_i32 m0, s34, 0x2000
	s_add_u32 s34, s52, 0x40080
	v_lshl_add_u64 v[220:221], v[222:223], 0, s[22:23]
	s_addc_u32 s35, s53, 0
	s_add_i32 s52, s88, s58
	global_load_lds_dwordx4 v[220:221], off
	v_lshl_add_u64 v[220:221], s[34:35], 0, v[136:137]
	s_mov_b32 m0, s52
	s_nop 0
	global_load_lds_dwordx4 v[220:221], off
	v_lshl_add_u64 v[220:221], s[34:35], 0, v[140:141]
	s_add_i32 m0, s52, 0x2000
	s_nop 0
	global_load_lds_dwordx4 v[220:221], off
	v_lshl_add_u64 v[220:221], v[224:225], 0, s[22:23]
	s_mov_b32 m0, s79
	s_nop 0
	global_load_lds_dwordx4 v[220:221], off
	v_lshl_add_u64 v[220:221], v[226:227], 0, s[22:23]
	s_mov_b32 m0, s81
	s_nop 0
	global_load_lds_dwordx4 v[220:221], off
	s_waitcnt vmcnt(8)
	s_waitcnt lgkmcnt(0)
	s_barrier
	s_setprio 1
	s_waitcnt lgkmcnt(0)
	v_mfma_f32_16x16x32_bf16 v[60:63], v[152:155], v[188:191], v[60:63]
	v_mfma_f32_16x16x32_bf16 v[56:59], v[164:167], v[188:191], v[56:59]
	v_mfma_f32_16x16x32_bf16 v[44:47], v[152:155], v[196:199], v[44:47]
	v_mfma_f32_16x16x32_bf16 v[40:43], v[164:167], v[196:199], v[40:43]
	v_mfma_f32_16x16x32_bf16 v[28:31], v[152:155], v[204:207], v[28:31]
	v_mfma_f32_16x16x32_bf16 v[24:27], v[164:167], v[204:207], v[24:27]
	v_mfma_f32_16x16x32_bf16 v[12:15], v[152:155], v[212:215], v[12:15]
	v_mfma_f32_16x16x32_bf16 v[8:11], v[164:167], v[212:215], v[8:11]
	v_mfma_f32_16x16x32_bf16 v[60:63], v[160:163], v[192:195], v[60:63]
	v_mfma_f32_16x16x32_bf16 v[56:59], v[168:171], v[192:195], v[56:59]
	v_mfma_f32_16x16x32_bf16 v[44:47], v[160:163], v[200:203], v[44:47]
	v_mfma_f32_16x16x32_bf16 v[40:43], v[168:171], v[200:203], v[40:43]
	v_mfma_f32_16x16x32_bf16 v[28:31], v[160:163], v[208:211], v[28:31]
	v_mfma_f32_16x16x32_bf16 v[24:27], v[168:171], v[208:211], v[24:27]
	v_mfma_f32_16x16x32_bf16 v[12:15], v[160:163], v[216:219], v[12:15]
	v_mfma_f32_16x16x32_bf16 v[8:11], v[168:171], v[216:219], v[8:11]
	s_setprio 0
	s_setprio 1
	v_mfma_f32_16x16x32_bf16 v[52:55], v[172:175], v[188:191], v[52:55]
	v_mfma_f32_16x16x32_bf16 v[48:51], v[180:183], v[188:191], v[48:51]
	v_mfma_f32_16x16x32_bf16 v[36:39], v[172:175], v[196:199], v[36:39]
	v_mfma_f32_16x16x32_bf16 v[32:35], v[180:183], v[196:199], v[32:35]
	v_mfma_f32_16x16x32_bf16 v[20:23], v[172:175], v[204:207], v[20:23]
	v_mfma_f32_16x16x32_bf16 v[16:19], v[180:183], v[204:207], v[16:19]
	v_mfma_f32_16x16x32_bf16 v[4:7], v[172:175], v[212:215], v[4:7]
	v_mfma_f32_16x16x32_bf16 v[0:3], v[180:183], v[212:215], v[0:3]
	v_mfma_f32_16x16x32_bf16 v[52:55], v[176:179], v[192:195], v[52:55]
	v_mfma_f32_16x16x32_bf16 v[48:51], v[184:187], v[192:195], v[48:51]
	v_mfma_f32_16x16x32_bf16 v[36:39], v[176:179], v[200:203], v[36:39]
	v_mfma_f32_16x16x32_bf16 v[32:35], v[184:187], v[200:203], v[32:35]
	v_mfma_f32_16x16x32_bf16 v[20:23], v[176:179], v[208:211], v[20:23]
	v_mfma_f32_16x16x32_bf16 v[16:19], v[184:187], v[208:211], v[16:19]
	v_mfma_f32_16x16x32_bf16 v[4:7], v[176:179], v[216:219], v[4:7]
	v_mfma_f32_16x16x32_bf16 v[0:3], v[184:187], v[216:219], v[0:3]
	s_setprio 0
	s_barrier
	s_add_i32 s86, s86, 2
	s_add_u32 s50, s50, 0x100
	s_addc_u32 s51, s51, 0
	s_add_u32 s29, s29, 0x100
	s_addc_u32 s41, s41, 0

.LBB0_385:
	s_ashr_i32 s29, s28, 31
	s_lshl_b64 s[12:13], s[28:29], 19
	s_add_u32 s40, s20, s12
	s_addc_u32 s41, s21, s13
	s_and_b64 s[12:13], s[6:7], exec
	s_cselect_b32 s12, s41, s51
	s_cselect_b32 s13, s40, s50
	s_ashr_i32 s27, s26, 31
	s_lshl_b64 s[34:35], s[26:27], 19
	s_add_u32 s42, s3, s34
	s_addc_u32 s43, s56, s35
	s_and_b64 s[34:35], s[6:7], exec
	s_cselect_b32 s27, s43, s53
	s_cselect_b32 s29, s42, s52
	s_add_u32 s50, s50, 0x40080
	s_addc_u32 s51, s51, 0
	s_add_u32 s49, s52, 0x100
	s_addc_u32 s77, s53, 0
	s_mov_b32 s85, -2
	s_waitcnt lgkmcnt(0)
	s_cmp_lg_u32 s84, 1
	s_cselect_b32 s100, s99, 0
	s_cmp_lg_u32 s100, 0
	s_cbranch_scc0 .Lmy_nobar2_4
	s_barrier
.Lmy_nobar2_4:
	ds_read_b128 v[148:151], v154
	ds_read_b128 v[160:163], v154 offset:1024
	ds_read_b128 v[164:167], v154 offset:2048
	ds_read_b128 v[168:171], v154 offset:3072
	ds_read_b128 v[172:175], v155
	ds_read_b128 v[176:179], v155 offset:1024
	ds_read_b128 v[180:183], v155 offset:2048
	ds_read_b128 v[184:187], v155 offset:3072
	s_add_u32 s34, s50, 0xfffc0080
	s_addc_u32 s35, s51, -1
	s_cmp_eq_u32 s85, 12
	s_cselect_b32 s55, s12, s35
	s_cselect_b32 s54, s13, s34
	s_cselect_b32 s53, s27, s77
	s_cselect_b32 s52, s29, s49
	v_lshl_add_u64 v[220:221], s[50:51], 0, v[140:141]
	s_add_i32 m0, s58, 0xc000
	ds_read_b128 v[188:191], v157
	ds_read_b128 v[192:195], v157 offset:1024
	ds_read_b128 v[196:199], v157 offset:2048
	ds_read_b128 v[200:203], v157 offset:3072
	ds_read_b128 v[204:207], v157 offset:4096
	ds_read_b128 v[208:211], v157 offset:5120
	ds_read_b128 v[212:215], v157 offset:6144
	ds_read_b128 v[216:219], v157 offset:7168
	global_load_lds_dwordx4 v[220:221], off
	v_lshl_add_u64 v[220:221], s[50:51], 0, v[142:143]
	s_add_i32 m0, s58, 0xe000
	s_nop 0
	global_load_lds_dwordx4 v[220:221], off
	s_waitcnt vmcnt(8)
	s_waitcnt lgkmcnt(0)
	s_barrier
	s_setprio 1
	s_waitcnt lgkmcnt(0)
	v_mfma_f32_16x16x32_bf16 v[124:127], v[148:151], v[188:191], 0
	v_mfma_f32_16x16x32_bf16 v[120:123], v[164:167], v[188:191], 0
	v_mfma_f32_16x16x32_bf16 v[108:111], v[148:151], v[196:199], 0
	v_mfma_f32_16x16x32_bf16 v[104:107], v[164:167], v[196:199], 0
	v_mfma_f32_16x16x32_bf16 v[92:95], v[148:151], v[204:207], 0
	v_mfma_f32_16x16x32_bf16 v[88:91], v[164:167], v[204:207], 0
	v_mfma_f32_16x16x32_bf16 v[76:79], v[148:151], v[212:215], 0
	v_mfma_f32_16x16x32_bf16 v[72:75], v[164:167], v[212:215], 0
	v_mfma_f32_16x16x32_bf16 v[124:127], v[160:163], v[192:195], v[124:127]
	v_mfma_f32_16x16x32_bf16 v[120:123], v[168:171], v[192:195], v[120:123]
	v_mfma_f32_16x16x32_bf16 v[108:111], v[160:163], v[200:203], v[108:111]
	v_mfma_f32_16x16x32_bf16 v[104:107], v[168:171], v[200:203], v[104:107]
	v_mfma_f32_16x16x32_bf16 v[92:95], v[160:163], v[208:211], v[92:95]
	v_mfma_f32_16x16x32_bf16 v[88:91], v[168:171], v[208:211], v[88:91]
	v_mfma_f32_16x16x32_bf16 v[76:79], v[160:163], v[216:219], v[76:79]
	v_mfma_f32_16x16x32_bf16 v[72:75], v[168:171], v[216:219], v[72:75]
	s_setprio 0
	s_setprio 1
	v_mfma_f32_16x16x32_bf16 v[116:119], v[172:175], v[188:191], 0
	v_mfma_f32_16x16x32_bf16 v[112:115], v[180:183], v[188:191], 0
	v_mfma_f32_16x16x32_bf16 v[100:103], v[172:175], v[196:199], 0
	v_mfma_f32_16x16x32_bf16 v[96:99], v[180:183], v[196:199], 0
	v_mfma_f32_16x16x32_bf16 v[84:87], v[172:175], v[204:207], 0
	v_mfma_f32_16x16x32_bf16 v[80:83], v[180:183], v[204:207], 0
	v_mfma_f32_16x16x32_bf16 v[68:71], v[172:175], v[212:215], 0
	v_mfma_f32_16x16x32_bf16 v[64:67], v[180:183], v[212:215], 0
	v_mfma_f32_16x16x32_bf16 v[116:119], v[176:179], v[192:195], v[116:119]
	v_mfma_f32_16x16x32_bf16 v[112:115], v[184:187], v[192:195], v[112:115]
	v_mfma_f32_16x16x32_bf16 v[100:103], v[176:179], v[200:203], v[100:103]
	v_mfma_f32_16x16x32_bf16 v[96:99], v[184:187], v[200:203], v[96:99]
	v_mfma_f32_16x16x32_bf16 v[84:87], v[176:179], v[208:211], v[84:87]
	v_mfma_f32_16x16x32_bf16 v[80:83], v[184:187], v[208:211], v[80:83]
	v_mfma_f32_16x16x32_bf16 v[68:71], v[176:179], v[216:219], v[68:71]
	v_mfma_f32_16x16x32_bf16 v[64:67], v[184:187], v[216:219], v[64:67]
	s_setprio 0
	s_barrier
	s_add_i32 s34, s82, s57
	v_lshl_add_u64 v[220:221], s[52:53], 0, v[134:135]
	s_mov_b32 m0, s34
	ds_read_b128 v[188:191], v157 offset:16384
	ds_read_b128 v[192:195], v157 offset:17408
	ds_read_b128 v[196:199], v157 offset:18432
	ds_read_b128 v[200:203], v157 offset:19456
	ds_read_b128 v[204:207], v157 offset:20480
	ds_read_b128 v[208:211], v157 offset:21504
	ds_read_b128 v[212:215], v157 offset:22528
	ds_read_b128 v[216:219], v157 offset:23552
	global_load_lds_dwordx4 v[220:221], off
	s_add_i32 m0, s34, 0x2000
	s_add_u32 s34, s52, 0x40000
	v_lshl_add_u64 v[222:223], s[52:53], 0, v[138:139]
	s_addc_u32 s35, s53, 0
	s_add_i32 s86, s83, s57
	global_load_lds_dwordx4 v[222:223], off
	v_lshl_add_u64 v[224:225], s[34:35], 0, v[134:135]
	s_mov_b32 m0, s86
	v_lshl_add_u64 v[226:227], s[54:55], 0, v[136:137]
	global_load_lds_dwordx4 v[224:225], off
	v_lshl_add_u64 v[224:225], s[34:35], 0, v[138:139]
	s_add_i32 m0, s86, 0x2000
	s_nop 0
	global_load_lds_dwordx4 v[224:225], off
	v_lshl_add_u64 v[224:225], s[54:55], 0, v[132:133]
	s_mov_b32 m0, s58
	s_nop 0
	global_load_lds_dwordx4 v[224:225], off
	s_mov_b32 m0, s59
	s_nop 0
	global_load_lds_dwordx4 v[226:227], off
	s_waitcnt vmcnt(8)
	s_waitcnt lgkmcnt(0)
	s_barrier
	s_setprio 1
	s_waitcnt lgkmcnt(0)
	v_mfma_f32_16x16x32_bf16 v[60:63], v[148:151], v[188:191], 0
	v_mfma_f32_16x16x32_bf16 v[56:59], v[164:167], v[188:191], 0
	v_mfma_f32_16x16x32_bf16 v[44:47], v[148:151], v[196:199], 0
	v_mfma_f32_16x16x32_bf16 v[40:43], v[164:167], v[196:199], 0
	v_mfma_f32_16x16x32_bf16 v[28:31], v[148:151], v[204:207], 0
	v_mfma_f32_16x16x32_bf16 v[24:27], v[164:167], v[204:207], 0
	v_mfma_f32_16x16x32_bf16 v[12:15], v[148:151], v[212:215], 0
	v_mfma_f32_16x16x32_bf16 v[8:11], v[164:167], v[212:215], 0
	v_mfma_f32_16x16x32_bf16 v[60:63], v[160:163], v[192:195], v[60:63]
	v_mfma_f32_16x16x32_bf16 v[56:59], v[168:171], v[192:195], v[56:59]
	v_mfma_f32_16x16x32_bf16 v[44:47], v[160:163], v[200:203], v[44:47]
	v_mfma_f32_16x16x32_bf16 v[40:43], v[168:171], v[200:203], v[40:43]
	v_mfma_f32_16x16x32_bf16 v[28:31], v[160:163], v[208:211], v[28:31]
	v_mfma_f32_16x16x32_bf16 v[24:27], v[168:171], v[208:211], v[24:27]
	v_mfma_f32_16x16x32_bf16 v[12:15], v[160:163], v[216:219], v[12:15]
	v_mfma_f32_16x16x32_bf16 v[8:11], v[168:171], v[216:219], v[8:11]
	s_setprio 0
	s_setprio 1
	v_mfma_f32_16x16x32_bf16 v[52:55], v[172:175], v[188:191], 0
	v_mfma_f32_16x16x32_bf16 v[48:51], v[180:183], v[188:191], 0
	v_mfma_f32_16x16x32_bf16 v[36:39], v[172:175], v[196:199], 0
	v_mfma_f32_16x16x32_bf16 v[32:35], v[180:183], v[196:199], 0
	v_mfma_f32_16x16x32_bf16 v[20:23], v[172:175], v[204:207], 0
	v_mfma_f32_16x16x32_bf16 v[16:19], v[180:183], v[204:207], 0
	v_mfma_f32_16x16x32_bf16 v[4:7], v[172:175], v[212:215], 0
	v_mfma_f32_16x16x32_bf16 v[0:3], v[180:183], v[212:215], 0
	v_mfma_f32_16x16x32_bf16 v[52:55], v[176:179], v[192:195], v[52:55]
	v_mfma_f32_16x16x32_bf16 v[48:51], v[184:187], v[192:195], v[48:51]
	v_mfma_f32_16x16x32_bf16 v[36:39], v[176:179], v[200:203], v[36:39]
	v_mfma_f32_16x16x32_bf16 v[32:35], v[184:187], v[200:203], v[32:35]
	v_mfma_f32_16x16x32_bf16 v[20:23], v[176:179], v[208:211], v[20:23]
	v_mfma_f32_16x16x32_bf16 v[16:19], v[184:187], v[208:211], v[16:19]
	v_mfma_f32_16x16x32_bf16 v[4:7], v[176:179], v[216:219], v[4:7]
	v_mfma_f32_16x16x32_bf16 v[0:3], v[184:187], v[216:219], v[0:3]
	s_setprio 0
	s_barrier
	s_add_i32 s86, 0, 0x18000
	v_add_u32_e32 v159, s86, v152
	s_add_i32 s87, 0, 0x1c000
	ds_read_b128 v[148:151], v159
	ds_read_b128 v[160:163], v159 offset:1024
	ds_read_b128 v[164:167], v159 offset:2048
	ds_read_b128 v[168:171], v159 offset:3072
	v_add_u32_e32 v159, s87, v152
	ds_read_b128 v[172:175], v159
	ds_read_b128 v[176:179], v159 offset:1024
	ds_read_b128 v[180:183], v159 offset:2048
	ds_read_b128 v[184:187], v159 offset:3072
	s_add_u32 s34, s54, 0x40000
	s_addc_u32 s35, s55, 0
	s_mov_b32 m0, s62
	v_lshl_add_u64 v[228:229], s[34:35], 0, v[132:133]
	ds_read_b128 v[188:191], v157 offset:32768
	ds_read_b128 v[192:195], v157 offset:33792
	ds_read_b128 v[196:199], v157 offset:34816
	ds_read_b128 v[200:203], v157 offset:35840
	ds_read_b128 v[204:207], v157 offset:36864
	ds_read_b128 v[208:211], v157 offset:37888
	ds_read_b128 v[212:215], v157 offset:38912
	ds_read_b128 v[216:219], v157 offset:39936
	global_load_lds_dwordx4 v[228:229], off
	v_lshl_add_u64 v[228:229], s[34:35], 0, v[136:137]
	s_mov_b32 m0, s63
	s_nop 0
	global_load_lds_dwordx4 v[228:229], off
	s_waitcnt vmcnt(8)
	s_waitcnt lgkmcnt(0)
	s_barrier
	s_setprio 1
	s_waitcnt lgkmcnt(0)
	v_mfma_f32_16x16x32_bf16 v[124:127], v[148:151], v[188:191], v[124:127]
	v_mfma_f32_16x16x32_bf16 v[120:123], v[164:167], v[188:191], v[120:123]
	v_mfma_f32_16x16x32_bf16 v[108:111], v[148:151], v[196:199], v[108:111]
	v_mfma_f32_16x16x32_bf16 v[104:107], v[164:167], v[196:199], v[104:107]
	v_mfma_f32_16x16x32_bf16 v[92:95], v[148:151], v[204:207], v[92:95]
	v_mfma_f32_16x16x32_bf16 v[88:91], v[164:167], v[204:207], v[88:91]
	v_mfma_f32_16x16x32_bf16 v[76:79], v[148:151], v[212:215], v[76:79]
	v_mfma_f32_16x16x32_bf16 v[72:75], v[164:167], v[212:215], v[72:75]
	v_mfma_f32_16x16x32_bf16 v[124:127], v[160:163], v[192:195], v[124:127]
	v_mfma_f32_16x16x32_bf16 v[120:123], v[168:171], v[192:195], v[120:123]
	v_mfma_f32_16x16x32_bf16 v[108:111], v[160:163], v[200:203], v[108:111]
	v_mfma_f32_16x16x32_bf16 v[104:107], v[168:171], v[200:203], v[104:107]
	v_mfma_f32_16x16x32_bf16 v[92:95], v[160:163], v[208:211], v[92:95]
	v_mfma_f32_16x16x32_bf16 v[88:91], v[168:171], v[208:211], v[88:91]
	v_mfma_f32_16x16x32_bf16 v[76:79], v[160:163], v[216:219], v[76:79]
	v_mfma_f32_16x16x32_bf16 v[72:75], v[168:171], v[216:219], v[72:75]
	s_setprio 0
	s_setprio 1
	v_mfma_f32_16x16x32_bf16 v[116:119], v[172:175], v[188:191], v[116:119]
	v_mfma_f32_16x16x32_bf16 v[112:115], v[180:183], v[188:191], v[112:115]
	v_mfma_f32_16x16x32_bf16 v[100:103], v[172:175], v[196:199], v[100:103]
	v_mfma_f32_16x16x32_bf16 v[96:99], v[180:183], v[196:199], v[96:99]
	v_mfma_f32_16x16x32_bf16 v[84:87], v[172:175], v[204:207], v[84:87]
	v_mfma_f32_16x16x32_bf16 v[80:83], v[180:183], v[204:207], v[80:83]
	v_mfma_f32_16x16x32_bf16 v[68:71], v[172:175], v[212:215], v[68:71]
	v_mfma_f32_16x16x32_bf16 v[64:67], v[180:183], v[212:215], v[64:67]
	v_mfma_f32_16x16x32_bf16 v[116:119], v[176:179], v[192:195], v[116:119]
	v_mfma_f32_16x16x32_bf16 v[112:115], v[184:187], v[192:195], v[112:115]
	v_mfma_f32_16x16x32_bf16 v[100:103], v[176:179], v[200:203], v[100:103]
	v_mfma_f32_16x16x32_bf16 v[96:99], v[184:187], v[200:203], v[96:99]
	v_mfma_f32_16x16x32_bf16 v[84:87], v[176:179], v[208:211], v[84:87]
	v_mfma_f32_16x16x32_bf16 v[80:83], v[184:187], v[208:211], v[80:83]
	v_mfma_f32_16x16x32_bf16 v[68:71], v[176:179], v[216:219], v[68:71]
	v_mfma_f32_16x16x32_bf16 v[64:67], v[184:187], v[216:219], v[64:67]
	s_setprio 0
	s_barrier
	s_add_i32 s34, s86, s57
	v_lshl_add_u64 v[220:221], v[220:221], 0, s[10:11]
	s_mov_b32 m0, s34
	ds_read_b128 v[188:191], v157 offset:49152
	ds_read_b128 v[192:195], v157 offset:50176
	ds_read_b128 v[196:199], v157 offset:51200
	ds_read_b128 v[200:203], v157 offset:52224
	ds_read_b128 v[204:207], v157 offset:53248
	ds_read_b128 v[208:211], v157 offset:54272
	ds_read_b128 v[212:215], v157 offset:55296
	ds_read_b128 v[216:219], v157 offset:56320
	global_load_lds_dwordx4 v[220:221], off
	s_add_i32 m0, s34, 0x2000
	s_add_u32 s34, s52, 0x40080
	v_lshl_add_u64 v[220:221], v[222:223], 0, s[10:11]
	s_addc_u32 s35, s53, 0
	s_add_i32 s52, s87, s57
	global_load_lds_dwordx4 v[220:221], off
	v_lshl_add_u64 v[220:221], s[34:35], 0, v[134:135]
	s_mov_b32 m0, s52
	s_nop 0
	global_load_lds_dwordx4 v[220:221], off
	v_lshl_add_u64 v[220:221], s[34:35], 0, v[138:139]
	s_add_i32 m0, s52, 0x2000
	s_nop 0
	global_load_lds_dwordx4 v[220:221], off
	v_lshl_add_u64 v[220:221], v[224:225], 0, s[10:11]
	s_mov_b32 m0, s65
	s_nop 0
	global_load_lds_dwordx4 v[220:221], off
	v_lshl_add_u64 v[220:221], v[226:227], 0, s[10:11]
	s_mov_b32 m0, s66
	s_nop 0
	global_load_lds_dwordx4 v[220:221], off
	s_waitcnt vmcnt(8)
	s_waitcnt lgkmcnt(0)
	s_barrier
	s_setprio 1
	s_waitcnt lgkmcnt(0)
	v_mfma_f32_16x16x32_bf16 v[60:63], v[148:151], v[188:191], v[60:63]
	v_mfma_f32_16x16x32_bf16 v[56:59], v[164:167], v[188:191], v[56:59]
	v_mfma_f32_16x16x32_bf16 v[44:47], v[148:151], v[196:199], v[44:47]
	v_mfma_f32_16x16x32_bf16 v[40:43], v[164:167], v[196:199], v[40:43]
	v_mfma_f32_16x16x32_bf16 v[28:31], v[148:151], v[204:207], v[28:31]
	v_mfma_f32_16x16x32_bf16 v[24:27], v[164:167], v[204:207], v[24:27]
	v_mfma_f32_16x16x32_bf16 v[12:15], v[148:151], v[212:215], v[12:15]
	v_mfma_f32_16x16x32_bf16 v[8:11], v[164:167], v[212:215], v[8:11]
	v_mfma_f32_16x16x32_bf16 v[60:63], v[160:163], v[192:195], v[60:63]
	v_mfma_f32_16x16x32_bf16 v[56:59], v[168:171], v[192:195], v[56:59]
	v_mfma_f32_16x16x32_bf16 v[44:47], v[160:163], v[200:203], v[44:47]
	v_mfma_f32_16x16x32_bf16 v[40:43], v[168:171], v[200:203], v[40:43]
	v_mfma_f32_16x16x32_bf16 v[28:31], v[160:163], v[208:211], v[28:31]
	v_mfma_f32_16x16x32_bf16 v[24:27], v[168:171], v[208:211], v[24:27]
	v_mfma_f32_16x16x32_bf16 v[12:15], v[160:163], v[216:219], v[12:15]
	v_mfma_f32_16x16x32_bf16 v[8:11], v[168:171], v[216:219], v[8:11]
	s_setprio 0
	s_setprio 1
	v_mfma_f32_16x16x32_bf16 v[52:55], v[172:175], v[188:191], v[52:55]
	v_mfma_f32_16x16x32_bf16 v[48:51], v[180:183], v[188:191], v[48:51]
	v_mfma_f32_16x16x32_bf16 v[36:39], v[172:175], v[196:199], v[36:39]
	v_mfma_f32_16x16x32_bf16 v[32:35], v[180:183], v[196:199], v[32:35]
	v_mfma_f32_16x16x32_bf16 v[20:23], v[172:175], v[204:207], v[20:23]
	v_mfma_f32_16x16x32_bf16 v[16:19], v[180:183], v[204:207], v[16:19]
	v_mfma_f32_16x16x32_bf16 v[4:7], v[172:175], v[212:215], v[4:7]
	v_mfma_f32_16x16x32_bf16 v[0:3], v[180:183], v[212:215], v[0:3]
	v_mfma_f32_16x16x32_bf16 v[52:55], v[176:179], v[192:195], v[52:55]
	v_mfma_f32_16x16x32_bf16 v[48:51], v[184:187], v[192:195], v[48:51]
	v_mfma_f32_16x16x32_bf16 v[36:39], v[176:179], v[200:203], v[36:39]
	v_mfma_f32_16x16x32_bf16 v[32:35], v[184:187], v[200:203], v[32:35]
	v_mfma_f32_16x16x32_bf16 v[20:23], v[176:179], v[208:211], v[20:23]
	v_mfma_f32_16x16x32_bf16 v[16:19], v[184:187], v[208:211], v[16:19]
	v_mfma_f32_16x16x32_bf16 v[4:7], v[176:179], v[216:219], v[4:7]
	v_mfma_f32_16x16x32_bf16 v[0:3], v[184:187], v[216:219], v[0:3]
	s_setprio 0
	s_barrier
	s_add_i32 s85, s85, 2
	s_add_u32 s50, s50, 0x100
	s_addc_u32 s51, s51, 0
	s_add_u32 s49, s49, 0x100
	s_addc_u32 s77, s77, 0

.LBB0_475:
	s_ashr_i32 s23, s22, 31
	s_lshl_b64 s[26:27], s[22:23], 19
	s_add_u32 s26, s14, s26
	s_addc_u32 s27, s15, s27
	s_and_b64 s[28:29], s[4:5], exec
	s_cselect_b32 s23, s27, s43
	s_cselect_b32 s81, s26, s42
	s_ashr_i32 s11, s10, 31
	s_lshl_b64 s[28:29], s[10:11], 19
	s_add_u32 s28, s55, s28
	s_addc_u32 s29, s56, s29
	s_and_b64 s[34:35], s[4:5], exec
	s_cselect_b32 s11, s29, s49
	s_cselect_b32 s82, s28, s48
	s_add_u32 s42, s42, 0x40080
	s_addc_u32 s43, s43, 0
	s_add_u32 s83, s48, 0x100
	s_addc_u32 s84, s49, 0
	s_mov_b32 s85, -2
	s_cmp_lg_u32 s77, 1
	s_cselect_b32 s100, s99, 0
	s_cmp_lg_u32 s100, 0
	s_cbranch_scc0 .Lmy_nobar2_5
	s_barrier
.Lmy_nobar2_5:
	ds_read_b128 v[148:151], v155
	ds_read_b128 v[160:163], v155 offset:1024
	ds_read_b128 v[164:167], v155 offset:2048
	ds_read_b128 v[168:171], v155 offset:3072
	ds_read_b128 v[172:175], v157
	ds_read_b128 v[176:179], v157 offset:1024
	ds_read_b128 v[180:183], v157 offset:2048
	ds_read_b128 v[184:187], v157 offset:3072
	s_add_u32 s34, s42, 0xfffc0080
	s_addc_u32 s35, s43, -1
	s_cmp_eq_u32 s85, 12
	s_cselect_b32 s51, s23, s35
	s_cselect_b32 s50, s81, s34
	s_cselect_b32 s49, s11, s84
	s_cselect_b32 s48, s82, s83
	v_lshl_add_u64 v[220:221], s[42:43], 0, v[140:141]
	s_add_i32 m0, s41, 0xc000
	ds_read_b128 v[188:191], v158
	ds_read_b128 v[192:195], v158 offset:1024
	ds_read_b128 v[196:199], v158 offset:2048
	ds_read_b128 v[200:203], v158 offset:3072
	ds_read_b128 v[204:207], v158 offset:4096
	ds_read_b128 v[208:211], v158 offset:5120
	ds_read_b128 v[212:215], v158 offset:6144
	ds_read_b128 v[216:219], v158 offset:7168
	global_load_lds_dwordx4 v[220:221], off
	v_lshl_add_u64 v[220:221], s[42:43], 0, v[142:143]
	s_add_i32 m0, s41, 0xe000
	s_nop 0
	global_load_lds_dwordx4 v[220:221], off
	s_waitcnt vmcnt(8)
	s_waitcnt lgkmcnt(0)
	s_barrier
	s_setprio 1
	s_waitcnt lgkmcnt(0)
	v_mfma_f32_16x16x32_bf16 v[124:127], v[148:151], v[188:191], 0
	v_mfma_f32_16x16x32_bf16 v[120:123], v[164:167], v[188:191], 0
	v_mfma_f32_16x16x32_bf16 v[108:111], v[148:151], v[196:199], 0
	v_mfma_f32_16x16x32_bf16 v[104:107], v[164:167], v[196:199], 0
	v_mfma_f32_16x16x32_bf16 v[92:95], v[148:151], v[204:207], 0
	v_mfma_f32_16x16x32_bf16 v[88:91], v[164:167], v[204:207], 0
	v_mfma_f32_16x16x32_bf16 v[76:79], v[148:151], v[212:215], 0
	v_mfma_f32_16x16x32_bf16 v[72:75], v[164:167], v[212:215], 0
	v_mfma_f32_16x16x32_bf16 v[124:127], v[160:163], v[192:195], v[124:127]
	v_mfma_f32_16x16x32_bf16 v[120:123], v[168:171], v[192:195], v[120:123]
	v_mfma_f32_16x16x32_bf16 v[108:111], v[160:163], v[200:203], v[108:111]
	v_mfma_f32_16x16x32_bf16 v[104:107], v[168:171], v[200:203], v[104:107]
	v_mfma_f32_16x16x32_bf16 v[92:95], v[160:163], v[208:211], v[92:95]
	v_mfma_f32_16x16x32_bf16 v[88:91], v[168:171], v[208:211], v[88:91]
	v_mfma_f32_16x16x32_bf16 v[76:79], v[160:163], v[216:219], v[76:79]
	v_mfma_f32_16x16x32_bf16 v[72:75], v[168:171], v[216:219], v[72:75]
	s_setprio 0
	s_setprio 1
	v_mfma_f32_16x16x32_bf16 v[116:119], v[172:175], v[188:191], 0
	v_mfma_f32_16x16x32_bf16 v[112:115], v[180:183], v[188:191], 0
	v_mfma_f32_16x16x32_bf16 v[100:103], v[172:175], v[196:199], 0
	v_mfma_f32_16x16x32_bf16 v[96:99], v[180:183], v[196:199], 0
	v_mfma_f32_16x16x32_bf16 v[84:87], v[172:175], v[204:207], 0
	v_mfma_f32_16x16x32_bf16 v[80:83], v[180:183], v[204:207], 0
	v_mfma_f32_16x16x32_bf16 v[68:71], v[172:175], v[212:215], 0
	v_mfma_f32_16x16x32_bf16 v[64:67], v[180:183], v[212:215], 0
	v_mfma_f32_16x16x32_bf16 v[116:119], v[176:179], v[192:195], v[116:119]
	v_mfma_f32_16x16x32_bf16 v[112:115], v[184:187], v[192:195], v[112:115]
	v_mfma_f32_16x16x32_bf16 v[100:103], v[176:179], v[200:203], v[100:103]
	v_mfma_f32_16x16x32_bf16 v[96:99], v[184:187], v[200:203], v[96:99]
	v_mfma_f32_16x16x32_bf16 v[84:87], v[176:179], v[208:211], v[84:87]
	v_mfma_f32_16x16x32_bf16 v[80:83], v[184:187], v[208:211], v[80:83]
	v_mfma_f32_16x16x32_bf16 v[68:71], v[176:179], v[216:219], v[68:71]
	v_mfma_f32_16x16x32_bf16 v[64:67], v[184:187], v[216:219], v[64:67]
	s_setprio 0
	s_barrier
	s_add_i32 s34, s65, s54
	v_lshl_add_u64 v[220:221], s[48:49], 0, v[136:137]
	s_mov_b32 m0, s34
	ds_read_b128 v[188:191], v158 offset:16384
	ds_read_b128 v[192:195], v158 offset:17408
	ds_read_b128 v[196:199], v158 offset:18432
	ds_read_b128 v[200:203], v158 offset:19456
	ds_read_b128 v[204:207], v158 offset:20480
	ds_read_b128 v[208:211], v158 offset:21504
	ds_read_b128 v[212:215], v158 offset:22528
	ds_read_b128 v[216:219], v158 offset:23552
	global_load_lds_dwordx4 v[220:221], off
	s_add_i32 m0, s34, 0x2000
	s_add_u32 s34, s48, 0x40000
	v_lshl_add_u64 v[222:223], s[48:49], 0, v[132:133]
	s_addc_u32 s35, s49, 0
	s_add_i32 s86, s66, s54
	global_load_lds_dwordx4 v[222:223], off
	v_lshl_add_u64 v[224:225], s[34:35], 0, v[136:137]
	s_mov_b32 m0, s86
	v_lshl_add_u64 v[226:227], s[50:51], 0, v[134:135]
	global_load_lds_dwordx4 v[224:225], off
	v_lshl_add_u64 v[224:225], s[34:35], 0, v[132:133]
	s_add_i32 m0, s86, 0x2000
	s_nop 0
	global_load_lds_dwordx4 v[224:225], off
	v_lshl_add_u64 v[224:225], s[50:51], 0, v[138:139]
	s_mov_b32 m0, s41
	s_nop 0
	global_load_lds_dwordx4 v[224:225], off
	s_mov_b32 m0, s58
	s_nop 0
	global_load_lds_dwordx4 v[226:227], off
	s_waitcnt vmcnt(8)
	s_waitcnt lgkmcnt(0)
	s_barrier
	s_setprio 1
	s_waitcnt lgkmcnt(0)
	v_mfma_f32_16x16x32_bf16 v[60:63], v[148:151], v[188:191], 0
	v_mfma_f32_16x16x32_bf16 v[56:59], v[164:167], v[188:191], 0
	v_mfma_f32_16x16x32_bf16 v[44:47], v[148:151], v[196:199], 0
	v_mfma_f32_16x16x32_bf16 v[40:43], v[164:167], v[196:199], 0
	v_mfma_f32_16x16x32_bf16 v[28:31], v[148:151], v[204:207], 0
	v_mfma_f32_16x16x32_bf16 v[24:27], v[164:167], v[204:207], 0
	v_mfma_f32_16x16x32_bf16 v[12:15], v[148:151], v[212:215], 0
	v_mfma_f32_16x16x32_bf16 v[8:11], v[164:167], v[212:215], 0
	v_mfma_f32_16x16x32_bf16 v[60:63], v[160:163], v[192:195], v[60:63]
	v_mfma_f32_16x16x32_bf16 v[56:59], v[168:171], v[192:195], v[56:59]
	v_mfma_f32_16x16x32_bf16 v[44:47], v[160:163], v[200:203], v[44:47]
	v_mfma_f32_16x16x32_bf16 v[40:43], v[168:171], v[200:203], v[40:43]
	v_mfma_f32_16x16x32_bf16 v[28:31], v[160:163], v[208:211], v[28:31]
	v_mfma_f32_16x16x32_bf16 v[24:27], v[168:171], v[208:211], v[24:27]
	v_mfma_f32_16x16x32_bf16 v[12:15], v[160:163], v[216:219], v[12:15]
	v_mfma_f32_16x16x32_bf16 v[8:11], v[168:171], v[216:219], v[8:11]
	s_setprio 0
	s_setprio 1
	v_mfma_f32_16x16x32_bf16 v[52:55], v[172:175], v[188:191], 0
	v_mfma_f32_16x16x32_bf16 v[48:51], v[180:183], v[188:191], 0
	v_mfma_f32_16x16x32_bf16 v[36:39], v[172:175], v[196:199], 0
	v_mfma_f32_16x16x32_bf16 v[32:35], v[180:183], v[196:199], 0
	v_mfma_f32_16x16x32_bf16 v[20:23], v[172:175], v[204:207], 0
	v_mfma_f32_16x16x32_bf16 v[16:19], v[180:183], v[204:207], 0
	v_mfma_f32_16x16x32_bf16 v[4:7], v[172:175], v[212:215], 0
	v_mfma_f32_16x16x32_bf16 v[0:3], v[180:183], v[212:215], 0
	v_mfma_f32_16x16x32_bf16 v[52:55], v[176:179], v[192:195], v[52:55]
	v_mfma_f32_16x16x32_bf16 v[48:51], v[184:187], v[192:195], v[48:51]
	v_mfma_f32_16x16x32_bf16 v[36:39], v[176:179], v[200:203], v[36:39]
	v_mfma_f32_16x16x32_bf16 v[32:35], v[184:187], v[200:203], v[32:35]
	v_mfma_f32_16x16x32_bf16 v[20:23], v[176:179], v[208:211], v[20:23]
	v_mfma_f32_16x16x32_bf16 v[16:19], v[184:187], v[208:211], v[16:19]
	v_mfma_f32_16x16x32_bf16 v[4:7], v[176:179], v[216:219], v[4:7]
	v_mfma_f32_16x16x32_bf16 v[0:3], v[184:187], v[216:219], v[0:3]
	s_setprio 0
	s_barrier
	s_add_i32 s86, 0, 0x18000
	v_add_u32_e32 v159, s86, v152
	s_add_i32 s87, 0, 0x1c000
	ds_read_b128 v[148:151], v159
	ds_read_b128 v[160:163], v159 offset:1024
	ds_read_b128 v[164:167], v159 offset:2048
	ds_read_b128 v[168:171], v159 offset:3072
	v_add_u32_e32 v159, s87, v152
	ds_read_b128 v[172:175], v159
	ds_read_b128 v[176:179], v159 offset:1024
	ds_read_b128 v[180:183], v159 offset:2048
	ds_read_b128 v[184:187], v159 offset:3072
	s_add_u32 s34, s50, 0x40000
	s_addc_u32 s35, s51, 0
	s_mov_b32 m0, s59
	v_lshl_add_u64 v[228:229], s[34:35], 0, v[138:139]
	ds_read_b128 v[188:191], v158 offset:32768
	ds_read_b128 v[192:195], v158 offset:33792
	ds_read_b128 v[196:199], v158 offset:34816
	ds_read_b128 v[200:203], v158 offset:35840
	ds_read_b128 v[204:207], v158 offset:36864
	ds_read_b128 v[208:211], v158 offset:37888
	ds_read_b128 v[212:215], v158 offset:38912
	ds_read_b128 v[216:219], v158 offset:39936
	global_load_lds_dwordx4 v[228:229], off
	v_lshl_add_u64 v[228:229], s[34:35], 0, v[134:135]
	s_mov_b32 m0, s62
	s_nop 0
	global_load_lds_dwordx4 v[228:229], off
	s_waitcnt vmcnt(8)
	s_waitcnt lgkmcnt(0)
	s_barrier
	s_setprio 1
	s_waitcnt lgkmcnt(0)
	v_mfma_f32_16x16x32_bf16 v[124:127], v[148:151], v[188:191], v[124:127]
	v_mfma_f32_16x16x32_bf16 v[120:123], v[164:167], v[188:191], v[120:123]
	v_mfma_f32_16x16x32_bf16 v[108:111], v[148:151], v[196:199], v[108:111]
	v_mfma_f32_16x16x32_bf16 v[104:107], v[164:167], v[196:199], v[104:107]
	v_mfma_f32_16x16x32_bf16 v[92:95], v[148:151], v[204:207], v[92:95]
	v_mfma_f32_16x16x32_bf16 v[88:91], v[164:167], v[204:207], v[88:91]
	v_mfma_f32_16x16x32_bf16 v[76:79], v[148:151], v[212:215], v[76:79]
	v_mfma_f32_16x16x32_bf16 v[72:75], v[164:167], v[212:215], v[72:75]
	v_mfma_f32_16x16x32_bf16 v[124:127], v[160:163], v[192:195], v[124:127]
	v_mfma_f32_16x16x32_bf16 v[120:123], v[168:171], v[192:195], v[120:123]
	v_mfma_f32_16x16x32_bf16 v[108:111], v[160:163], v[200:203], v[108:111]
	v_mfma_f32_16x16x32_bf16 v[104:107], v[168:171], v[200:203], v[104:107]
	v_mfma_f32_16x16x32_bf16 v[92:95], v[160:163], v[208:211], v[92:95]
	v_mfma_f32_16x16x32_bf16 v[88:91], v[168:171], v[208:211], v[88:91]
	v_mfma_f32_16x16x32_bf16 v[76:79], v[160:163], v[216:219], v[76:79]
	v_mfma_f32_16x16x32_bf16 v[72:75], v[168:171], v[216:219], v[72:75]
	s_setprio 0
	s_setprio 1
	v_mfma_f32_16x16x32_bf16 v[116:119], v[172:175], v[188:191], v[116:119]
	v_mfma_f32_16x16x32_bf16 v[112:115], v[180:183], v[188:191], v[112:115]
	v_mfma_f32_16x16x32_bf16 v[100:103], v[172:175], v[196:199], v[100:103]
	v_mfma_f32_16x16x32_bf16 v[96:99], v[180:183], v[196:199], v[96:99]
	v_mfma_f32_16x16x32_bf16 v[84:87], v[172:175], v[204:207], v[84:87]
	v_mfma_f32_16x16x32_bf16 v[80:83], v[180:183], v[204:207], v[80:83]
	v_mfma_f32_16x16x32_bf16 v[68:71], v[172:175], v[212:215], v[68:71]
	v_mfma_f32_16x16x32_bf16 v[64:67], v[180:183], v[212:215], v[64:67]
	v_mfma_f32_16x16x32_bf16 v[116:119], v[176:179], v[192:195], v[116:119]
	v_mfma_f32_16x16x32_bf16 v[112:115], v[184:187], v[192:195], v[112:115]
	v_mfma_f32_16x16x32_bf16 v[100:103], v[176:179], v[200:203], v[100:103]
	v_mfma_f32_16x16x32_bf16 v[96:99], v[184:187], v[200:203], v[96:99]
	v_mfma_f32_16x16x32_bf16 v[84:87], v[176:179], v[208:211], v[84:87]
	v_mfma_f32_16x16x32_bf16 v[80:83], v[184:187], v[208:211], v[80:83]
	v_mfma_f32_16x16x32_bf16 v[68:71], v[176:179], v[216:219], v[68:71]
	v_mfma_f32_16x16x32_bf16 v[64:67], v[184:187], v[216:219], v[64:67]
	s_setprio 0
	s_barrier
	s_add_i32 s34, s86, s54
	v_lshl_add_u64 v[220:221], v[220:221], 0, s[6:7]
	s_mov_b32 m0, s34
	ds_read_b128 v[188:191], v158 offset:49152
	ds_read_b128 v[192:195], v158 offset:50176
	ds_read_b128 v[196:199], v158 offset:51200
	ds_read_b128 v[200:203], v158 offset:52224
	ds_read_b128 v[204:207], v158 offset:53248
	ds_read_b128 v[208:211], v158 offset:54272
	ds_read_b128 v[212:215], v158 offset:55296
	ds_read_b128 v[216:219], v158 offset:56320
	global_load_lds_dwordx4 v[220:221], off
	s_add_i32 m0, s34, 0x2000
	s_add_u32 s34, s48, 0x40080
	v_lshl_add_u64 v[220:221], v[222:223], 0, s[6:7]
	s_addc_u32 s35, s49, 0
	s_add_i32 s48, s87, s54
	global_load_lds_dwordx4 v[220:221], off
	v_lshl_add_u64 v[220:221], s[34:35], 0, v[136:137]
	s_mov_b32 m0, s48
	s_nop 0
	global_load_lds_dwordx4 v[220:221], off
	v_lshl_add_u64 v[220:221], s[34:35], 0, v[132:133]
	s_add_i32 m0, s48, 0x2000
	s_nop 0
	global_load_lds_dwordx4 v[220:221], off
	v_lshl_add_u64 v[220:221], v[224:225], 0, s[6:7]
	s_mov_b32 m0, s63
	s_nop 0
	global_load_lds_dwordx4 v[220:221], off
	v_lshl_add_u64 v[220:221], v[226:227], 0, s[6:7]
	s_mov_b32 m0, s64
	s_nop 0
	global_load_lds_dwordx4 v[220:221], off
	s_waitcnt vmcnt(8)
	s_waitcnt lgkmcnt(0)
	s_barrier
	s_setprio 1
	s_waitcnt lgkmcnt(0)
	v_mfma_f32_16x16x32_bf16 v[60:63], v[148:151], v[188:191], v[60:63]
	v_mfma_f32_16x16x32_bf16 v[56:59], v[164:167], v[188:191], v[56:59]
	v_mfma_f32_16x16x32_bf16 v[44:47], v[148:151], v[196:199], v[44:47]
	v_mfma_f32_16x16x32_bf16 v[40:43], v[164:167], v[196:199], v[40:43]
	v_mfma_f32_16x16x32_bf16 v[28:31], v[148:151], v[204:207], v[28:31]
	v_mfma_f32_16x16x32_bf16 v[24:27], v[164:167], v[204:207], v[24:27]
	v_mfma_f32_16x16x32_bf16 v[12:15], v[148:151], v[212:215], v[12:15]
	v_mfma_f32_16x16x32_bf16 v[8:11], v[164:167], v[212:215], v[8:11]
	v_mfma_f32_16x16x32_bf16 v[60:63], v[160:163], v[192:195], v[60:63]
	v_mfma_f32_16x16x32_bf16 v[56:59], v[168:171], v[192:195], v[56:59]
	v_mfma_f32_16x16x32_bf16 v[44:47], v[160:163], v[200:203], v[44:47]
	v_mfma_f32_16x16x32_bf16 v[40:43], v[168:171], v[200:203], v[40:43]
	v_mfma_f32_16x16x32_bf16 v[28:31], v[160:163], v[208:211], v[28:31]
	v_mfma_f32_16x16x32_bf16 v[24:27], v[168:171], v[208:211], v[24:27]
	v_mfma_f32_16x16x32_bf16 v[12:15], v[160:163], v[216:219], v[12:15]
	v_mfma_f32_16x16x32_bf16 v[8:11], v[168:171], v[216:219], v[8:11]
	s_setprio 0
	s_setprio 1
	v_mfma_f32_16x16x32_bf16 v[52:55], v[172:175], v[188:191], v[52:55]
	v_mfma_f32_16x16x32_bf16 v[48:51], v[180:183], v[188:191], v[48:51]
	v_mfma_f32_16x16x32_bf16 v[36:39], v[172:175], v[196:199], v[36:39]
	v_mfma_f32_16x16x32_bf16 v[32:35], v[180:183], v[196:199], v[32:35]
	v_mfma_f32_16x16x32_bf16 v[20:23], v[172:175], v[204:207], v[20:23]
	v_mfma_f32_16x16x32_bf16 v[16:19], v[180:183], v[204:207], v[16:19]
	v_mfma_f32_16x16x32_bf16 v[4:7], v[172:175], v[212:215], v[4:7]
	v_mfma_f32_16x16x32_bf16 v[0:3], v[180:183], v[212:215], v[0:3]
	v_mfma_f32_16x16x32_bf16 v[52:55], v[176:179], v[192:195], v[52:55]
	v_mfma_f32_16x16x32_bf16 v[48:51], v[184:187], v[192:195], v[48:51]
	v_mfma_f32_16x16x32_bf16 v[36:39], v[176:179], v[200:203], v[36:39]
	v_mfma_f32_16x16x32_bf16 v[32:35], v[184:187], v[200:203], v[32:35]
	v_mfma_f32_16x16x32_bf16 v[20:23], v[176:179], v[208:211], v[20:23]
	v_mfma_f32_16x16x32_bf16 v[16:19], v[184:187], v[208:211], v[16:19]
	v_mfma_f32_16x16x32_bf16 v[4:7], v[176:179], v[216:219], v[4:7]
	v_mfma_f32_16x16x32_bf16 v[0:3], v[184:187], v[216:219], v[0:3]
	s_setprio 0
	s_barrier
	s_add_i32 s85, s85, 2
	s_add_u32 s42, s42, 0x100
	s_addc_u32 s43, s43, 0
	s_add_u32 s83, s83, 0x100
	s_addc_u32 s84, s84, 0

.LBB0_561:
	s_add_u32 s40, s40, 0xb0080
	s_addc_u32 s41, s41, 0
	s_add_u32 s13, s42, 0x100
	s_addc_u32 s77, s43, 0
	s_mov_b32 s81, -2
	s_waitcnt lgkmcnt(0)
	s_cmp_lg_u32 s66, 1
	s_cselect_b32 s100, s99, 0
	s_cmp_lg_u32 s100, 0
	s_cbranch_scc0 .Lmy_nobar2_6
	s_barrier
.Lmy_nobar2_6:
	ds_read_b128 v[148:151], v154
	ds_read_b128 v[160:163], v154 offset:1024
	ds_read_b128 v[164:167], v154 offset:2048
	ds_read_b128 v[168:171], v154 offset:3072
	ds_read_b128 v[172:175], v155
	ds_read_b128 v[176:179], v155 offset:1024
	ds_read_b128 v[180:183], v155 offset:2048
	ds_read_b128 v[184:187], v155 offset:3072
	s_add_u32 s34, s40, 0xfff50080
	s_addc_u32 s35, s41, -1
	s_cmp_eq_u32 s81, 40
	s_cselect_b32 s49, s1, s35
	s_cselect_b32 s48, s0, s34
	s_cselect_b32 s43, s29, s77
	s_cselect_b32 s42, s28, s13
	v_lshl_add_u64 v[220:221], s[40:41], 0, v[140:141]
	s_add_i32 m0, s52, 0xc000
	ds_read_b128 v[188:191], v157
	ds_read_b128 v[192:195], v157 offset:1024
	ds_read_b128 v[196:199], v157 offset:2048
	ds_read_b128 v[200:203], v157 offset:3072
	ds_read_b128 v[204:207], v157 offset:4096
	ds_read_b128 v[208:211], v157 offset:5120
	ds_read_b128 v[212:215], v157 offset:6144
	ds_read_b128 v[216:219], v157 offset:7168
	global_load_lds_dwordx4 v[220:221], off
	v_lshl_add_u64 v[220:221], s[40:41], 0, v[142:143]
	s_add_i32 m0, s52, 0xe000
	s_nop 0
	global_load_lds_dwordx4 v[220:221], off
	s_waitcnt vmcnt(8)
	s_waitcnt lgkmcnt(0)
	s_barrier
	s_setprio 1
	s_waitcnt lgkmcnt(0)
	v_mfma_f32_16x16x32_bf16 v[124:127], v[148:151], v[188:191], 0
	v_mfma_f32_16x16x32_bf16 v[120:123], v[164:167], v[188:191], 0
	v_mfma_f32_16x16x32_bf16 v[108:111], v[148:151], v[196:199], 0
	v_mfma_f32_16x16x32_bf16 v[104:107], v[164:167], v[196:199], 0
	v_mfma_f32_16x16x32_bf16 v[92:95], v[148:151], v[204:207], 0
	v_mfma_f32_16x16x32_bf16 v[88:91], v[164:167], v[204:207], 0
	v_mfma_f32_16x16x32_bf16 v[76:79], v[148:151], v[212:215], 0
	v_mfma_f32_16x16x32_bf16 v[72:75], v[164:167], v[212:215], 0
	v_mfma_f32_16x16x32_bf16 v[124:127], v[160:163], v[192:195], v[124:127]
	v_mfma_f32_16x16x32_bf16 v[120:123], v[168:171], v[192:195], v[120:123]
	v_mfma_f32_16x16x32_bf16 v[108:111], v[160:163], v[200:203], v[108:111]
	v_mfma_f32_16x16x32_bf16 v[104:107], v[168:171], v[200:203], v[104:107]
	v_mfma_f32_16x16x32_bf16 v[92:95], v[160:163], v[208:211], v[92:95]
	v_mfma_f32_16x16x32_bf16 v[88:91], v[168:171], v[208:211], v[88:91]
	v_mfma_f32_16x16x32_bf16 v[76:79], v[160:163], v[216:219], v[76:79]
	v_mfma_f32_16x16x32_bf16 v[72:75], v[168:171], v[216:219], v[72:75]
	s_setprio 0
	s_setprio 1
	v_mfma_f32_16x16x32_bf16 v[116:119], v[172:175], v[188:191], 0
	v_mfma_f32_16x16x32_bf16 v[112:115], v[180:183], v[188:191], 0
	v_mfma_f32_16x16x32_bf16 v[100:103], v[172:175], v[196:199], 0
	v_mfma_f32_16x16x32_bf16 v[96:99], v[180:183], v[196:199], 0
	v_mfma_f32_16x16x32_bf16 v[84:87], v[172:175], v[204:207], 0
	v_mfma_f32_16x16x32_bf16 v[80:83], v[180:183], v[204:207], 0
	v_mfma_f32_16x16x32_bf16 v[68:71], v[172:175], v[212:215], 0
	v_mfma_f32_16x16x32_bf16 v[64:67], v[180:183], v[212:215], 0
	v_mfma_f32_16x16x32_bf16 v[116:119], v[176:179], v[192:195], v[116:119]
	v_mfma_f32_16x16x32_bf16 v[112:115], v[184:187], v[192:195], v[112:115]
	v_mfma_f32_16x16x32_bf16 v[100:103], v[176:179], v[200:203], v[100:103]
	v_mfma_f32_16x16x32_bf16 v[96:99], v[184:187], v[200:203], v[96:99]
	v_mfma_f32_16x16x32_bf16 v[84:87], v[176:179], v[208:211], v[84:87]
	v_mfma_f32_16x16x32_bf16 v[80:83], v[184:187], v[208:211], v[80:83]
	v_mfma_f32_16x16x32_bf16 v[68:71], v[176:179], v[216:219], v[68:71]
	v_mfma_f32_16x16x32_bf16 v[64:67], v[184:187], v[216:219], v[64:67]
	s_setprio 0
	s_barrier
	s_add_i32 s34, s64, s51
	v_lshl_add_u64 v[220:221], s[42:43], 0, v[134:135]
	s_mov_b32 m0, s34
	ds_read_b128 v[188:191], v157 offset:16384
	ds_read_b128 v[192:195], v157 offset:17408
	ds_read_b128 v[196:199], v157 offset:18432
	ds_read_b128 v[200:203], v157 offset:19456
	ds_read_b128 v[204:207], v157 offset:20480
	ds_read_b128 v[208:211], v157 offset:21504
	ds_read_b128 v[212:215], v157 offset:22528
	ds_read_b128 v[216:219], v157 offset:23552
	global_load_lds_dwordx4 v[220:221], off
	s_add_i32 m0, s34, 0x2000
	s_add_u32 s34, s42, 0xb0000
	v_lshl_add_u64 v[222:223], s[42:43], 0, v[138:139]
	s_addc_u32 s35, s43, 0
	s_add_i32 s82, s65, s51
	global_load_lds_dwordx4 v[222:223], off
	v_lshl_add_u64 v[224:225], s[34:35], 0, v[134:135]
	s_mov_b32 m0, s82
	v_lshl_add_u64 v[226:227], s[48:49], 0, v[136:137]
	global_load_lds_dwordx4 v[224:225], off
	v_lshl_add_u64 v[224:225], s[34:35], 0, v[138:139]
	s_add_i32 m0, s82, 0x2000
	s_nop 0
	global_load_lds_dwordx4 v[224:225], off
	v_lshl_add_u64 v[224:225], s[48:49], 0, v[132:133]
	s_mov_b32 m0, s52
	s_nop 0
	global_load_lds_dwordx4 v[224:225], off
	s_mov_b32 m0, s53
	s_nop 0
	global_load_lds_dwordx4 v[226:227], off
	s_waitcnt vmcnt(8)
	s_waitcnt lgkmcnt(0)
	s_barrier
	s_setprio 1
	s_waitcnt lgkmcnt(0)
	v_mfma_f32_16x16x32_bf16 v[60:63], v[148:151], v[188:191], 0
	v_mfma_f32_16x16x32_bf16 v[56:59], v[164:167], v[188:191], 0
	v_mfma_f32_16x16x32_bf16 v[44:47], v[148:151], v[196:199], 0
	v_mfma_f32_16x16x32_bf16 v[40:43], v[164:167], v[196:199], 0
	v_mfma_f32_16x16x32_bf16 v[28:31], v[148:151], v[204:207], 0
	v_mfma_f32_16x16x32_bf16 v[24:27], v[164:167], v[204:207], 0
	v_mfma_f32_16x16x32_bf16 v[12:15], v[148:151], v[212:215], 0
	v_mfma_f32_16x16x32_bf16 v[8:11], v[164:167], v[212:215], 0
	v_mfma_f32_16x16x32_bf16 v[60:63], v[160:163], v[192:195], v[60:63]
	v_mfma_f32_16x16x32_bf16 v[56:59], v[168:171], v[192:195], v[56:59]
	v_mfma_f32_16x16x32_bf16 v[44:47], v[160:163], v[200:203], v[44:47]
	v_mfma_f32_16x16x32_bf16 v[40:43], v[168:171], v[200:203], v[40:43]
	v_mfma_f32_16x16x32_bf16 v[28:31], v[160:163], v[208:211], v[28:31]
	v_mfma_f32_16x16x32_bf16 v[24:27], v[168:171], v[208:211], v[24:27]
	v_mfma_f32_16x16x32_bf16 v[12:15], v[160:163], v[216:219], v[12:15]
	v_mfma_f32_16x16x32_bf16 v[8:11], v[168:171], v[216:219], v[8:11]
	s_setprio 0
	s_setprio 1
	v_mfma_f32_16x16x32_bf16 v[52:55], v[172:175], v[188:191], 0
	v_mfma_f32_16x16x32_bf16 v[48:51], v[180:183], v[188:191], 0
	v_mfma_f32_16x16x32_bf16 v[36:39], v[172:175], v[196:199], 0
	v_mfma_f32_16x16x32_bf16 v[32:35], v[180:183], v[196:199], 0
	v_mfma_f32_16x16x32_bf16 v[20:23], v[172:175], v[204:207], 0
	v_mfma_f32_16x16x32_bf16 v[16:19], v[180:183], v[204:207], 0
	v_mfma_f32_16x16x32_bf16 v[4:7], v[172:175], v[212:215], 0
	v_mfma_f32_16x16x32_bf16 v[0:3], v[180:183], v[212:215], 0
	v_mfma_f32_16x16x32_bf16 v[52:55], v[176:179], v[192:195], v[52:55]
	v_mfma_f32_16x16x32_bf16 v[48:51], v[184:187], v[192:195], v[48:51]
	v_mfma_f32_16x16x32_bf16 v[36:39], v[176:179], v[200:203], v[36:39]
	v_mfma_f32_16x16x32_bf16 v[32:35], v[184:187], v[200:203], v[32:35]
	v_mfma_f32_16x16x32_bf16 v[20:23], v[176:179], v[208:211], v[20:23]
	v_mfma_f32_16x16x32_bf16 v[16:19], v[184:187], v[208:211], v[16:19]
	v_mfma_f32_16x16x32_bf16 v[4:7], v[176:179], v[216:219], v[4:7]
	v_mfma_f32_16x16x32_bf16 v[0:3], v[184:187], v[216:219], v[0:3]
	s_setprio 0
	s_barrier
	s_add_i32 s82, 0, 0x18000
	v_add_u32_e32 v159, s82, v152
	s_add_i32 s83, 0, 0x1c000
	ds_read_b128 v[148:151], v159
	ds_read_b128 v[160:163], v159 offset:1024
	ds_read_b128 v[164:167], v159 offset:2048
	ds_read_b128 v[168:171], v159 offset:3072
	v_add_u32_e32 v159, s83, v152
	ds_read_b128 v[172:175], v159
	ds_read_b128 v[176:179], v159 offset:1024
	ds_read_b128 v[180:183], v159 offset:2048
	ds_read_b128 v[184:187], v159 offset:3072
	s_add_u32 s34, s48, 0xb0000
	s_addc_u32 s35, s49, 0
	s_mov_b32 m0, s54
	v_lshl_add_u64 v[228:229], s[34:35], 0, v[132:133]
	ds_read_b128 v[188:191], v157 offset:32768
	ds_read_b128 v[192:195], v157 offset:33792
	ds_read_b128 v[196:199], v157 offset:34816
	ds_read_b128 v[200:203], v157 offset:35840
	ds_read_b128 v[204:207], v157 offset:36864
	ds_read_b128 v[208:211], v157 offset:37888
	ds_read_b128 v[212:215], v157 offset:38912
	ds_read_b128 v[216:219], v157 offset:39936
	global_load_lds_dwordx4 v[228:229], off
	v_lshl_add_u64 v[228:229], s[34:35], 0, v[136:137]
	s_mov_b32 m0, s55
	s_nop 0
	global_load_lds_dwordx4 v[228:229], off
	s_waitcnt vmcnt(8)
	s_waitcnt lgkmcnt(0)
	s_barrier
	s_setprio 1
	s_waitcnt lgkmcnt(0)
	v_mfma_f32_16x16x32_bf16 v[124:127], v[148:151], v[188:191], v[124:127]
	v_mfma_f32_16x16x32_bf16 v[120:123], v[164:167], v[188:191], v[120:123]
	v_mfma_f32_16x16x32_bf16 v[108:111], v[148:151], v[196:199], v[108:111]
	v_mfma_f32_16x16x32_bf16 v[104:107], v[164:167], v[196:199], v[104:107]
	v_mfma_f32_16x16x32_bf16 v[92:95], v[148:151], v[204:207], v[92:95]
	v_mfma_f32_16x16x32_bf16 v[88:91], v[164:167], v[204:207], v[88:91]
	v_mfma_f32_16x16x32_bf16 v[76:79], v[148:151], v[212:215], v[76:79]
	v_mfma_f32_16x16x32_bf16 v[72:75], v[164:167], v[212:215], v[72:75]
	v_mfma_f32_16x16x32_bf16 v[124:127], v[160:163], v[192:195], v[124:127]
	v_mfma_f32_16x16x32_bf16 v[120:123], v[168:171], v[192:195], v[120:123]
	v_mfma_f32_16x16x32_bf16 v[108:111], v[160:163], v[200:203], v[108:111]
	v_mfma_f32_16x16x32_bf16 v[104:107], v[168:171], v[200:203], v[104:107]
	v_mfma_f32_16x16x32_bf16 v[92:95], v[160:163], v[208:211], v[92:95]
	v_mfma_f32_16x16x32_bf16 v[88:91], v[168:171], v[208:211], v[88:91]
	v_mfma_f32_16x16x32_bf16 v[76:79], v[160:163], v[216:219], v[76:79]
	v_mfma_f32_16x16x32_bf16 v[72:75], v[168:171], v[216:219], v[72:75]
	s_setprio 0
	s_setprio 1
	v_mfma_f32_16x16x32_bf16 v[116:119], v[172:175], v[188:191], v[116:119]
	v_mfma_f32_16x16x32_bf16 v[112:115], v[180:183], v[188:191], v[112:115]
	v_mfma_f32_16x16x32_bf16 v[100:103], v[172:175], v[196:199], v[100:103]
	v_mfma_f32_16x16x32_bf16 v[96:99], v[180:183], v[196:199], v[96:99]
	v_mfma_f32_16x16x32_bf16 v[84:87], v[172:175], v[204:207], v[84:87]
	v_mfma_f32_16x16x32_bf16 v[80:83], v[180:183], v[204:207], v[80:83]
	v_mfma_f32_16x16x32_bf16 v[68:71], v[172:175], v[212:215], v[68:71]
	v_mfma_f32_16x16x32_bf16 v[64:67], v[180:183], v[212:215], v[64:67]
	v_mfma_f32_16x16x32_bf16 v[116:119], v[176:179], v[192:195], v[116:119]
	v_mfma_f32_16x16x32_bf16 v[112:115], v[184:187], v[192:195], v[112:115]
	v_mfma_f32_16x16x32_bf16 v[100:103], v[176:179], v[200:203], v[100:103]
	v_mfma_f32_16x16x32_bf16 v[96:99], v[184:187], v[200:203], v[96:99]
	v_mfma_f32_16x16x32_bf16 v[84:87], v[176:179], v[208:211], v[84:87]
	v_mfma_f32_16x16x32_bf16 v[80:83], v[184:187], v[208:211], v[80:83]
	v_mfma_f32_16x16x32_bf16 v[68:71], v[176:179], v[216:219], v[68:71]
	v_mfma_f32_16x16x32_bf16 v[64:67], v[184:187], v[216:219], v[64:67]
	s_setprio 0
	s_barrier
	s_add_i32 s34, s82, s51
	v_lshl_add_u64 v[220:221], v[220:221], 0, s[22:23]
	s_mov_b32 m0, s34
	ds_read_b128 v[188:191], v157 offset:49152
	ds_read_b128 v[192:195], v157 offset:50176
	ds_read_b128 v[196:199], v157 offset:51200
	ds_read_b128 v[200:203], v157 offset:52224
	ds_read_b128 v[204:207], v157 offset:53248
	ds_read_b128 v[208:211], v157 offset:54272
	ds_read_b128 v[212:215], v157 offset:55296
	ds_read_b128 v[216:219], v157 offset:56320
	global_load_lds_dwordx4 v[220:221], off
	s_add_i32 m0, s34, 0x2000
	s_add_u32 s34, s42, 0xb0080
	v_lshl_add_u64 v[220:221], v[222:223], 0, s[22:23]
	s_addc_u32 s35, s43, 0
	s_add_i32 s42, s83, s51
	global_load_lds_dwordx4 v[220:221], off
	v_lshl_add_u64 v[220:221], s[34:35], 0, v[134:135]
	s_mov_b32 m0, s42
	s_nop 0
	global_load_lds_dwordx4 v[220:221], off
	v_lshl_add_u64 v[220:221], s[34:35], 0, v[138:139]
	s_add_i32 m0, s42, 0x2000
	s_nop 0
	global_load_lds_dwordx4 v[220:221], off
	v_lshl_add_u64 v[220:221], v[224:225], 0, s[22:23]
	s_mov_b32 m0, s57
	s_nop 0
	global_load_lds_dwordx4 v[220:221], off
	v_lshl_add_u64 v[220:221], v[226:227], 0, s[22:23]
	s_mov_b32 m0, s58
	s_nop 0
	global_load_lds_dwordx4 v[220:221], off
	s_waitcnt vmcnt(8)
	s_waitcnt lgkmcnt(0)
	s_barrier
	s_setprio 1
	s_waitcnt lgkmcnt(0)
	v_mfma_f32_16x16x32_bf16 v[60:63], v[148:151], v[188:191], v[60:63]
	v_mfma_f32_16x16x32_bf16 v[56:59], v[164:167], v[188:191], v[56:59]
	v_mfma_f32_16x16x32_bf16 v[44:47], v[148:151], v[196:199], v[44:47]
	v_mfma_f32_16x16x32_bf16 v[40:43], v[164:167], v[196:199], v[40:43]
	v_mfma_f32_16x16x32_bf16 v[28:31], v[148:151], v[204:207], v[28:31]
	v_mfma_f32_16x16x32_bf16 v[24:27], v[164:167], v[204:207], v[24:27]
	v_mfma_f32_16x16x32_bf16 v[12:15], v[148:151], v[212:215], v[12:15]
	v_mfma_f32_16x16x32_bf16 v[8:11], v[164:167], v[212:215], v[8:11]
	v_mfma_f32_16x16x32_bf16 v[60:63], v[160:163], v[192:195], v[60:63]
	v_mfma_f32_16x16x32_bf16 v[56:59], v[168:171], v[192:195], v[56:59]
	v_mfma_f32_16x16x32_bf16 v[44:47], v[160:163], v[200:203], v[44:47]
	v_mfma_f32_16x16x32_bf16 v[40:43], v[168:171], v[200:203], v[40:43]
	v_mfma_f32_16x16x32_bf16 v[28:31], v[160:163], v[208:211], v[28:31]
	v_mfma_f32_16x16x32_bf16 v[24:27], v[168:171], v[208:211], v[24:27]
	v_mfma_f32_16x16x32_bf16 v[12:15], v[160:163], v[216:219], v[12:15]
	v_mfma_f32_16x16x32_bf16 v[8:11], v[168:171], v[216:219], v[8:11]
	s_setprio 0
	s_setprio 1
	v_mfma_f32_16x16x32_bf16 v[52:55], v[172:175], v[188:191], v[52:55]
	v_mfma_f32_16x16x32_bf16 v[48:51], v[180:183], v[188:191], v[48:51]
	v_mfma_f32_16x16x32_bf16 v[36:39], v[172:175], v[196:199], v[36:39]
	v_mfma_f32_16x16x32_bf16 v[32:35], v[180:183], v[196:199], v[32:35]
	v_mfma_f32_16x16x32_bf16 v[20:23], v[172:175], v[204:207], v[20:23]
	v_mfma_f32_16x16x32_bf16 v[16:19], v[180:183], v[204:207], v[16:19]
	v_mfma_f32_16x16x32_bf16 v[4:7], v[172:175], v[212:215], v[4:7]
	v_mfma_f32_16x16x32_bf16 v[0:3], v[180:183], v[212:215], v[0:3]
	v_mfma_f32_16x16x32_bf16 v[52:55], v[176:179], v[192:195], v[52:55]
	v_mfma_f32_16x16x32_bf16 v[48:51], v[184:187], v[192:195], v[48:51]
	v_mfma_f32_16x16x32_bf16 v[36:39], v[176:179], v[200:203], v[36:39]
	v_mfma_f32_16x16x32_bf16 v[32:35], v[184:187], v[200:203], v[32:35]
	v_mfma_f32_16x16x32_bf16 v[20:23], v[176:179], v[208:211], v[20:23]
	v_mfma_f32_16x16x32_bf16 v[16:19], v[184:187], v[208:211], v[16:19]
	v_mfma_f32_16x16x32_bf16 v[4:7], v[176:179], v[216:219], v[4:7]
	v_mfma_f32_16x16x32_bf16 v[0:3], v[184:187], v[216:219], v[0:3]
	s_setprio 0
	s_barrier
	s_add_i32 s81, s81, 2
	s_add_u32 s40, s40, 0x100
	s_addc_u32 s41, s41, 0
	s_add_u32 s13, s13, 0x100
	s_addc_u32 s77, s77, 0

.LBB0_654:
	s_ashr_i32 s43, s42, 31
	s_lshl_b64 s[12:13], s[42:43], 19
	s_add_u32 s48, s14, s12
	s_addc_u32 s49, s15, s13
	s_and_b64 s[12:13], s[6:7], exec
	s_cselect_b32 s9, s49, s53
	s_cselect_b32 s10, s48, s52
	s_ashr_i32 s41, s40, 31
	s_lshl_b64 s[12:13], s[40:41], 19
	s_add_u32 s50, s63, s12
	s_addc_u32 s51, s64, s13
	s_and_b64 s[12:13], s[6:7], exec
	s_cselect_b32 s12, s51, s55
	s_cselect_b32 s13, s50, s54
	s_add_u32 s52, s52, 0x40080
	s_addc_u32 s53, s53, 0
	s_add_u32 s41, s54, 0x100
	s_addc_u32 s43, s55, 0
	s_mov_b32 s77, -2
	s_waitcnt lgkmcnt(0)
	s_cmp_lg_u32 s93, 1
	s_cselect_b32 s100, s99, 0
	s_cmp_lg_u32 s100, 0
	s_cbranch_scc0 .Lmy_nobar2_7
	s_barrier
.Lmy_nobar2_7:
	ds_read_b128 v[148:151], v160
	ds_read_b128 v[152:155], v160 offset:1024
	ds_read_b128 v[164:167], v160 offset:2048
	ds_read_b128 v[168:171], v160 offset:3072
	ds_read_b128 v[172:175], v161
	ds_read_b128 v[176:179], v161 offset:1024
	ds_read_b128 v[180:183], v161 offset:2048
	ds_read_b128 v[184:187], v161 offset:3072
	s_add_u32 s34, s52, 0xfffc0080
	s_addc_u32 s35, s53, -1
	s_cmp_eq_u32 s77, 12
	s_cselect_b32 s57, s9, s35
	s_cselect_b32 s56, s10, s34
	s_cselect_b32 s55, s12, s43
	s_cselect_b32 s54, s13, s41
	v_lshl_add_u64 v[220:221], s[52:53], 0, v[140:141]
	s_add_i32 m0, s65, 0xc000
	ds_read_b128 v[188:191], v162
	ds_read_b128 v[192:195], v162 offset:1024
	ds_read_b128 v[196:199], v162 offset:2048
	ds_read_b128 v[200:203], v162 offset:3072
	ds_read_b128 v[204:207], v162 offset:4096
	ds_read_b128 v[208:211], v162 offset:5120
	ds_read_b128 v[212:215], v162 offset:6144
	ds_read_b128 v[216:219], v162 offset:7168
	global_load_lds_dwordx4 v[220:221], off
	v_lshl_add_u64 v[220:221], s[52:53], 0, v[142:143]
	s_add_i32 m0, s65, 0xe000
	s_nop 0
	global_load_lds_dwordx4 v[220:221], off
	s_waitcnt vmcnt(8)
	s_waitcnt lgkmcnt(0)
	s_barrier
	s_setprio 1
	s_waitcnt lgkmcnt(0)
	v_mfma_f32_16x16x32_bf16 v[124:127], v[148:151], v[188:191], 0
	v_mfma_f32_16x16x32_bf16 v[120:123], v[164:167], v[188:191], 0
	v_mfma_f32_16x16x32_bf16 v[108:111], v[148:151], v[196:199], 0
	v_mfma_f32_16x16x32_bf16 v[104:107], v[164:167], v[196:199], 0
	v_mfma_f32_16x16x32_bf16 v[92:95], v[148:151], v[204:207], 0
	v_mfma_f32_16x16x32_bf16 v[88:91], v[164:167], v[204:207], 0
	v_mfma_f32_16x16x32_bf16 v[76:79], v[148:151], v[212:215], 0
	v_mfma_f32_16x16x32_bf16 v[72:75], v[164:167], v[212:215], 0
	v_mfma_f32_16x16x32_bf16 v[124:127], v[152:155], v[192:195], v[124:127]
	v_mfma_f32_16x16x32_bf16 v[120:123], v[168:171], v[192:195], v[120:123]
	v_mfma_f32_16x16x32_bf16 v[108:111], v[152:155], v[200:203], v[108:111]
	v_mfma_f32_16x16x32_bf16 v[104:107], v[168:171], v[200:203], v[104:107]
	v_mfma_f32_16x16x32_bf16 v[92:95], v[152:155], v[208:211], v[92:95]
	v_mfma_f32_16x16x32_bf16 v[88:91], v[168:171], v[208:211], v[88:91]
	v_mfma_f32_16x16x32_bf16 v[76:79], v[152:155], v[216:219], v[76:79]
	v_mfma_f32_16x16x32_bf16 v[72:75], v[168:171], v[216:219], v[72:75]
	s_setprio 0
	s_setprio 1
	v_mfma_f32_16x16x32_bf16 v[116:119], v[172:175], v[188:191], 0
	v_mfma_f32_16x16x32_bf16 v[112:115], v[180:183], v[188:191], 0
	v_mfma_f32_16x16x32_bf16 v[100:103], v[172:175], v[196:199], 0
	v_mfma_f32_16x16x32_bf16 v[96:99], v[180:183], v[196:199], 0
	v_mfma_f32_16x16x32_bf16 v[84:87], v[172:175], v[204:207], 0
	v_mfma_f32_16x16x32_bf16 v[80:83], v[180:183], v[204:207], 0
	v_mfma_f32_16x16x32_bf16 v[68:71], v[172:175], v[212:215], 0
	v_mfma_f32_16x16x32_bf16 v[64:67], v[180:183], v[212:215], 0
	v_mfma_f32_16x16x32_bf16 v[116:119], v[176:179], v[192:195], v[116:119]
	v_mfma_f32_16x16x32_bf16 v[112:115], v[184:187], v[192:195], v[112:115]
	v_mfma_f32_16x16x32_bf16 v[100:103], v[176:179], v[200:203], v[100:103]
	v_mfma_f32_16x16x32_bf16 v[96:99], v[184:187], v[200:203], v[96:99]
	v_mfma_f32_16x16x32_bf16 v[84:87], v[176:179], v[208:211], v[84:87]
	v_mfma_f32_16x16x32_bf16 v[80:83], v[184:187], v[208:211], v[80:83]
	v_mfma_f32_16x16x32_bf16 v[68:71], v[176:179], v[216:219], v[68:71]
	v_mfma_f32_16x16x32_bf16 v[64:67], v[184:187], v[216:219], v[64:67]
	s_setprio 0
	s_barrier
	s_add_i32 s34, s88, s62
	v_lshl_add_u64 v[220:221], s[54:55], 0, v[134:135]
	s_mov_b32 m0, s34
	ds_read_b128 v[188:191], v162 offset:16384
	ds_read_b128 v[192:195], v162 offset:17408
	ds_read_b128 v[196:199], v162 offset:18432
	ds_read_b128 v[200:203], v162 offset:19456
	ds_read_b128 v[204:207], v162 offset:20480
	ds_read_b128 v[208:211], v162 offset:21504
	ds_read_b128 v[212:215], v162 offset:22528
	ds_read_b128 v[216:219], v162 offset:23552
	global_load_lds_dwordx4 v[220:221], off
	s_add_i32 m0, s34, 0x2000
	s_add_u32 s34, s54, 0x40000
	v_lshl_add_u64 v[222:223], s[54:55], 0, v[138:139]
	s_addc_u32 s35, s55, 0
	s_add_i32 s90, s89, s62
	global_load_lds_dwordx4 v[222:223], off
	v_lshl_add_u64 v[224:225], s[34:35], 0, v[134:135]
	s_mov_b32 m0, s90
	v_lshl_add_u64 v[226:227], s[56:57], 0, v[136:137]
	global_load_lds_dwordx4 v[224:225], off
	v_lshl_add_u64 v[224:225], s[34:35], 0, v[138:139]
	s_add_i32 m0, s90, 0x2000
	s_nop 0
	global_load_lds_dwordx4 v[224:225], off
	v_lshl_add_u64 v[224:225], s[56:57], 0, v[132:133]
	s_mov_b32 m0, s65
	s_nop 0
	global_load_lds_dwordx4 v[224:225], off
	s_mov_b32 m0, s66
	s_nop 0
	global_load_lds_dwordx4 v[226:227], off
	s_waitcnt vmcnt(8)
	s_waitcnt lgkmcnt(0)
	s_barrier
	s_setprio 1
	s_waitcnt lgkmcnt(0)
	v_mfma_f32_16x16x32_bf16 v[60:63], v[148:151], v[188:191], 0
	v_mfma_f32_16x16x32_bf16 v[56:59], v[164:167], v[188:191], 0
	v_mfma_f32_16x16x32_bf16 v[44:47], v[148:151], v[196:199], 0
	v_mfma_f32_16x16x32_bf16 v[40:43], v[164:167], v[196:199], 0
	v_mfma_f32_16x16x32_bf16 v[28:31], v[148:151], v[204:207], 0
	v_mfma_f32_16x16x32_bf16 v[24:27], v[164:167], v[204:207], 0
	v_mfma_f32_16x16x32_bf16 v[12:15], v[148:151], v[212:215], 0
	v_mfma_f32_16x16x32_bf16 v[8:11], v[164:167], v[212:215], 0
	v_mfma_f32_16x16x32_bf16 v[60:63], v[152:155], v[192:195], v[60:63]
	v_mfma_f32_16x16x32_bf16 v[56:59], v[168:171], v[192:195], v[56:59]
	v_mfma_f32_16x16x32_bf16 v[44:47], v[152:155], v[200:203], v[44:47]
	v_mfma_f32_16x16x32_bf16 v[40:43], v[168:171], v[200:203], v[40:43]
	v_mfma_f32_16x16x32_bf16 v[28:31], v[152:155], v[208:211], v[28:31]
	v_mfma_f32_16x16x32_bf16 v[24:27], v[168:171], v[208:211], v[24:27]
	v_mfma_f32_16x16x32_bf16 v[12:15], v[152:155], v[216:219], v[12:15]
	v_mfma_f32_16x16x32_bf16 v[8:11], v[168:171], v[216:219], v[8:11]
	s_setprio 0
	s_setprio 1
	v_mfma_f32_16x16x32_bf16 v[52:55], v[172:175], v[188:191], 0
	v_mfma_f32_16x16x32_bf16 v[48:51], v[180:183], v[188:191], 0
	v_mfma_f32_16x16x32_bf16 v[36:39], v[172:175], v[196:199], 0
	v_mfma_f32_16x16x32_bf16 v[32:35], v[180:183], v[196:199], 0
	v_mfma_f32_16x16x32_bf16 v[20:23], v[172:175], v[204:207], 0
	v_mfma_f32_16x16x32_bf16 v[16:19], v[180:183], v[204:207], 0
	v_mfma_f32_16x16x32_bf16 v[4:7], v[172:175], v[212:215], 0
	v_mfma_f32_16x16x32_bf16 v[0:3], v[180:183], v[212:215], 0
	v_mfma_f32_16x16x32_bf16 v[52:55], v[176:179], v[192:195], v[52:55]
	v_mfma_f32_16x16x32_bf16 v[48:51], v[184:187], v[192:195], v[48:51]
	v_mfma_f32_16x16x32_bf16 v[36:39], v[176:179], v[200:203], v[36:39]
	v_mfma_f32_16x16x32_bf16 v[32:35], v[184:187], v[200:203], v[32:35]
	v_mfma_f32_16x16x32_bf16 v[20:23], v[176:179], v[208:211], v[20:23]
	v_mfma_f32_16x16x32_bf16 v[16:19], v[184:187], v[208:211], v[16:19]
	v_mfma_f32_16x16x32_bf16 v[4:7], v[176:179], v[216:219], v[4:7]
	v_mfma_f32_16x16x32_bf16 v[0:3], v[184:187], v[216:219], v[0:3]
	s_setprio 0
	s_barrier
	s_add_i32 s90, 0, 0x18000
	s_add_i32 s95, 0, 0x1c000
	v_add_u32_e32 v168, s90, v157
	v_add_u32_e32 v184, s95, v157
	ds_read_b128 v[148:151], v168
	ds_read_b128 v[152:155], v168 offset:1024
	ds_read_b128 v[164:167], v168 offset:2048
	ds_read_b128 v[168:171], v168 offset:3072
	ds_read_b128 v[172:175], v184
	ds_read_b128 v[176:179], v184 offset:1024
	ds_read_b128 v[180:183], v184 offset:2048
	ds_read_b128 v[184:187], v184 offset:3072
	s_add_u32 s34, s56, 0x40000
	s_addc_u32 s35, s57, 0
	s_mov_b32 m0, s67
	v_lshl_add_u64 v[228:229], s[34:35], 0, v[132:133]
	ds_read_b128 v[188:191], v162 offset:32768
	ds_read_b128 v[192:195], v162 offset:33792
	ds_read_b128 v[196:199], v162 offset:34816
	ds_read_b128 v[200:203], v162 offset:35840
	ds_read_b128 v[204:207], v162 offset:36864
	ds_read_b128 v[208:211], v162 offset:37888
	ds_read_b128 v[212:215], v162 offset:38912
	ds_read_b128 v[216:219], v162 offset:39936
	global_load_lds_dwordx4 v[228:229], off
	v_lshl_add_u64 v[228:229], s[34:35], 0, v[136:137]
	s_mov_b32 m0, s79
	s_nop 0
	global_load_lds_dwordx4 v[228:229], off
	s_waitcnt vmcnt(8)
	s_waitcnt lgkmcnt(0)
	s_barrier
	s_setprio 1
	s_waitcnt lgkmcnt(0)
	v_mfma_f32_16x16x32_bf16 v[124:127], v[148:151], v[188:191], v[124:127]
	v_mfma_f32_16x16x32_bf16 v[120:123], v[164:167], v[188:191], v[120:123]
	v_mfma_f32_16x16x32_bf16 v[108:111], v[148:151], v[196:199], v[108:111]
	v_mfma_f32_16x16x32_bf16 v[104:107], v[164:167], v[196:199], v[104:107]
	v_mfma_f32_16x16x32_bf16 v[92:95], v[148:151], v[204:207], v[92:95]
	v_mfma_f32_16x16x32_bf16 v[88:91], v[164:167], v[204:207], v[88:91]
	v_mfma_f32_16x16x32_bf16 v[76:79], v[148:151], v[212:215], v[76:79]
	v_mfma_f32_16x16x32_bf16 v[72:75], v[164:167], v[212:215], v[72:75]
	v_mfma_f32_16x16x32_bf16 v[124:127], v[152:155], v[192:195], v[124:127]
	v_mfma_f32_16x16x32_bf16 v[120:123], v[168:171], v[192:195], v[120:123]
	v_mfma_f32_16x16x32_bf16 v[108:111], v[152:155], v[200:203], v[108:111]
	v_mfma_f32_16x16x32_bf16 v[104:107], v[168:171], v[200:203], v[104:107]
	v_mfma_f32_16x16x32_bf16 v[92:95], v[152:155], v[208:211], v[92:95]
	v_mfma_f32_16x16x32_bf16 v[88:91], v[168:171], v[208:211], v[88:91]
	v_mfma_f32_16x16x32_bf16 v[76:79], v[152:155], v[216:219], v[76:79]
	v_mfma_f32_16x16x32_bf16 v[72:75], v[168:171], v[216:219], v[72:75]
	s_setprio 0
	s_setprio 1
	v_mfma_f32_16x16x32_bf16 v[116:119], v[172:175], v[188:191], v[116:119]
	v_mfma_f32_16x16x32_bf16 v[112:115], v[180:183], v[188:191], v[112:115]
	v_mfma_f32_16x16x32_bf16 v[100:103], v[172:175], v[196:199], v[100:103]
	v_mfma_f32_16x16x32_bf16 v[96:99], v[180:183], v[196:199], v[96:99]
	v_mfma_f32_16x16x32_bf16 v[84:87], v[172:175], v[204:207], v[84:87]
	v_mfma_f32_16x16x32_bf16 v[80:83], v[180:183], v[204:207], v[80:83]
	v_mfma_f32_16x16x32_bf16 v[68:71], v[172:175], v[212:215], v[68:71]
	v_mfma_f32_16x16x32_bf16 v[64:67], v[180:183], v[212:215], v[64:67]
	v_mfma_f32_16x16x32_bf16 v[116:119], v[176:179], v[192:195], v[116:119]
	v_mfma_f32_16x16x32_bf16 v[112:115], v[184:187], v[192:195], v[112:115]
	v_mfma_f32_16x16x32_bf16 v[100:103], v[176:179], v[200:203], v[100:103]
	v_mfma_f32_16x16x32_bf16 v[96:99], v[184:187], v[200:203], v[96:99]
	v_mfma_f32_16x16x32_bf16 v[84:87], v[176:179], v[208:211], v[84:87]
	v_mfma_f32_16x16x32_bf16 v[80:83], v[184:187], v[208:211], v[80:83]
	v_mfma_f32_16x16x32_bf16 v[68:71], v[176:179], v[216:219], v[68:71]
	v_mfma_f32_16x16x32_bf16 v[64:67], v[184:187], v[216:219], v[64:67]
	s_setprio 0
	s_barrier
	s_add_i32 s34, s90, s62
	v_lshl_add_u64 v[220:221], v[220:221], 0, s[26:27]
	s_mov_b32 m0, s34
	ds_read_b128 v[188:191], v162 offset:49152
	ds_read_b128 v[192:195], v162 offset:50176
	ds_read_b128 v[196:199], v162 offset:51200
	ds_read_b128 v[200:203], v162 offset:52224
	ds_read_b128 v[204:207], v162 offset:53248
	ds_read_b128 v[208:211], v162 offset:54272
	ds_read_b128 v[212:215], v162 offset:55296
	ds_read_b128 v[216:219], v162 offset:56320
	global_load_lds_dwordx4 v[220:221], off
	s_add_i32 m0, s34, 0x2000
	s_add_u32 s34, s54, 0x40080
	v_lshl_add_u64 v[220:221], v[222:223], 0, s[26:27]
	s_addc_u32 s35, s55, 0
	s_add_i32 s54, s95, s62
	global_load_lds_dwordx4 v[220:221], off
	v_lshl_add_u64 v[220:221], s[34:35], 0, v[134:135]
	s_mov_b32 m0, s54
	s_nop 0
	global_load_lds_dwordx4 v[220:221], off
	v_lshl_add_u64 v[220:221], s[34:35], 0, v[138:139]
	s_add_i32 m0, s54, 0x2000
	s_nop 0
	global_load_lds_dwordx4 v[220:221], off
	v_lshl_add_u64 v[220:221], v[224:225], 0, s[26:27]
	s_mov_b32 m0, s83
	s_nop 0
	global_load_lds_dwordx4 v[220:221], off
	v_lshl_add_u64 v[220:221], v[226:227], 0, s[26:27]
	s_mov_b32 m0, s84
	s_nop 0
	global_load_lds_dwordx4 v[220:221], off
	s_waitcnt vmcnt(8)
	s_waitcnt lgkmcnt(0)
	s_barrier
	s_setprio 1
	s_waitcnt lgkmcnt(0)
	v_mfma_f32_16x16x32_bf16 v[60:63], v[148:151], v[188:191], v[60:63]
	v_mfma_f32_16x16x32_bf16 v[56:59], v[164:167], v[188:191], v[56:59]
	v_mfma_f32_16x16x32_bf16 v[44:47], v[148:151], v[196:199], v[44:47]
	v_mfma_f32_16x16x32_bf16 v[40:43], v[164:167], v[196:199], v[40:43]
	v_mfma_f32_16x16x32_bf16 v[28:31], v[148:151], v[204:207], v[28:31]
	v_mfma_f32_16x16x32_bf16 v[24:27], v[164:167], v[204:207], v[24:27]
	v_mfma_f32_16x16x32_bf16 v[12:15], v[148:151], v[212:215], v[12:15]
	v_mfma_f32_16x16x32_bf16 v[8:11], v[164:167], v[212:215], v[8:11]
	v_mfma_f32_16x16x32_bf16 v[60:63], v[152:155], v[192:195], v[60:63]
	v_mfma_f32_16x16x32_bf16 v[56:59], v[168:171], v[192:195], v[56:59]
	v_mfma_f32_16x16x32_bf16 v[44:47], v[152:155], v[200:203], v[44:47]
	v_mfma_f32_16x16x32_bf16 v[40:43], v[168:171], v[200:203], v[40:43]
	v_mfma_f32_16x16x32_bf16 v[28:31], v[152:155], v[208:211], v[28:31]
	v_mfma_f32_16x16x32_bf16 v[24:27], v[168:171], v[208:211], v[24:27]
	v_mfma_f32_16x16x32_bf16 v[12:15], v[152:155], v[216:219], v[12:15]
	v_mfma_f32_16x16x32_bf16 v[8:11], v[168:171], v[216:219], v[8:11]
	s_setprio 0
	s_setprio 1
	v_mfma_f32_16x16x32_bf16 v[52:55], v[172:175], v[188:191], v[52:55]
	v_mfma_f32_16x16x32_bf16 v[48:51], v[180:183], v[188:191], v[48:51]
	v_mfma_f32_16x16x32_bf16 v[36:39], v[172:175], v[196:199], v[36:39]
	v_mfma_f32_16x16x32_bf16 v[32:35], v[180:183], v[196:199], v[32:35]
	v_mfma_f32_16x16x32_bf16 v[20:23], v[172:175], v[204:207], v[20:23]
	v_mfma_f32_16x16x32_bf16 v[16:19], v[180:183], v[204:207], v[16:19]
	v_mfma_f32_16x16x32_bf16 v[4:7], v[172:175], v[212:215], v[4:7]
	v_mfma_f32_16x16x32_bf16 v[0:3], v[180:183], v[212:215], v[0:3]
	v_mfma_f32_16x16x32_bf16 v[52:55], v[176:179], v[192:195], v[52:55]
	v_mfma_f32_16x16x32_bf16 v[48:51], v[184:187], v[192:195], v[48:51]
	v_mfma_f32_16x16x32_bf16 v[36:39], v[176:179], v[200:203], v[36:39]
	v_mfma_f32_16x16x32_bf16 v[32:35], v[184:187], v[200:203], v[32:35]
	v_mfma_f32_16x16x32_bf16 v[20:23], v[176:179], v[208:211], v[20:23]
	v_mfma_f32_16x16x32_bf16 v[16:19], v[184:187], v[208:211], v[16:19]
	v_mfma_f32_16x16x32_bf16 v[4:7], v[176:179], v[216:219], v[4:7]
	v_mfma_f32_16x16x32_bf16 v[0:3], v[184:187], v[216:219], v[0:3]
	s_setprio 0
	s_barrier
	s_add_i32 s77, s77, 2
	s_add_u32 s52, s52, 0x100
	s_addc_u32 s53, s53, 0
	s_add_u32 s41, s41, 0x100
	s_addc_u32 s43, s43, 0

.LBB0_968:
	s_ashr_i32 s29, s28, 31
	s_lshl_b64 s[12:13], s[28:29], 19
	s_add_u32 s30, s20, s12
	s_addc_u32 s31, s21, s13
	s_and_b64 s[12:13], s[6:7], exec
	s_cselect_b32 s12, s31, s41
	s_cselect_b32 s13, s30, s40
	s_ashr_i32 s27, s26, 31
	s_lshl_b64 s[34:35], s[26:27], 19
	s_add_u32 s36, s3, s34
	s_addc_u32 s37, s50, s35
	s_and_b64 s[34:35], s[6:7], exec
	s_cselect_b32 s27, s37, s43
	s_cselect_b32 s29, s36, s42
	s_add_u32 s40, s40, 0x40080
	s_addc_u32 s41, s41, 0
	s_add_u32 s39, s42, 0x100
	s_addc_u32 s67, s43, 0
	s_mov_b32 s77, -2
	s_waitcnt lgkmcnt(0)
	s_cmp_lg_u32 s66, 1
	s_cselect_b32 s100, s99, 0
	s_cmp_lg_u32 s100, 0
	s_cbranch_scc0 .Lmy_nobar2_9
	s_barrier
.Lmy_nobar2_9:
	ds_read_b128 v[148:151], v154
	ds_read_b128 v[160:163], v154 offset:1024
	ds_read_b128 v[164:167], v154 offset:2048
	ds_read_b128 v[168:171], v154 offset:3072
	ds_read_b128 v[172:175], v155
	ds_read_b128 v[176:179], v155 offset:1024
	ds_read_b128 v[180:183], v155 offset:2048
	ds_read_b128 v[184:187], v155 offset:3072
	s_add_u32 s34, s40, 0xfffc0080
	s_addc_u32 s35, s41, -1
	s_cmp_eq_u32 s77, 12
	s_cselect_b32 s49, s12, s35
	s_cselect_b32 s48, s13, s34
	s_cselect_b32 s43, s27, s67
	s_cselect_b32 s42, s29, s39
	v_lshl_add_u64 v[220:221], s[40:41], 0, v[140:141]
	s_add_i32 m0, s52, 0xc000
	ds_read_b128 v[188:191], v157
	ds_read_b128 v[192:195], v157 offset:1024
	ds_read_b128 v[196:199], v157 offset:2048
	ds_read_b128 v[200:203], v157 offset:3072
	ds_read_b128 v[204:207], v157 offset:4096
	ds_read_b128 v[208:211], v157 offset:5120
	ds_read_b128 v[212:215], v157 offset:6144
	ds_read_b128 v[216:219], v157 offset:7168
	global_load_lds_dwordx4 v[220:221], off
	v_lshl_add_u64 v[220:221], s[40:41], 0, v[142:143]
	s_add_i32 m0, s52, 0xe000
	s_nop 0
	global_load_lds_dwordx4 v[220:221], off
	s_waitcnt vmcnt(8)
	s_waitcnt lgkmcnt(0)
	s_barrier
	s_setprio 1
	s_waitcnt lgkmcnt(0)
	v_mfma_f32_16x16x32_bf16 v[124:127], v[148:151], v[188:191], 0
	v_mfma_f32_16x16x32_bf16 v[120:123], v[164:167], v[188:191], 0
	v_mfma_f32_16x16x32_bf16 v[108:111], v[148:151], v[196:199], 0
	v_mfma_f32_16x16x32_bf16 v[104:107], v[164:167], v[196:199], 0
	v_mfma_f32_16x16x32_bf16 v[92:95], v[148:151], v[204:207], 0
	v_mfma_f32_16x16x32_bf16 v[88:91], v[164:167], v[204:207], 0
	v_mfma_f32_16x16x32_bf16 v[76:79], v[148:151], v[212:215], 0
	v_mfma_f32_16x16x32_bf16 v[72:75], v[164:167], v[212:215], 0
	v_mfma_f32_16x16x32_bf16 v[124:127], v[160:163], v[192:195], v[124:127]
	v_mfma_f32_16x16x32_bf16 v[120:123], v[168:171], v[192:195], v[120:123]
	v_mfma_f32_16x16x32_bf16 v[108:111], v[160:163], v[200:203], v[108:111]
	v_mfma_f32_16x16x32_bf16 v[104:107], v[168:171], v[200:203], v[104:107]
	v_mfma_f32_16x16x32_bf16 v[92:95], v[160:163], v[208:211], v[92:95]
	v_mfma_f32_16x16x32_bf16 v[88:91], v[168:171], v[208:211], v[88:91]
	v_mfma_f32_16x16x32_bf16 v[76:79], v[160:163], v[216:219], v[76:79]
	v_mfma_f32_16x16x32_bf16 v[72:75], v[168:171], v[216:219], v[72:75]
	s_setprio 0
	s_setprio 1
	v_mfma_f32_16x16x32_bf16 v[116:119], v[172:175], v[188:191], 0
	v_mfma_f32_16x16x32_bf16 v[112:115], v[180:183], v[188:191], 0
	v_mfma_f32_16x16x32_bf16 v[100:103], v[172:175], v[196:199], 0
	v_mfma_f32_16x16x32_bf16 v[96:99], v[180:183], v[196:199], 0
	v_mfma_f32_16x16x32_bf16 v[84:87], v[172:175], v[204:207], 0
	v_mfma_f32_16x16x32_bf16 v[80:83], v[180:183], v[204:207], 0
	v_mfma_f32_16x16x32_bf16 v[68:71], v[172:175], v[212:215], 0
	v_mfma_f32_16x16x32_bf16 v[64:67], v[180:183], v[212:215], 0
	v_mfma_f32_16x16x32_bf16 v[116:119], v[176:179], v[192:195], v[116:119]
	v_mfma_f32_16x16x32_bf16 v[112:115], v[184:187], v[192:195], v[112:115]
	v_mfma_f32_16x16x32_bf16 v[100:103], v[176:179], v[200:203], v[100:103]
	v_mfma_f32_16x16x32_bf16 v[96:99], v[184:187], v[200:203], v[96:99]
	v_mfma_f32_16x16x32_bf16 v[84:87], v[176:179], v[208:211], v[84:87]
	v_mfma_f32_16x16x32_bf16 v[80:83], v[184:187], v[208:211], v[80:83]
	v_mfma_f32_16x16x32_bf16 v[68:71], v[176:179], v[216:219], v[68:71]
	v_mfma_f32_16x16x32_bf16 v[64:67], v[184:187], v[216:219], v[64:67]
	s_setprio 0
	s_barrier
	s_add_i32 s34, s64, s51
	v_lshl_add_u64 v[220:221], s[42:43], 0, v[134:135]
	s_mov_b32 m0, s34
	ds_read_b128 v[188:191], v157 offset:16384
	ds_read_b128 v[192:195], v157 offset:17408
	ds_read_b128 v[196:199], v157 offset:18432
	ds_read_b128 v[200:203], v157 offset:19456
	ds_read_b128 v[204:207], v157 offset:20480
	ds_read_b128 v[208:211], v157 offset:21504
	ds_read_b128 v[212:215], v157 offset:22528
	ds_read_b128 v[216:219], v157 offset:23552
	global_load_lds_dwordx4 v[220:221], off
	s_add_i32 m0, s34, 0x2000
	s_add_u32 s34, s42, 0x40000
	v_lshl_add_u64 v[222:223], s[42:43], 0, v[138:139]
	s_addc_u32 s35, s43, 0
	s_add_i32 s79, s65, s51
	global_load_lds_dwordx4 v[222:223], off
	v_lshl_add_u64 v[224:225], s[34:35], 0, v[134:135]
	s_mov_b32 m0, s79
	v_lshl_add_u64 v[226:227], s[48:49], 0, v[136:137]
	global_load_lds_dwordx4 v[224:225], off
	v_lshl_add_u64 v[224:225], s[34:35], 0, v[138:139]
	s_add_i32 m0, s79, 0x2000
	s_nop 0
	global_load_lds_dwordx4 v[224:225], off
	v_lshl_add_u64 v[224:225], s[48:49], 0, v[132:133]
	s_mov_b32 m0, s52
	s_nop 0
	global_load_lds_dwordx4 v[224:225], off
	s_mov_b32 m0, s53
	s_nop 0
	global_load_lds_dwordx4 v[226:227], off
	s_waitcnt vmcnt(8)
	s_waitcnt lgkmcnt(0)
	s_barrier
	s_setprio 1
	s_waitcnt lgkmcnt(0)
	v_mfma_f32_16x16x32_bf16 v[60:63], v[148:151], v[188:191], 0
	v_mfma_f32_16x16x32_bf16 v[56:59], v[164:167], v[188:191], 0
	v_mfma_f32_16x16x32_bf16 v[44:47], v[148:151], v[196:199], 0
	v_mfma_f32_16x16x32_bf16 v[40:43], v[164:167], v[196:199], 0
	v_mfma_f32_16x16x32_bf16 v[28:31], v[148:151], v[204:207], 0
	v_mfma_f32_16x16x32_bf16 v[24:27], v[164:167], v[204:207], 0
	v_mfma_f32_16x16x32_bf16 v[12:15], v[148:151], v[212:215], 0
	v_mfma_f32_16x16x32_bf16 v[8:11], v[164:167], v[212:215], 0
	v_mfma_f32_16x16x32_bf16 v[60:63], v[160:163], v[192:195], v[60:63]
	v_mfma_f32_16x16x32_bf16 v[56:59], v[168:171], v[192:195], v[56:59]
	v_mfma_f32_16x16x32_bf16 v[44:47], v[160:163], v[200:203], v[44:47]
	v_mfma_f32_16x16x32_bf16 v[40:43], v[168:171], v[200:203], v[40:43]
	v_mfma_f32_16x16x32_bf16 v[28:31], v[160:163], v[208:211], v[28:31]
	v_mfma_f32_16x16x32_bf16 v[24:27], v[168:171], v[208:211], v[24:27]
	v_mfma_f32_16x16x32_bf16 v[12:15], v[160:163], v[216:219], v[12:15]
	v_mfma_f32_16x16x32_bf16 v[8:11], v[168:171], v[216:219], v[8:11]
	s_setprio 0
	s_setprio 1
	v_mfma_f32_16x16x32_bf16 v[52:55], v[172:175], v[188:191], 0
	v_mfma_f32_16x16x32_bf16 v[48:51], v[180:183], v[188:191], 0
	v_mfma_f32_16x16x32_bf16 v[36:39], v[172:175], v[196:199], 0
	v_mfma_f32_16x16x32_bf16 v[32:35], v[180:183], v[196:199], 0
	v_mfma_f32_16x16x32_bf16 v[20:23], v[172:175], v[204:207], 0
	v_mfma_f32_16x16x32_bf16 v[16:19], v[180:183], v[204:207], 0
	v_mfma_f32_16x16x32_bf16 v[4:7], v[172:175], v[212:215], 0
	v_mfma_f32_16x16x32_bf16 v[0:3], v[180:183], v[212:215], 0
	v_mfma_f32_16x16x32_bf16 v[52:55], v[176:179], v[192:195], v[52:55]
	v_mfma_f32_16x16x32_bf16 v[48:51], v[184:187], v[192:195], v[48:51]
	v_mfma_f32_16x16x32_bf16 v[36:39], v[176:179], v[200:203], v[36:39]
	v_mfma_f32_16x16x32_bf16 v[32:35], v[184:187], v[200:203], v[32:35]
	v_mfma_f32_16x16x32_bf16 v[20:23], v[176:179], v[208:211], v[20:23]
	v_mfma_f32_16x16x32_bf16 v[16:19], v[184:187], v[208:211], v[16:19]
	v_mfma_f32_16x16x32_bf16 v[4:7], v[176:179], v[216:219], v[4:7]
	v_mfma_f32_16x16x32_bf16 v[0:3], v[184:187], v[216:219], v[0:3]
	s_setprio 0
	s_barrier
	s_add_i32 s79, 0, 0x18000
	v_add_u32_e32 v159, s79, v152
	s_add_i32 s81, 0, 0x1c000
	ds_read_b128 v[148:151], v159
	ds_read_b128 v[160:163], v159 offset:1024
	ds_read_b128 v[164:167], v159 offset:2048
	ds_read_b128 v[168:171], v159 offset:3072
	v_add_u32_e32 v159, s81, v152
	ds_read_b128 v[172:175], v159
	ds_read_b128 v[176:179], v159 offset:1024
	ds_read_b128 v[180:183], v159 offset:2048
	ds_read_b128 v[184:187], v159 offset:3072
	s_add_u32 s34, s48, 0x40000
	s_addc_u32 s35, s49, 0
	s_mov_b32 m0, s54
	v_lshl_add_u64 v[228:229], s[34:35], 0, v[132:133]
	ds_read_b128 v[188:191], v157 offset:32768
	ds_read_b128 v[192:195], v157 offset:33792
	ds_read_b128 v[196:199], v157 offset:34816
	ds_read_b128 v[200:203], v157 offset:35840
	ds_read_b128 v[204:207], v157 offset:36864
	ds_read_b128 v[208:211], v157 offset:37888
	ds_read_b128 v[212:215], v157 offset:38912
	ds_read_b128 v[216:219], v157 offset:39936
	global_load_lds_dwordx4 v[228:229], off
	v_lshl_add_u64 v[228:229], s[34:35], 0, v[136:137]
	s_mov_b32 m0, s55
	s_nop 0
	global_load_lds_dwordx4 v[228:229], off
	s_waitcnt vmcnt(8)
	s_waitcnt lgkmcnt(0)
	s_barrier
	s_setprio 1
	s_waitcnt lgkmcnt(0)
	v_mfma_f32_16x16x32_bf16 v[124:127], v[148:151], v[188:191], v[124:127]
	v_mfma_f32_16x16x32_bf16 v[120:123], v[164:167], v[188:191], v[120:123]
	v_mfma_f32_16x16x32_bf16 v[108:111], v[148:151], v[196:199], v[108:111]
	v_mfma_f32_16x16x32_bf16 v[104:107], v[164:167], v[196:199], v[104:107]
	v_mfma_f32_16x16x32_bf16 v[92:95], v[148:151], v[204:207], v[92:95]
	v_mfma_f32_16x16x32_bf16 v[88:91], v[164:167], v[204:207], v[88:91]
	v_mfma_f32_16x16x32_bf16 v[76:79], v[148:151], v[212:215], v[76:79]
	v_mfma_f32_16x16x32_bf16 v[72:75], v[164:167], v[212:215], v[72:75]
	v_mfma_f32_16x16x32_bf16 v[124:127], v[160:163], v[192:195], v[124:127]
	v_mfma_f32_16x16x32_bf16 v[120:123], v[168:171], v[192:195], v[120:123]
	v_mfma_f32_16x16x32_bf16 v[108:111], v[160:163], v[200:203], v[108:111]
	v_mfma_f32_16x16x32_bf16 v[104:107], v[168:171], v[200:203], v[104:107]
	v_mfma_f32_16x16x32_bf16 v[92:95], v[160:163], v[208:211], v[92:95]
	v_mfma_f32_16x16x32_bf16 v[88:91], v[168:171], v[208:211], v[88:91]
	v_mfma_f32_16x16x32_bf16 v[76:79], v[160:163], v[216:219], v[76:79]
	v_mfma_f32_16x16x32_bf16 v[72:75], v[168:171], v[216:219], v[72:75]
	s_setprio 0
	s_setprio 1
	v_mfma_f32_16x16x32_bf16 v[116:119], v[172:175], v[188:191], v[116:119]
	v_mfma_f32_16x16x32_bf16 v[112:115], v[180:183], v[188:191], v[112:115]
	v_mfma_f32_16x16x32_bf16 v[100:103], v[172:175], v[196:199], v[100:103]
	v_mfma_f32_16x16x32_bf16 v[96:99], v[180:183], v[196:199], v[96:99]
	v_mfma_f32_16x16x32_bf16 v[84:87], v[172:175], v[204:207], v[84:87]
	v_mfma_f32_16x16x32_bf16 v[80:83], v[180:183], v[204:207], v[80:83]
	v_mfma_f32_16x16x32_bf16 v[68:71], v[172:175], v[212:215], v[68:71]
	v_mfma_f32_16x16x32_bf16 v[64:67], v[180:183], v[212:215], v[64:67]
	v_mfma_f32_16x16x32_bf16 v[116:119], v[176:179], v[192:195], v[116:119]
	v_mfma_f32_16x16x32_bf16 v[112:115], v[184:187], v[192:195], v[112:115]
	v_mfma_f32_16x16x32_bf16 v[100:103], v[176:179], v[200:203], v[100:103]
	v_mfma_f32_16x16x32_bf16 v[96:99], v[184:187], v[200:203], v[96:99]
	v_mfma_f32_16x16x32_bf16 v[84:87], v[176:179], v[208:211], v[84:87]
	v_mfma_f32_16x16x32_bf16 v[80:83], v[184:187], v[208:211], v[80:83]
	v_mfma_f32_16x16x32_bf16 v[68:71], v[176:179], v[216:219], v[68:71]
	v_mfma_f32_16x16x32_bf16 v[64:67], v[184:187], v[216:219], v[64:67]
	s_setprio 0
	s_barrier
	s_add_i32 s34, s79, s51
	v_lshl_add_u64 v[220:221], v[220:221], 0, s[10:11]
	s_mov_b32 m0, s34
	ds_read_b128 v[188:191], v157 offset:49152
	ds_read_b128 v[192:195], v157 offset:50176
	ds_read_b128 v[196:199], v157 offset:51200
	ds_read_b128 v[200:203], v157 offset:52224
	ds_read_b128 v[204:207], v157 offset:53248
	ds_read_b128 v[208:211], v157 offset:54272
	ds_read_b128 v[212:215], v157 offset:55296
	ds_read_b128 v[216:219], v157 offset:56320
	global_load_lds_dwordx4 v[220:221], off
	s_add_i32 m0, s34, 0x2000
	s_add_u32 s34, s42, 0x40080
	v_lshl_add_u64 v[220:221], v[222:223], 0, s[10:11]
	s_addc_u32 s35, s43, 0
	s_add_i32 s42, s81, s51
	global_load_lds_dwordx4 v[220:221], off
	v_lshl_add_u64 v[220:221], s[34:35], 0, v[134:135]
	s_mov_b32 m0, s42
	s_nop 0
	global_load_lds_dwordx4 v[220:221], off
	v_lshl_add_u64 v[220:221], s[34:35], 0, v[138:139]
	s_add_i32 m0, s42, 0x2000
	s_nop 0
	global_load_lds_dwordx4 v[220:221], off
	v_lshl_add_u64 v[220:221], v[224:225], 0, s[10:11]
	s_mov_b32 m0, s57
	s_nop 0
	global_load_lds_dwordx4 v[220:221], off
	v_lshl_add_u64 v[220:221], v[226:227], 0, s[10:11]
	s_mov_b32 m0, s58
	s_nop 0
	global_load_lds_dwordx4 v[220:221], off
	s_waitcnt vmcnt(8)
	s_waitcnt lgkmcnt(0)
	s_barrier
	s_setprio 1
	s_waitcnt lgkmcnt(0)
	v_mfma_f32_16x16x32_bf16 v[60:63], v[148:151], v[188:191], v[60:63]
	v_mfma_f32_16x16x32_bf16 v[56:59], v[164:167], v[188:191], v[56:59]
	v_mfma_f32_16x16x32_bf16 v[44:47], v[148:151], v[196:199], v[44:47]
	v_mfma_f32_16x16x32_bf16 v[40:43], v[164:167], v[196:199], v[40:43]
	v_mfma_f32_16x16x32_bf16 v[28:31], v[148:151], v[204:207], v[28:31]
	v_mfma_f32_16x16x32_bf16 v[24:27], v[164:167], v[204:207], v[24:27]
	v_mfma_f32_16x16x32_bf16 v[12:15], v[148:151], v[212:215], v[12:15]
	v_mfma_f32_16x16x32_bf16 v[8:11], v[164:167], v[212:215], v[8:11]
	v_mfma_f32_16x16x32_bf16 v[60:63], v[160:163], v[192:195], v[60:63]
	v_mfma_f32_16x16x32_bf16 v[56:59], v[168:171], v[192:195], v[56:59]
	v_mfma_f32_16x16x32_bf16 v[44:47], v[160:163], v[200:203], v[44:47]
	v_mfma_f32_16x16x32_bf16 v[40:43], v[168:171], v[200:203], v[40:43]
	v_mfma_f32_16x16x32_bf16 v[28:31], v[160:163], v[208:211], v[28:31]
	v_mfma_f32_16x16x32_bf16 v[24:27], v[168:171], v[208:211], v[24:27]
	v_mfma_f32_16x16x32_bf16 v[12:15], v[160:163], v[216:219], v[12:15]
	v_mfma_f32_16x16x32_bf16 v[8:11], v[168:171], v[216:219], v[8:11]
	s_setprio 0
	s_setprio 1
	v_mfma_f32_16x16x32_bf16 v[52:55], v[172:175], v[188:191], v[52:55]
	v_mfma_f32_16x16x32_bf16 v[48:51], v[180:183], v[188:191], v[48:51]
	v_mfma_f32_16x16x32_bf16 v[36:39], v[172:175], v[196:199], v[36:39]
	v_mfma_f32_16x16x32_bf16 v[32:35], v[180:183], v[196:199], v[32:35]
	v_mfma_f32_16x16x32_bf16 v[20:23], v[172:175], v[204:207], v[20:23]
	v_mfma_f32_16x16x32_bf16 v[16:19], v[180:183], v[204:207], v[16:19]
	v_mfma_f32_16x16x32_bf16 v[4:7], v[172:175], v[212:215], v[4:7]
	v_mfma_f32_16x16x32_bf16 v[0:3], v[180:183], v[212:215], v[0:3]
	v_mfma_f32_16x16x32_bf16 v[52:55], v[176:179], v[192:195], v[52:55]
	v_mfma_f32_16x16x32_bf16 v[48:51], v[184:187], v[192:195], v[48:51]
	v_mfma_f32_16x16x32_bf16 v[36:39], v[176:179], v[200:203], v[36:39]
	v_mfma_f32_16x16x32_bf16 v[32:35], v[184:187], v[200:203], v[32:35]
	v_mfma_f32_16x16x32_bf16 v[20:23], v[176:179], v[208:211], v[20:23]
	v_mfma_f32_16x16x32_bf16 v[16:19], v[184:187], v[208:211], v[16:19]
	v_mfma_f32_16x16x32_bf16 v[4:7], v[176:179], v[216:219], v[4:7]
	v_mfma_f32_16x16x32_bf16 v[0:3], v[184:187], v[216:219], v[0:3]
	s_setprio 0
	s_barrier
	s_add_i32 s77, s77, 2
	s_add_u32 s40, s40, 0x100
	s_addc_u32 s41, s41, 0
	s_add_u32 s39, s39, 0x100
	s_addc_u32 s67, s67, 0

.LBB0_1058:
	s_ashr_i32 s23, s22, 31
	s_lshl_b64 s[26:27], s[22:23], 19
	s_add_u32 s26, s14, s26
	s_addc_u32 s27, s15, s27
	s_and_b64 s[28:29], s[4:5], exec
	s_cselect_b32 s23, s27, s37
	s_cselect_b32 s64, s26, s36
	s_ashr_i32 s11, s10, 31
	s_lshl_b64 s[28:29], s[10:11], 19
	s_add_u32 s28, s49, s28
	s_addc_u32 s29, s50, s29
	s_and_b64 s[34:35], s[4:5], exec
	s_cselect_b32 s11, s29, s39
	s_cselect_b32 s65, s28, s38
	s_add_u32 s36, s36, 0x40080
	s_addc_u32 s37, s37, 0
	s_add_u32 s66, s38, 0x100
	s_addc_u32 s67, s39, 0
	s_mov_b32 s77, -2
	s_cmp_lg_u32 s62, 1
	s_cselect_b32 s100, s99, 0
	s_cmp_lg_u32 s100, 0
	s_cbranch_scc0 .Lmy_nobar2_10
	s_barrier
.Lmy_nobar2_10:
	ds_read_b128 v[148:151], v155
	ds_read_b128 v[160:163], v155 offset:1024
	ds_read_b128 v[164:167], v155 offset:2048
	ds_read_b128 v[168:171], v155 offset:3072
	ds_read_b128 v[172:175], v157
	ds_read_b128 v[176:179], v157 offset:1024
	ds_read_b128 v[180:183], v157 offset:2048
	ds_read_b128 v[184:187], v157 offset:3072
	s_add_u32 s34, s36, 0xfffc0080
	s_addc_u32 s35, s37, -1
	s_cmp_eq_u32 s77, 12
	s_cselect_b32 s41, s23, s35
	s_cselect_b32 s40, s64, s34
	s_cselect_b32 s39, s11, s67
	s_cselect_b32 s38, s65, s66
	v_lshl_add_u64 v[220:221], s[36:37], 0, v[140:141]
	s_add_i32 m0, s31, 0xc000
	ds_read_b128 v[188:191], v158
	ds_read_b128 v[192:195], v158 offset:1024
	ds_read_b128 v[196:199], v158 offset:2048
	ds_read_b128 v[200:203], v158 offset:3072
	ds_read_b128 v[204:207], v158 offset:4096
	ds_read_b128 v[208:211], v158 offset:5120
	ds_read_b128 v[212:215], v158 offset:6144
	ds_read_b128 v[216:219], v158 offset:7168
	global_load_lds_dwordx4 v[220:221], off
	v_lshl_add_u64 v[220:221], s[36:37], 0, v[142:143]
	s_add_i32 m0, s31, 0xe000
	s_nop 0
	global_load_lds_dwordx4 v[220:221], off
	s_waitcnt vmcnt(8)
	s_waitcnt lgkmcnt(0)
	s_barrier
	s_setprio 1
	s_waitcnt lgkmcnt(0)
	v_mfma_f32_16x16x32_bf16 v[124:127], v[148:151], v[188:191], 0
	v_mfma_f32_16x16x32_bf16 v[120:123], v[164:167], v[188:191], 0
	v_mfma_f32_16x16x32_bf16 v[108:111], v[148:151], v[196:199], 0
	v_mfma_f32_16x16x32_bf16 v[104:107], v[164:167], v[196:199], 0
	v_mfma_f32_16x16x32_bf16 v[92:95], v[148:151], v[204:207], 0
	v_mfma_f32_16x16x32_bf16 v[88:91], v[164:167], v[204:207], 0
	v_mfma_f32_16x16x32_bf16 v[76:79], v[148:151], v[212:215], 0
	v_mfma_f32_16x16x32_bf16 v[72:75], v[164:167], v[212:215], 0
	v_mfma_f32_16x16x32_bf16 v[124:127], v[160:163], v[192:195], v[124:127]
	v_mfma_f32_16x16x32_bf16 v[120:123], v[168:171], v[192:195], v[120:123]
	v_mfma_f32_16x16x32_bf16 v[108:111], v[160:163], v[200:203], v[108:111]
	v_mfma_f32_16x16x32_bf16 v[104:107], v[168:171], v[200:203], v[104:107]
	v_mfma_f32_16x16x32_bf16 v[92:95], v[160:163], v[208:211], v[92:95]
	v_mfma_f32_16x16x32_bf16 v[88:91], v[168:171], v[208:211], v[88:91]
	v_mfma_f32_16x16x32_bf16 v[76:79], v[160:163], v[216:219], v[76:79]
	v_mfma_f32_16x16x32_bf16 v[72:75], v[168:171], v[216:219], v[72:75]
	s_setprio 0
	s_setprio 1
	v_mfma_f32_16x16x32_bf16 v[116:119], v[172:175], v[188:191], 0
	v_mfma_f32_16x16x32_bf16 v[112:115], v[180:183], v[188:191], 0
	v_mfma_f32_16x16x32_bf16 v[100:103], v[172:175], v[196:199], 0
	v_mfma_f32_16x16x32_bf16 v[96:99], v[180:183], v[196:199], 0
	v_mfma_f32_16x16x32_bf16 v[84:87], v[172:175], v[204:207], 0
	v_mfma_f32_16x16x32_bf16 v[80:83], v[180:183], v[204:207], 0
	v_mfma_f32_16x16x32_bf16 v[68:71], v[172:175], v[212:215], 0
	v_mfma_f32_16x16x32_bf16 v[64:67], v[180:183], v[212:215], 0
	v_mfma_f32_16x16x32_bf16 v[116:119], v[176:179], v[192:195], v[116:119]
	v_mfma_f32_16x16x32_bf16 v[112:115], v[184:187], v[192:195], v[112:115]
	v_mfma_f32_16x16x32_bf16 v[100:103], v[176:179], v[200:203], v[100:103]
	v_mfma_f32_16x16x32_bf16 v[96:99], v[184:187], v[200:203], v[96:99]
	v_mfma_f32_16x16x32_bf16 v[84:87], v[176:179], v[208:211], v[84:87]
	v_mfma_f32_16x16x32_bf16 v[80:83], v[184:187], v[208:211], v[80:83]
	v_mfma_f32_16x16x32_bf16 v[68:71], v[176:179], v[216:219], v[68:71]
	v_mfma_f32_16x16x32_bf16 v[64:67], v[184:187], v[216:219], v[64:67]
	s_setprio 0
	s_barrier
	s_add_i32 s34, s57, s48
	v_lshl_add_u64 v[220:221], s[38:39], 0, v[136:137]
	s_mov_b32 m0, s34
	ds_read_b128 v[188:191], v158 offset:16384
	ds_read_b128 v[192:195], v158 offset:17408
	ds_read_b128 v[196:199], v158 offset:18432
	ds_read_b128 v[200:203], v158 offset:19456
	ds_read_b128 v[204:207], v158 offset:20480
	ds_read_b128 v[208:211], v158 offset:21504
	ds_read_b128 v[212:215], v158 offset:22528
	ds_read_b128 v[216:219], v158 offset:23552
	global_load_lds_dwordx4 v[220:221], off
	s_add_i32 m0, s34, 0x2000
	s_add_u32 s34, s38, 0x40000
	v_lshl_add_u64 v[222:223], s[38:39], 0, v[132:133]
	s_addc_u32 s35, s39, 0
	s_add_i32 s79, s58, s48
	global_load_lds_dwordx4 v[222:223], off
	v_lshl_add_u64 v[224:225], s[34:35], 0, v[136:137]
	s_mov_b32 m0, s79
	v_lshl_add_u64 v[226:227], s[40:41], 0, v[134:135]
	global_load_lds_dwordx4 v[224:225], off
	v_lshl_add_u64 v[224:225], s[34:35], 0, v[132:133]
	s_add_i32 m0, s79, 0x2000
	s_nop 0
	global_load_lds_dwordx4 v[224:225], off
	v_lshl_add_u64 v[224:225], s[40:41], 0, v[138:139]
	s_mov_b32 m0, s31
	s_nop 0
	global_load_lds_dwordx4 v[224:225], off
	s_mov_b32 m0, s52
	s_nop 0
	global_load_lds_dwordx4 v[226:227], off
	s_waitcnt vmcnt(8)
	s_waitcnt lgkmcnt(0)
	s_barrier
	s_setprio 1
	s_waitcnt lgkmcnt(0)
	v_mfma_f32_16x16x32_bf16 v[60:63], v[148:151], v[188:191], 0
	v_mfma_f32_16x16x32_bf16 v[56:59], v[164:167], v[188:191], 0
	v_mfma_f32_16x16x32_bf16 v[44:47], v[148:151], v[196:199], 0
	v_mfma_f32_16x16x32_bf16 v[40:43], v[164:167], v[196:199], 0
	v_mfma_f32_16x16x32_bf16 v[28:31], v[148:151], v[204:207], 0
	v_mfma_f32_16x16x32_bf16 v[24:27], v[164:167], v[204:207], 0
	v_mfma_f32_16x16x32_bf16 v[12:15], v[148:151], v[212:215], 0
	v_mfma_f32_16x16x32_bf16 v[8:11], v[164:167], v[212:215], 0
	v_mfma_f32_16x16x32_bf16 v[60:63], v[160:163], v[192:195], v[60:63]
	v_mfma_f32_16x16x32_bf16 v[56:59], v[168:171], v[192:195], v[56:59]
	v_mfma_f32_16x16x32_bf16 v[44:47], v[160:163], v[200:203], v[44:47]
	v_mfma_f32_16x16x32_bf16 v[40:43], v[168:171], v[200:203], v[40:43]
	v_mfma_f32_16x16x32_bf16 v[28:31], v[160:163], v[208:211], v[28:31]
	v_mfma_f32_16x16x32_bf16 v[24:27], v[168:171], v[208:211], v[24:27]
	v_mfma_f32_16x16x32_bf16 v[12:15], v[160:163], v[216:219], v[12:15]
	v_mfma_f32_16x16x32_bf16 v[8:11], v[168:171], v[216:219], v[8:11]
	s_setprio 0
	s_setprio 1
	v_mfma_f32_16x16x32_bf16 v[52:55], v[172:175], v[188:191], 0
	v_mfma_f32_16x16x32_bf16 v[48:51], v[180:183], v[188:191], 0
	v_mfma_f32_16x16x32_bf16 v[36:39], v[172:175], v[196:199], 0
	v_mfma_f32_16x16x32_bf16 v[32:35], v[180:183], v[196:199], 0
	v_mfma_f32_16x16x32_bf16 v[20:23], v[172:175], v[204:207], 0
	v_mfma_f32_16x16x32_bf16 v[16:19], v[180:183], v[204:207], 0
	v_mfma_f32_16x16x32_bf16 v[4:7], v[172:175], v[212:215], 0
	v_mfma_f32_16x16x32_bf16 v[0:3], v[180:183], v[212:215], 0
	v_mfma_f32_16x16x32_bf16 v[52:55], v[176:179], v[192:195], v[52:55]
	v_mfma_f32_16x16x32_bf16 v[48:51], v[184:187], v[192:195], v[48:51]
	v_mfma_f32_16x16x32_bf16 v[36:39], v[176:179], v[200:203], v[36:39]
	v_mfma_f32_16x16x32_bf16 v[32:35], v[184:187], v[200:203], v[32:35]
	v_mfma_f32_16x16x32_bf16 v[20:23], v[176:179], v[208:211], v[20:23]
	v_mfma_f32_16x16x32_bf16 v[16:19], v[184:187], v[208:211], v[16:19]
	v_mfma_f32_16x16x32_bf16 v[4:7], v[176:179], v[216:219], v[4:7]
	v_mfma_f32_16x16x32_bf16 v[0:3], v[184:187], v[216:219], v[0:3]
	s_setprio 0
	s_barrier
	s_add_i32 s79, 0, 0x18000
	v_add_u32_e32 v159, s79, v152
	s_add_i32 s81, 0, 0x1c000
	ds_read_b128 v[148:151], v159
	ds_read_b128 v[160:163], v159 offset:1024
	ds_read_b128 v[164:167], v159 offset:2048
	ds_read_b128 v[168:171], v159 offset:3072
	v_add_u32_e32 v159, s81, v152
	ds_read_b128 v[172:175], v159
	ds_read_b128 v[176:179], v159 offset:1024
	ds_read_b128 v[180:183], v159 offset:2048
	ds_read_b128 v[184:187], v159 offset:3072
	s_add_u32 s34, s40, 0x40000
	s_addc_u32 s35, s41, 0
	s_mov_b32 m0, s53
	v_lshl_add_u64 v[228:229], s[34:35], 0, v[138:139]
	ds_read_b128 v[188:191], v158 offset:32768
	ds_read_b128 v[192:195], v158 offset:33792
	ds_read_b128 v[196:199], v158 offset:34816
	ds_read_b128 v[200:203], v158 offset:35840
	ds_read_b128 v[204:207], v158 offset:36864
	ds_read_b128 v[208:211], v158 offset:37888
	ds_read_b128 v[212:215], v158 offset:38912
	ds_read_b128 v[216:219], v158 offset:39936
	global_load_lds_dwordx4 v[228:229], off
	v_lshl_add_u64 v[228:229], s[34:35], 0, v[134:135]
	s_mov_b32 m0, s54
	s_nop 0
	global_load_lds_dwordx4 v[228:229], off
	s_waitcnt vmcnt(8)
	s_waitcnt lgkmcnt(0)
	s_barrier
	s_setprio 1
	s_waitcnt lgkmcnt(0)
	v_mfma_f32_16x16x32_bf16 v[124:127], v[148:151], v[188:191], v[124:127]
	v_mfma_f32_16x16x32_bf16 v[120:123], v[164:167], v[188:191], v[120:123]
	v_mfma_f32_16x16x32_bf16 v[108:111], v[148:151], v[196:199], v[108:111]
	v_mfma_f32_16x16x32_bf16 v[104:107], v[164:167], v[196:199], v[104:107]
	v_mfma_f32_16x16x32_bf16 v[92:95], v[148:151], v[204:207], v[92:95]
	v_mfma_f32_16x16x32_bf16 v[88:91], v[164:167], v[204:207], v[88:91]
	v_mfma_f32_16x16x32_bf16 v[76:79], v[148:151], v[212:215], v[76:79]
	v_mfma_f32_16x16x32_bf16 v[72:75], v[164:167], v[212:215], v[72:75]
	v_mfma_f32_16x16x32_bf16 v[124:127], v[160:163], v[192:195], v[124:127]
	v_mfma_f32_16x16x32_bf16 v[120:123], v[168:171], v[192:195], v[120:123]
	v_mfma_f32_16x16x32_bf16 v[108:111], v[160:163], v[200:203], v[108:111]
	v_mfma_f32_16x16x32_bf16 v[104:107], v[168:171], v[200:203], v[104:107]
	v_mfma_f32_16x16x32_bf16 v[92:95], v[160:163], v[208:211], v[92:95]
	v_mfma_f32_16x16x32_bf16 v[88:91], v[168:171], v[208:211], v[88:91]
	v_mfma_f32_16x16x32_bf16 v[76:79], v[160:163], v[216:219], v[76:79]
	v_mfma_f32_16x16x32_bf16 v[72:75], v[168:171], v[216:219], v[72:75]
	s_setprio 0
	s_setprio 1
	v_mfma_f32_16x16x32_bf16 v[116:119], v[172:175], v[188:191], v[116:119]
	v_mfma_f32_16x16x32_bf16 v[112:115], v[180:183], v[188:191], v[112:115]
	v_mfma_f32_16x16x32_bf16 v[100:103], v[172:175], v[196:199], v[100:103]
	v_mfma_f32_16x16x32_bf16 v[96:99], v[180:183], v[196:199], v[96:99]
	v_mfma_f32_16x16x32_bf16 v[84:87], v[172:175], v[204:207], v[84:87]
	v_mfma_f32_16x16x32_bf16 v[80:83], v[180:183], v[204:207], v[80:83]
	v_mfma_f32_16x16x32_bf16 v[68:71], v[172:175], v[212:215], v[68:71]
	v_mfma_f32_16x16x32_bf16 v[64:67], v[180:183], v[212:215], v[64:67]
	v_mfma_f32_16x16x32_bf16 v[116:119], v[176:179], v[192:195], v[116:119]
	v_mfma_f32_16x16x32_bf16 v[112:115], v[184:187], v[192:195], v[112:115]
	v_mfma_f32_16x16x32_bf16 v[100:103], v[176:179], v[200:203], v[100:103]
	v_mfma_f32_16x16x32_bf16 v[96:99], v[184:187], v[200:203], v[96:99]
	v_mfma_f32_16x16x32_bf16 v[84:87], v[176:179], v[208:211], v[84:87]
	v_mfma_f32_16x16x32_bf16 v[80:83], v[184:187], v[208:211], v[80:83]
	v_mfma_f32_16x16x32_bf16 v[68:71], v[176:179], v[216:219], v[68:71]
	v_mfma_f32_16x16x32_bf16 v[64:67], v[184:187], v[216:219], v[64:67]
	s_setprio 0
	s_barrier
	s_add_i32 s34, s79, s48
	v_lshl_add_u64 v[220:221], v[220:221], 0, s[6:7]
	s_mov_b32 m0, s34
	ds_read_b128 v[188:191], v158 offset:49152
	ds_read_b128 v[192:195], v158 offset:50176
	ds_read_b128 v[196:199], v158 offset:51200
	ds_read_b128 v[200:203], v158 offset:52224
	ds_read_b128 v[204:207], v158 offset:53248
	ds_read_b128 v[208:211], v158 offset:54272
	ds_read_b128 v[212:215], v158 offset:55296
	ds_read_b128 v[216:219], v158 offset:56320
	global_load_lds_dwordx4 v[220:221], off
	s_add_i32 m0, s34, 0x2000
	s_add_u32 s34, s38, 0x40080
	v_lshl_add_u64 v[220:221], v[222:223], 0, s[6:7]
	s_addc_u32 s35, s39, 0
	s_add_i32 s38, s81, s48
	global_load_lds_dwordx4 v[220:221], off
	v_lshl_add_u64 v[220:221], s[34:35], 0, v[136:137]
	s_mov_b32 m0, s38
	s_nop 0
	global_load_lds_dwordx4 v[220:221], off
	v_lshl_add_u64 v[220:221], s[34:35], 0, v[132:133]
	s_add_i32 m0, s38, 0x2000
	s_nop 0
	global_load_lds_dwordx4 v[220:221], off
	v_lshl_add_u64 v[220:221], v[224:225], 0, s[6:7]
	s_mov_b32 m0, s55
	s_nop 0
	global_load_lds_dwordx4 v[220:221], off
	v_lshl_add_u64 v[220:221], v[226:227], 0, s[6:7]
	s_mov_b32 m0, s56
	s_nop 0
	global_load_lds_dwordx4 v[220:221], off
	s_waitcnt vmcnt(8)
	s_waitcnt lgkmcnt(0)
	s_barrier
	s_setprio 1
	s_waitcnt lgkmcnt(0)
	v_mfma_f32_16x16x32_bf16 v[60:63], v[148:151], v[188:191], v[60:63]
	v_mfma_f32_16x16x32_bf16 v[56:59], v[164:167], v[188:191], v[56:59]
	v_mfma_f32_16x16x32_bf16 v[44:47], v[148:151], v[196:199], v[44:47]
	v_mfma_f32_16x16x32_bf16 v[40:43], v[164:167], v[196:199], v[40:43]
	v_mfma_f32_16x16x32_bf16 v[28:31], v[148:151], v[204:207], v[28:31]
	v_mfma_f32_16x16x32_bf16 v[24:27], v[164:167], v[204:207], v[24:27]
	v_mfma_f32_16x16x32_bf16 v[12:15], v[148:151], v[212:215], v[12:15]
	v_mfma_f32_16x16x32_bf16 v[8:11], v[164:167], v[212:215], v[8:11]
	v_mfma_f32_16x16x32_bf16 v[60:63], v[160:163], v[192:195], v[60:63]
	v_mfma_f32_16x16x32_bf16 v[56:59], v[168:171], v[192:195], v[56:59]
	v_mfma_f32_16x16x32_bf16 v[44:47], v[160:163], v[200:203], v[44:47]
	v_mfma_f32_16x16x32_bf16 v[40:43], v[168:171], v[200:203], v[40:43]
	v_mfma_f32_16x16x32_bf16 v[28:31], v[160:163], v[208:211], v[28:31]
	v_mfma_f32_16x16x32_bf16 v[24:27], v[168:171], v[208:211], v[24:27]
	v_mfma_f32_16x16x32_bf16 v[12:15], v[160:163], v[216:219], v[12:15]
	v_mfma_f32_16x16x32_bf16 v[8:11], v[168:171], v[216:219], v[8:11]
	s_setprio 0
	s_setprio 1
	v_mfma_f32_16x16x32_bf16 v[52:55], v[172:175], v[188:191], v[52:55]
	v_mfma_f32_16x16x32_bf16 v[48:51], v[180:183], v[188:191], v[48:51]
	v_mfma_f32_16x16x32_bf16 v[36:39], v[172:175], v[196:199], v[36:39]
	v_mfma_f32_16x16x32_bf16 v[32:35], v[180:183], v[196:199], v[32:35]
	v_mfma_f32_16x16x32_bf16 v[20:23], v[172:175], v[204:207], v[20:23]
	v_mfma_f32_16x16x32_bf16 v[16:19], v[180:183], v[204:207], v[16:19]
	v_mfma_f32_16x16x32_bf16 v[4:7], v[172:175], v[212:215], v[4:7]
	v_mfma_f32_16x16x32_bf16 v[0:3], v[180:183], v[212:215], v[0:3]
	v_mfma_f32_16x16x32_bf16 v[52:55], v[176:179], v[192:195], v[52:55]
	v_mfma_f32_16x16x32_bf16 v[48:51], v[184:187], v[192:195], v[48:51]
	v_mfma_f32_16x16x32_bf16 v[36:39], v[176:179], v[200:203], v[36:39]
	v_mfma_f32_16x16x32_bf16 v[32:35], v[184:187], v[200:203], v[32:35]
	v_mfma_f32_16x16x32_bf16 v[20:23], v[176:179], v[208:211], v[20:23]
	v_mfma_f32_16x16x32_bf16 v[16:19], v[184:187], v[208:211], v[16:19]
	v_mfma_f32_16x16x32_bf16 v[4:7], v[176:179], v[216:219], v[4:7]
	v_mfma_f32_16x16x32_bf16 v[0:3], v[184:187], v[216:219], v[0:3]
	s_setprio 0
	s_barrier
	s_add_i32 s77, s77, 2
	s_add_u32 s36, s36, 0x100
	s_addc_u32 s37, s37, 0
	s_add_u32 s66, s66, 0x100
	s_addc_u32 s67, s67, 0

.LBB0_1144:
	s_add_u32 s30, s30, 0xb0080
	s_addc_u32 s31, s31, 0
	s_add_u32 s13, s36, 0x100
	s_addc_u32 s63, s37, 0
	s_mov_b32 s64, -2
	s_waitcnt lgkmcnt(0)
	s_cmp_lg_u32 s58, 1
	s_cselect_b32 s100, s99, 0
	s_cmp_lg_u32 s100, 0
	s_cbranch_scc0 .Lmy_nobar2_11
	s_barrier
.Lmy_nobar2_11:
	ds_read_b128 v[148:151], v154
	ds_read_b128 v[160:163], v154 offset:1024
	ds_read_b128 v[164:167], v154 offset:2048
	ds_read_b128 v[168:171], v154 offset:3072
	ds_read_b128 v[172:175], v155
	ds_read_b128 v[176:179], v155 offset:1024
	ds_read_b128 v[180:183], v155 offset:2048
	ds_read_b128 v[184:187], v155 offset:3072
	s_add_u32 s34, s30, 0xfff50080
	s_addc_u32 s35, s31, -1
	s_cmp_eq_u32 s64, 40
	s_cselect_b32 s39, s1, s35
	s_cselect_b32 s38, s0, s34
	s_cselect_b32 s37, s29, s63
	s_cselect_b32 s36, s28, s13
	v_lshl_add_u64 v[220:221], s[30:31], 0, v[140:141]
	s_add_i32 m0, s42, 0xc000
	ds_read_b128 v[188:191], v157
	ds_read_b128 v[192:195], v157 offset:1024
	ds_read_b128 v[196:199], v157 offset:2048
	ds_read_b128 v[200:203], v157 offset:3072
	ds_read_b128 v[204:207], v157 offset:4096
	ds_read_b128 v[208:211], v157 offset:5120
	ds_read_b128 v[212:215], v157 offset:6144
	ds_read_b128 v[216:219], v157 offset:7168
	global_load_lds_dwordx4 v[220:221], off
	v_lshl_add_u64 v[220:221], s[30:31], 0, v[142:143]
	s_add_i32 m0, s42, 0xe000
	s_nop 0
	global_load_lds_dwordx4 v[220:221], off
	s_waitcnt vmcnt(8)
	s_waitcnt lgkmcnt(0)
	s_barrier
	s_setprio 1
	s_waitcnt lgkmcnt(0)
	v_mfma_f32_16x16x32_bf16 v[124:127], v[148:151], v[188:191], 0
	v_mfma_f32_16x16x32_bf16 v[120:123], v[164:167], v[188:191], 0
	v_mfma_f32_16x16x32_bf16 v[108:111], v[148:151], v[196:199], 0
	v_mfma_f32_16x16x32_bf16 v[104:107], v[164:167], v[196:199], 0
	v_mfma_f32_16x16x32_bf16 v[92:95], v[148:151], v[204:207], 0
	v_mfma_f32_16x16x32_bf16 v[88:91], v[164:167], v[204:207], 0
	v_mfma_f32_16x16x32_bf16 v[76:79], v[148:151], v[212:215], 0
	v_mfma_f32_16x16x32_bf16 v[72:75], v[164:167], v[212:215], 0
	v_mfma_f32_16x16x32_bf16 v[124:127], v[160:163], v[192:195], v[124:127]
	v_mfma_f32_16x16x32_bf16 v[120:123], v[168:171], v[192:195], v[120:123]
	v_mfma_f32_16x16x32_bf16 v[108:111], v[160:163], v[200:203], v[108:111]
	v_mfma_f32_16x16x32_bf16 v[104:107], v[168:171], v[200:203], v[104:107]
	v_mfma_f32_16x16x32_bf16 v[92:95], v[160:163], v[208:211], v[92:95]
	v_mfma_f32_16x16x32_bf16 v[88:91], v[168:171], v[208:211], v[88:91]
	v_mfma_f32_16x16x32_bf16 v[76:79], v[160:163], v[216:219], v[76:79]
	v_mfma_f32_16x16x32_bf16 v[72:75], v[168:171], v[216:219], v[72:75]
	s_setprio 0
	s_setprio 1
	v_mfma_f32_16x16x32_bf16 v[116:119], v[172:175], v[188:191], 0
	v_mfma_f32_16x16x32_bf16 v[112:115], v[180:183], v[188:191], 0
	v_mfma_f32_16x16x32_bf16 v[100:103], v[172:175], v[196:199], 0
	v_mfma_f32_16x16x32_bf16 v[96:99], v[180:183], v[196:199], 0
	v_mfma_f32_16x16x32_bf16 v[84:87], v[172:175], v[204:207], 0
	v_mfma_f32_16x16x32_bf16 v[80:83], v[180:183], v[204:207], 0
	v_mfma_f32_16x16x32_bf16 v[68:71], v[172:175], v[212:215], 0
	v_mfma_f32_16x16x32_bf16 v[64:67], v[180:183], v[212:215], 0
	v_mfma_f32_16x16x32_bf16 v[116:119], v[176:179], v[192:195], v[116:119]
	v_mfma_f32_16x16x32_bf16 v[112:115], v[184:187], v[192:195], v[112:115]
	v_mfma_f32_16x16x32_bf16 v[100:103], v[176:179], v[200:203], v[100:103]
	v_mfma_f32_16x16x32_bf16 v[96:99], v[184:187], v[200:203], v[96:99]
	v_mfma_f32_16x16x32_bf16 v[84:87], v[176:179], v[208:211], v[84:87]
	v_mfma_f32_16x16x32_bf16 v[80:83], v[184:187], v[208:211], v[80:83]
	v_mfma_f32_16x16x32_bf16 v[68:71], v[176:179], v[216:219], v[68:71]
	v_mfma_f32_16x16x32_bf16 v[64:67], v[184:187], v[216:219], v[64:67]
	s_setprio 0
	s_barrier
	s_add_i32 s34, s56, s41
	v_lshl_add_u64 v[220:221], s[36:37], 0, v[134:135]
	s_mov_b32 m0, s34
	ds_read_b128 v[188:191], v157 offset:16384
	ds_read_b128 v[192:195], v157 offset:17408
	ds_read_b128 v[196:199], v157 offset:18432
	ds_read_b128 v[200:203], v157 offset:19456
	ds_read_b128 v[204:207], v157 offset:20480
	ds_read_b128 v[208:211], v157 offset:21504
	ds_read_b128 v[212:215], v157 offset:22528
	ds_read_b128 v[216:219], v157 offset:23552
	global_load_lds_dwordx4 v[220:221], off
	s_add_i32 m0, s34, 0x2000
	s_add_u32 s34, s36, 0xb0000
	v_lshl_add_u64 v[222:223], s[36:37], 0, v[138:139]
	s_addc_u32 s35, s37, 0
	s_add_i32 s65, s57, s41
	global_load_lds_dwordx4 v[222:223], off
	v_lshl_add_u64 v[224:225], s[34:35], 0, v[134:135]
	s_mov_b32 m0, s65
	v_lshl_add_u64 v[226:227], s[38:39], 0, v[136:137]
	global_load_lds_dwordx4 v[224:225], off
	v_lshl_add_u64 v[224:225], s[34:35], 0, v[138:139]
	s_add_i32 m0, s65, 0x2000
	s_nop 0
	global_load_lds_dwordx4 v[224:225], off
	v_lshl_add_u64 v[224:225], s[38:39], 0, v[132:133]
	s_mov_b32 m0, s42
	s_nop 0
	global_load_lds_dwordx4 v[224:225], off
	s_mov_b32 m0, s43
	s_nop 0
	global_load_lds_dwordx4 v[226:227], off
	s_waitcnt vmcnt(8)
	s_waitcnt lgkmcnt(0)
	s_barrier
	s_setprio 1
	s_waitcnt lgkmcnt(0)
	v_mfma_f32_16x16x32_bf16 v[60:63], v[148:151], v[188:191], 0
	v_mfma_f32_16x16x32_bf16 v[56:59], v[164:167], v[188:191], 0
	v_mfma_f32_16x16x32_bf16 v[44:47], v[148:151], v[196:199], 0
	v_mfma_f32_16x16x32_bf16 v[40:43], v[164:167], v[196:199], 0
	v_mfma_f32_16x16x32_bf16 v[28:31], v[148:151], v[204:207], 0
	v_mfma_f32_16x16x32_bf16 v[24:27], v[164:167], v[204:207], 0
	v_mfma_f32_16x16x32_bf16 v[12:15], v[148:151], v[212:215], 0
	v_mfma_f32_16x16x32_bf16 v[8:11], v[164:167], v[212:215], 0
	v_mfma_f32_16x16x32_bf16 v[60:63], v[160:163], v[192:195], v[60:63]
	v_mfma_f32_16x16x32_bf16 v[56:59], v[168:171], v[192:195], v[56:59]
	v_mfma_f32_16x16x32_bf16 v[44:47], v[160:163], v[200:203], v[44:47]
	v_mfma_f32_16x16x32_bf16 v[40:43], v[168:171], v[200:203], v[40:43]
	v_mfma_f32_16x16x32_bf16 v[28:31], v[160:163], v[208:211], v[28:31]
	v_mfma_f32_16x16x32_bf16 v[24:27], v[168:171], v[208:211], v[24:27]
	v_mfma_f32_16x16x32_bf16 v[12:15], v[160:163], v[216:219], v[12:15]
	v_mfma_f32_16x16x32_bf16 v[8:11], v[168:171], v[216:219], v[8:11]
	s_setprio 0
	s_setprio 1
	v_mfma_f32_16x16x32_bf16 v[52:55], v[172:175], v[188:191], 0
	v_mfma_f32_16x16x32_bf16 v[48:51], v[180:183], v[188:191], 0
	v_mfma_f32_16x16x32_bf16 v[36:39], v[172:175], v[196:199], 0
	v_mfma_f32_16x16x32_bf16 v[32:35], v[180:183], v[196:199], 0
	v_mfma_f32_16x16x32_bf16 v[20:23], v[172:175], v[204:207], 0
	v_mfma_f32_16x16x32_bf16 v[16:19], v[180:183], v[204:207], 0
	v_mfma_f32_16x16x32_bf16 v[4:7], v[172:175], v[212:215], 0
	v_mfma_f32_16x16x32_bf16 v[0:3], v[180:183], v[212:215], 0
	v_mfma_f32_16x16x32_bf16 v[52:55], v[176:179], v[192:195], v[52:55]
	v_mfma_f32_16x16x32_bf16 v[48:51], v[184:187], v[192:195], v[48:51]
	v_mfma_f32_16x16x32_bf16 v[36:39], v[176:179], v[200:203], v[36:39]
	v_mfma_f32_16x16x32_bf16 v[32:35], v[184:187], v[200:203], v[32:35]
	v_mfma_f32_16x16x32_bf16 v[20:23], v[176:179], v[208:211], v[20:23]
	v_mfma_f32_16x16x32_bf16 v[16:19], v[184:187], v[208:211], v[16:19]
	v_mfma_f32_16x16x32_bf16 v[4:7], v[176:179], v[216:219], v[4:7]
	v_mfma_f32_16x16x32_bf16 v[0:3], v[184:187], v[216:219], v[0:3]
	s_setprio 0
	s_barrier
	s_add_i32 s65, 0, 0x18000
	v_add_u32_e32 v159, s65, v152
	s_add_i32 s66, 0, 0x1c000
	ds_read_b128 v[148:151], v159
	ds_read_b128 v[160:163], v159 offset:1024
	ds_read_b128 v[164:167], v159 offset:2048
	ds_read_b128 v[168:171], v159 offset:3072
	v_add_u32_e32 v159, s66, v152
	ds_read_b128 v[172:175], v159
	ds_read_b128 v[176:179], v159 offset:1024
	ds_read_b128 v[180:183], v159 offset:2048
	ds_read_b128 v[184:187], v159 offset:3072
	s_add_u32 s34, s38, 0xb0000
	s_addc_u32 s35, s39, 0
	s_mov_b32 m0, s48
	v_lshl_add_u64 v[228:229], s[34:35], 0, v[132:133]
	ds_read_b128 v[188:191], v157 offset:32768
	ds_read_b128 v[192:195], v157 offset:33792
	ds_read_b128 v[196:199], v157 offset:34816
	ds_read_b128 v[200:203], v157 offset:35840
	ds_read_b128 v[204:207], v157 offset:36864
	ds_read_b128 v[208:211], v157 offset:37888
	ds_read_b128 v[212:215], v157 offset:38912
	ds_read_b128 v[216:219], v157 offset:39936
	global_load_lds_dwordx4 v[228:229], off
	v_lshl_add_u64 v[228:229], s[34:35], 0, v[136:137]
	s_mov_b32 m0, s49
	s_nop 0
	global_load_lds_dwordx4 v[228:229], off
	s_waitcnt vmcnt(8)
	s_waitcnt lgkmcnt(0)
	s_barrier
	s_setprio 1
	s_waitcnt lgkmcnt(0)
	v_mfma_f32_16x16x32_bf16 v[124:127], v[148:151], v[188:191], v[124:127]
	v_mfma_f32_16x16x32_bf16 v[120:123], v[164:167], v[188:191], v[120:123]
	v_mfma_f32_16x16x32_bf16 v[108:111], v[148:151], v[196:199], v[108:111]
	v_mfma_f32_16x16x32_bf16 v[104:107], v[164:167], v[196:199], v[104:107]
	v_mfma_f32_16x16x32_bf16 v[92:95], v[148:151], v[204:207], v[92:95]
	v_mfma_f32_16x16x32_bf16 v[88:91], v[164:167], v[204:207], v[88:91]
	v_mfma_f32_16x16x32_bf16 v[76:79], v[148:151], v[212:215], v[76:79]
	v_mfma_f32_16x16x32_bf16 v[72:75], v[164:167], v[212:215], v[72:75]
	v_mfma_f32_16x16x32_bf16 v[124:127], v[160:163], v[192:195], v[124:127]
	v_mfma_f32_16x16x32_bf16 v[120:123], v[168:171], v[192:195], v[120:123]
	v_mfma_f32_16x16x32_bf16 v[108:111], v[160:163], v[200:203], v[108:111]
	v_mfma_f32_16x16x32_bf16 v[104:107], v[168:171], v[200:203], v[104:107]
	v_mfma_f32_16x16x32_bf16 v[92:95], v[160:163], v[208:211], v[92:95]
	v_mfma_f32_16x16x32_bf16 v[88:91], v[168:171], v[208:211], v[88:91]
	v_mfma_f32_16x16x32_bf16 v[76:79], v[160:163], v[216:219], v[76:79]
	v_mfma_f32_16x16x32_bf16 v[72:75], v[168:171], v[216:219], v[72:75]
	s_setprio 0
	s_setprio 1
	v_mfma_f32_16x16x32_bf16 v[116:119], v[172:175], v[188:191], v[116:119]
	v_mfma_f32_16x16x32_bf16 v[112:115], v[180:183], v[188:191], v[112:115]
	v_mfma_f32_16x16x32_bf16 v[100:103], v[172:175], v[196:199], v[100:103]
	v_mfma_f32_16x16x32_bf16 v[96:99], v[180:183], v[196:199], v[96:99]
	v_mfma_f32_16x16x32_bf16 v[84:87], v[172:175], v[204:207], v[84:87]
	v_mfma_f32_16x16x32_bf16 v[80:83], v[180:183], v[204:207], v[80:83]
	v_mfma_f32_16x16x32_bf16 v[68:71], v[172:175], v[212:215], v[68:71]
	v_mfma_f32_16x16x32_bf16 v[64:67], v[180:183], v[212:215], v[64:67]
	v_mfma_f32_16x16x32_bf16 v[116:119], v[176:179], v[192:195], v[116:119]
	v_mfma_f32_16x16x32_bf16 v[112:115], v[184:187], v[192:195], v[112:115]
	v_mfma_f32_16x16x32_bf16 v[100:103], v[176:179], v[200:203], v[100:103]
	v_mfma_f32_16x16x32_bf16 v[96:99], v[184:187], v[200:203], v[96:99]
	v_mfma_f32_16x16x32_bf16 v[84:87], v[176:179], v[208:211], v[84:87]
	v_mfma_f32_16x16x32_bf16 v[80:83], v[184:187], v[208:211], v[80:83]
	v_mfma_f32_16x16x32_bf16 v[68:71], v[176:179], v[216:219], v[68:71]
	v_mfma_f32_16x16x32_bf16 v[64:67], v[184:187], v[216:219], v[64:67]
	s_setprio 0
	s_barrier
	s_add_i32 s34, s65, s41
	v_lshl_add_u64 v[220:221], v[220:221], 0, s[22:23]
	s_mov_b32 m0, s34
	ds_read_b128 v[188:191], v157 offset:49152
	ds_read_b128 v[192:195], v157 offset:50176
	ds_read_b128 v[196:199], v157 offset:51200
	ds_read_b128 v[200:203], v157 offset:52224
	ds_read_b128 v[204:207], v157 offset:53248
	ds_read_b128 v[208:211], v157 offset:54272
	ds_read_b128 v[212:215], v157 offset:55296
	ds_read_b128 v[216:219], v157 offset:56320
	global_load_lds_dwordx4 v[220:221], off
	s_add_i32 m0, s34, 0x2000
	s_add_u32 s34, s36, 0xb0080
	v_lshl_add_u64 v[220:221], v[222:223], 0, s[22:23]
	s_addc_u32 s35, s37, 0
	s_add_i32 s36, s66, s41
	global_load_lds_dwordx4 v[220:221], off
	v_lshl_add_u64 v[220:221], s[34:35], 0, v[134:135]
	s_mov_b32 m0, s36
	s_nop 0
	global_load_lds_dwordx4 v[220:221], off
	v_lshl_add_u64 v[220:221], s[34:35], 0, v[138:139]
	s_add_i32 m0, s36, 0x2000
	s_nop 0
	global_load_lds_dwordx4 v[220:221], off
	v_lshl_add_u64 v[220:221], v[224:225], 0, s[22:23]
	s_mov_b32 m0, s51
	s_nop 0
	global_load_lds_dwordx4 v[220:221], off
	v_lshl_add_u64 v[220:221], v[226:227], 0, s[22:23]
	s_mov_b32 m0, s52
	s_nop 0
	global_load_lds_dwordx4 v[220:221], off
	s_waitcnt vmcnt(8)
	s_waitcnt lgkmcnt(0)
	s_barrier
	s_setprio 1
	s_waitcnt lgkmcnt(0)
	v_mfma_f32_16x16x32_bf16 v[60:63], v[148:151], v[188:191], v[60:63]
	v_mfma_f32_16x16x32_bf16 v[56:59], v[164:167], v[188:191], v[56:59]
	v_mfma_f32_16x16x32_bf16 v[44:47], v[148:151], v[196:199], v[44:47]
	v_mfma_f32_16x16x32_bf16 v[40:43], v[164:167], v[196:199], v[40:43]
	v_mfma_f32_16x16x32_bf16 v[28:31], v[148:151], v[204:207], v[28:31]
	v_mfma_f32_16x16x32_bf16 v[24:27], v[164:167], v[204:207], v[24:27]
	v_mfma_f32_16x16x32_bf16 v[12:15], v[148:151], v[212:215], v[12:15]
	v_mfma_f32_16x16x32_bf16 v[8:11], v[164:167], v[212:215], v[8:11]
	v_mfma_f32_16x16x32_bf16 v[60:63], v[160:163], v[192:195], v[60:63]
	v_mfma_f32_16x16x32_bf16 v[56:59], v[168:171], v[192:195], v[56:59]
	v_mfma_f32_16x16x32_bf16 v[44:47], v[160:163], v[200:203], v[44:47]
	v_mfma_f32_16x16x32_bf16 v[40:43], v[168:171], v[200:203], v[40:43]
	v_mfma_f32_16x16x32_bf16 v[28:31], v[160:163], v[208:211], v[28:31]
	v_mfma_f32_16x16x32_bf16 v[24:27], v[168:171], v[208:211], v[24:27]
	v_mfma_f32_16x16x32_bf16 v[12:15], v[160:163], v[216:219], v[12:15]
	v_mfma_f32_16x16x32_bf16 v[8:11], v[168:171], v[216:219], v[8:11]
	s_setprio 0
	s_setprio 1
	v_mfma_f32_16x16x32_bf16 v[52:55], v[172:175], v[188:191], v[52:55]
	v_mfma_f32_16x16x32_bf16 v[48:51], v[180:183], v[188:191], v[48:51]
	v_mfma_f32_16x16x32_bf16 v[36:39], v[172:175], v[196:199], v[36:39]
	v_mfma_f32_16x16x32_bf16 v[32:35], v[180:183], v[196:199], v[32:35]
	v_mfma_f32_16x16x32_bf16 v[20:23], v[172:175], v[204:207], v[20:23]
	v_mfma_f32_16x16x32_bf16 v[16:19], v[180:183], v[204:207], v[16:19]
	v_mfma_f32_16x16x32_bf16 v[4:7], v[172:175], v[212:215], v[4:7]
	v_mfma_f32_16x16x32_bf16 v[0:3], v[180:183], v[212:215], v[0:3]
	v_mfma_f32_16x16x32_bf16 v[52:55], v[176:179], v[192:195], v[52:55]
	v_mfma_f32_16x16x32_bf16 v[48:51], v[184:187], v[192:195], v[48:51]
	v_mfma_f32_16x16x32_bf16 v[36:39], v[176:179], v[200:203], v[36:39]
	v_mfma_f32_16x16x32_bf16 v[32:35], v[184:187], v[200:203], v[32:35]
	v_mfma_f32_16x16x32_bf16 v[20:23], v[176:179], v[208:211], v[20:23]
	v_mfma_f32_16x16x32_bf16 v[16:19], v[184:187], v[208:211], v[16:19]
	v_mfma_f32_16x16x32_bf16 v[4:7], v[176:179], v[216:219], v[4:7]
	v_mfma_f32_16x16x32_bf16 v[0:3], v[184:187], v[216:219], v[0:3]
	s_setprio 0
	s_barrier
	s_add_i32 s64, s64, 2
	s_add_u32 s30, s30, 0x100
	s_addc_u32 s31, s31, 0
	s_add_u32 s13, s13, 0x100
	s_addc_u32 s63, s63, 0

.LBB0_1234:
	s_ashr_i32 s23, s22, 31
	s_lshl_b64 s[26:27], s[22:23], 19
	s_add_u32 s26, s14, s26
	s_addc_u32 s27, s15, s27
	s_and_b64 s[28:29], s[4:5], exec
	s_cselect_b32 s23, s27, s37
	s_cselect_b32 s64, s26, s36
	s_ashr_i32 s11, s10, 31
	s_lshl_b64 s[28:29], s[10:11], 19
	s_add_u32 s28, s49, s28
	s_addc_u32 s29, s50, s29
	s_and_b64 s[34:35], s[4:5], exec
	s_cselect_b32 s11, s29, s39
	s_cselect_b32 s65, s28, s38
	s_add_u32 s36, s36, 0x40080
	s_addc_u32 s37, s37, 0
	s_add_u32 s66, s38, 0x100
	s_addc_u32 s67, s39, 0
	s_mov_b32 s77, -2
	s_cmp_lg_u32 s58, 1
	s_cselect_b32 s100, s99, 0
	s_cmp_lg_u32 s100, 0
	s_cbranch_scc0 .Lmy_nobar2_12
	s_barrier
.Lmy_nobar2_12:
	ds_read_b128 v[148:151], v155
	ds_read_b128 v[160:163], v155 offset:1024
	ds_read_b128 v[164:167], v155 offset:2048
	ds_read_b128 v[168:171], v155 offset:3072
	ds_read_b128 v[172:175], v157
	ds_read_b128 v[176:179], v157 offset:1024
	ds_read_b128 v[180:183], v157 offset:2048
	ds_read_b128 v[184:187], v157 offset:3072
	s_add_u32 s34, s36, 0xfffc0080
	s_addc_u32 s35, s37, -1
	s_cmp_eq_u32 s77, 12
	s_cselect_b32 s41, s23, s35
	s_cselect_b32 s40, s64, s34
	s_cselect_b32 s39, s11, s67
	s_cselect_b32 s38, s65, s66
	v_lshl_add_u64 v[220:221], s[36:37], 0, v[140:141]
	s_add_i32 m0, s31, 0xc000
	ds_read_b128 v[188:191], v158
	ds_read_b128 v[192:195], v158 offset:1024
	ds_read_b128 v[196:199], v158 offset:2048
	ds_read_b128 v[200:203], v158 offset:3072
	ds_read_b128 v[204:207], v158 offset:4096
	ds_read_b128 v[208:211], v158 offset:5120
	ds_read_b128 v[212:215], v158 offset:6144
	ds_read_b128 v[216:219], v158 offset:7168
	global_load_lds_dwordx4 v[220:221], off
	v_lshl_add_u64 v[220:221], s[36:37], 0, v[142:143]
	s_add_i32 m0, s31, 0xe000
	s_nop 0
	global_load_lds_dwordx4 v[220:221], off
	s_waitcnt vmcnt(8)
	s_waitcnt lgkmcnt(0)
	s_barrier
	s_setprio 1
	s_waitcnt lgkmcnt(0)
	v_mfma_f32_16x16x32_bf16 v[124:127], v[148:151], v[188:191], 0
	v_mfma_f32_16x16x32_bf16 v[120:123], v[164:167], v[188:191], 0
	v_mfma_f32_16x16x32_bf16 v[108:111], v[148:151], v[196:199], 0
	v_mfma_f32_16x16x32_bf16 v[104:107], v[164:167], v[196:199], 0
	v_mfma_f32_16x16x32_bf16 v[92:95], v[148:151], v[204:207], 0
	v_mfma_f32_16x16x32_bf16 v[88:91], v[164:167], v[204:207], 0
	v_mfma_f32_16x16x32_bf16 v[76:79], v[148:151], v[212:215], 0
	v_mfma_f32_16x16x32_bf16 v[72:75], v[164:167], v[212:215], 0
	v_mfma_f32_16x16x32_bf16 v[124:127], v[160:163], v[192:195], v[124:127]
	v_mfma_f32_16x16x32_bf16 v[120:123], v[168:171], v[192:195], v[120:123]
	v_mfma_f32_16x16x32_bf16 v[108:111], v[160:163], v[200:203], v[108:111]
	v_mfma_f32_16x16x32_bf16 v[104:107], v[168:171], v[200:203], v[104:107]
	v_mfma_f32_16x16x32_bf16 v[92:95], v[160:163], v[208:211], v[92:95]
	v_mfma_f32_16x16x32_bf16 v[88:91], v[168:171], v[208:211], v[88:91]
	v_mfma_f32_16x16x32_bf16 v[76:79], v[160:163], v[216:219], v[76:79]
	v_mfma_f32_16x16x32_bf16 v[72:75], v[168:171], v[216:219], v[72:75]
	s_setprio 0
	s_setprio 1
	v_mfma_f32_16x16x32_bf16 v[116:119], v[172:175], v[188:191], 0
	v_mfma_f32_16x16x32_bf16 v[112:115], v[180:183], v[188:191], 0
	v_mfma_f32_16x16x32_bf16 v[100:103], v[172:175], v[196:199], 0
	v_mfma_f32_16x16x32_bf16 v[96:99], v[180:183], v[196:199], 0
	v_mfma_f32_16x16x32_bf16 v[84:87], v[172:175], v[204:207], 0
	v_mfma_f32_16x16x32_bf16 v[80:83], v[180:183], v[204:207], 0
	v_mfma_f32_16x16x32_bf16 v[68:71], v[172:175], v[212:215], 0
	v_mfma_f32_16x16x32_bf16 v[64:67], v[180:183], v[212:215], 0
	v_mfma_f32_16x16x32_bf16 v[116:119], v[176:179], v[192:195], v[116:119]
	v_mfma_f32_16x16x32_bf16 v[112:115], v[184:187], v[192:195], v[112:115]
	v_mfma_f32_16x16x32_bf16 v[100:103], v[176:179], v[200:203], v[100:103]
	v_mfma_f32_16x16x32_bf16 v[96:99], v[184:187], v[200:203], v[96:99]
	v_mfma_f32_16x16x32_bf16 v[84:87], v[176:179], v[208:211], v[84:87]
	v_mfma_f32_16x16x32_bf16 v[80:83], v[184:187], v[208:211], v[80:83]
	v_mfma_f32_16x16x32_bf16 v[68:71], v[176:179], v[216:219], v[68:71]
	v_mfma_f32_16x16x32_bf16 v[64:67], v[184:187], v[216:219], v[64:67]
	s_setprio 0
	s_barrier
	s_add_i32 s34, s55, s48
	v_lshl_add_u64 v[220:221], s[38:39], 0, v[136:137]
	s_mov_b32 m0, s34
	ds_read_b128 v[188:191], v158 offset:16384
	ds_read_b128 v[192:195], v158 offset:17408
	ds_read_b128 v[196:199], v158 offset:18432
	ds_read_b128 v[200:203], v158 offset:19456
	ds_read_b128 v[204:207], v158 offset:20480
	ds_read_b128 v[208:211], v158 offset:21504
	ds_read_b128 v[212:215], v158 offset:22528
	ds_read_b128 v[216:219], v158 offset:23552
	global_load_lds_dwordx4 v[220:221], off
	s_add_i32 m0, s34, 0x2000
	s_add_u32 s34, s38, 0x40000
	v_lshl_add_u64 v[222:223], s[38:39], 0, v[132:133]
	s_addc_u32 s35, s39, 0
	s_add_i32 s79, s56, s48
	global_load_lds_dwordx4 v[222:223], off
	v_lshl_add_u64 v[224:225], s[34:35], 0, v[136:137]
	s_mov_b32 m0, s79
	v_lshl_add_u64 v[226:227], s[40:41], 0, v[134:135]
	global_load_lds_dwordx4 v[224:225], off
	v_lshl_add_u64 v[224:225], s[34:35], 0, v[132:133]
	s_add_i32 m0, s79, 0x2000
	s_nop 0
	global_load_lds_dwordx4 v[224:225], off
	v_lshl_add_u64 v[224:225], s[40:41], 0, v[138:139]
	s_mov_b32 m0, s31
	s_nop 0
	global_load_lds_dwordx4 v[224:225], off
	s_mov_b32 m0, s52
	s_nop 0
	global_load_lds_dwordx4 v[226:227], off
	s_waitcnt vmcnt(8)
	s_waitcnt lgkmcnt(0)
	s_barrier
	s_setprio 1
	s_waitcnt lgkmcnt(0)
	v_mfma_f32_16x16x32_bf16 v[60:63], v[148:151], v[188:191], 0
	v_mfma_f32_16x16x32_bf16 v[56:59], v[164:167], v[188:191], 0
	v_mfma_f32_16x16x32_bf16 v[44:47], v[148:151], v[196:199], 0
	v_mfma_f32_16x16x32_bf16 v[40:43], v[164:167], v[196:199], 0
	v_mfma_f32_16x16x32_bf16 v[28:31], v[148:151], v[204:207], 0
	v_mfma_f32_16x16x32_bf16 v[24:27], v[164:167], v[204:207], 0
	v_mfma_f32_16x16x32_bf16 v[12:15], v[148:151], v[212:215], 0
	v_mfma_f32_16x16x32_bf16 v[8:11], v[164:167], v[212:215], 0
	v_mfma_f32_16x16x32_bf16 v[60:63], v[160:163], v[192:195], v[60:63]
	v_mfma_f32_16x16x32_bf16 v[56:59], v[168:171], v[192:195], v[56:59]
	v_mfma_f32_16x16x32_bf16 v[44:47], v[160:163], v[200:203], v[44:47]
	v_mfma_f32_16x16x32_bf16 v[40:43], v[168:171], v[200:203], v[40:43]
	v_mfma_f32_16x16x32_bf16 v[28:31], v[160:163], v[208:211], v[28:31]
	v_mfma_f32_16x16x32_bf16 v[24:27], v[168:171], v[208:211], v[24:27]
	v_mfma_f32_16x16x32_bf16 v[12:15], v[160:163], v[216:219], v[12:15]
	v_mfma_f32_16x16x32_bf16 v[8:11], v[168:171], v[216:219], v[8:11]
	s_setprio 0
	s_setprio 1
	v_mfma_f32_16x16x32_bf16 v[52:55], v[172:175], v[188:191], 0
	v_mfma_f32_16x16x32_bf16 v[48:51], v[180:183], v[188:191], 0
	v_mfma_f32_16x16x32_bf16 v[36:39], v[172:175], v[196:199], 0
	v_mfma_f32_16x16x32_bf16 v[32:35], v[180:183], v[196:199], 0
	v_mfma_f32_16x16x32_bf16 v[20:23], v[172:175], v[204:207], 0
	v_mfma_f32_16x16x32_bf16 v[16:19], v[180:183], v[204:207], 0
	v_mfma_f32_16x16x32_bf16 v[4:7], v[172:175], v[212:215], 0
	v_mfma_f32_16x16x32_bf16 v[0:3], v[180:183], v[212:215], 0
	v_mfma_f32_16x16x32_bf16 v[52:55], v[176:179], v[192:195], v[52:55]
	v_mfma_f32_16x16x32_bf16 v[48:51], v[184:187], v[192:195], v[48:51]
	v_mfma_f32_16x16x32_bf16 v[36:39], v[176:179], v[200:203], v[36:39]
	v_mfma_f32_16x16x32_bf16 v[32:35], v[184:187], v[200:203], v[32:35]
	v_mfma_f32_16x16x32_bf16 v[20:23], v[176:179], v[208:211], v[20:23]
	v_mfma_f32_16x16x32_bf16 v[16:19], v[184:187], v[208:211], v[16:19]
	v_mfma_f32_16x16x32_bf16 v[4:7], v[176:179], v[216:219], v[4:7]
	v_mfma_f32_16x16x32_bf16 v[0:3], v[184:187], v[216:219], v[0:3]
	s_setprio 0
	s_barrier
	s_add_i32 s79, 0, 0x18000
	v_add_u32_e32 v159, s79, v152
	s_add_i32 s81, 0, 0x1c000
	ds_read_b128 v[148:151], v159
	ds_read_b128 v[160:163], v159 offset:1024
	ds_read_b128 v[164:167], v159 offset:2048
	ds_read_b128 v[168:171], v159 offset:3072
	v_add_u32_e32 v159, s81, v152
	ds_read_b128 v[172:175], v159
	ds_read_b128 v[176:179], v159 offset:1024
	ds_read_b128 v[180:183], v159 offset:2048
	ds_read_b128 v[184:187], v159 offset:3072
	s_add_u32 s34, s40, 0x40000
	s_addc_u32 s35, s41, 0
	s_mov_b32 m0, s53
	v_lshl_add_u64 v[228:229], s[34:35], 0, v[138:139]
	ds_read_b128 v[188:191], v158 offset:32768
	ds_read_b128 v[192:195], v158 offset:33792
	ds_read_b128 v[196:199], v158 offset:34816
	ds_read_b128 v[200:203], v158 offset:35840
	ds_read_b128 v[204:207], v158 offset:36864
	ds_read_b128 v[208:211], v158 offset:37888
	ds_read_b128 v[212:215], v158 offset:38912
	ds_read_b128 v[216:219], v158 offset:39936
	global_load_lds_dwordx4 v[228:229], off
	v_lshl_add_u64 v[228:229], s[34:35], 0, v[134:135]
	s_mov_b32 m0, s54
	s_nop 0
	global_load_lds_dwordx4 v[228:229], off
	s_waitcnt vmcnt(8)
	s_waitcnt lgkmcnt(0)
	s_barrier
	s_setprio 1
	s_waitcnt lgkmcnt(0)
	v_mfma_f32_16x16x32_bf16 v[124:127], v[148:151], v[188:191], v[124:127]
	v_mfma_f32_16x16x32_bf16 v[120:123], v[164:167], v[188:191], v[120:123]
	v_mfma_f32_16x16x32_bf16 v[108:111], v[148:151], v[196:199], v[108:111]
	v_mfma_f32_16x16x32_bf16 v[104:107], v[164:167], v[196:199], v[104:107]
	v_mfma_f32_16x16x32_bf16 v[92:95], v[148:151], v[204:207], v[92:95]
	v_mfma_f32_16x16x32_bf16 v[88:91], v[164:167], v[204:207], v[88:91]
	v_mfma_f32_16x16x32_bf16 v[76:79], v[148:151], v[212:215], v[76:79]
	v_mfma_f32_16x16x32_bf16 v[72:75], v[164:167], v[212:215], v[72:75]
	v_mfma_f32_16x16x32_bf16 v[124:127], v[160:163], v[192:195], v[124:127]
	v_mfma_f32_16x16x32_bf16 v[120:123], v[168:171], v[192:195], v[120:123]
	v_mfma_f32_16x16x32_bf16 v[108:111], v[160:163], v[200:203], v[108:111]
	v_mfma_f32_16x16x32_bf16 v[104:107], v[168:171], v[200:203], v[104:107]
	v_mfma_f32_16x16x32_bf16 v[92:95], v[160:163], v[208:211], v[92:95]
	v_mfma_f32_16x16x32_bf16 v[88:91], v[168:171], v[208:211], v[88:91]
	v_mfma_f32_16x16x32_bf16 v[76:79], v[160:163], v[216:219], v[76:79]
	v_mfma_f32_16x16x32_bf16 v[72:75], v[168:171], v[216:219], v[72:75]
	s_setprio 0
	s_setprio 1
	v_mfma_f32_16x16x32_bf16 v[116:119], v[172:175], v[188:191], v[116:119]
	v_mfma_f32_16x16x32_bf16 v[112:115], v[180:183], v[188:191], v[112:115]
	v_mfma_f32_16x16x32_bf16 v[100:103], v[172:175], v[196:199], v[100:103]
	v_mfma_f32_16x16x32_bf16 v[96:99], v[180:183], v[196:199], v[96:99]
	v_mfma_f32_16x16x32_bf16 v[84:87], v[172:175], v[204:207], v[84:87]
	v_mfma_f32_16x16x32_bf16 v[80:83], v[180:183], v[204:207], v[80:83]
	v_mfma_f32_16x16x32_bf16 v[68:71], v[172:175], v[212:215], v[68:71]
	v_mfma_f32_16x16x32_bf16 v[64:67], v[180:183], v[212:215], v[64:67]
	v_mfma_f32_16x16x32_bf16 v[116:119], v[176:179], v[192:195], v[116:119]
	v_mfma_f32_16x16x32_bf16 v[112:115], v[184:187], v[192:195], v[112:115]
	v_mfma_f32_16x16x32_bf16 v[100:103], v[176:179], v[200:203], v[100:103]
	v_mfma_f32_16x16x32_bf16 v[96:99], v[184:187], v[200:203], v[96:99]
	v_mfma_f32_16x16x32_bf16 v[84:87], v[176:179], v[208:211], v[84:87]
	v_mfma_f32_16x16x32_bf16 v[80:83], v[184:187], v[208:211], v[80:83]
	v_mfma_f32_16x16x32_bf16 v[68:71], v[176:179], v[216:219], v[68:71]
	v_mfma_f32_16x16x32_bf16 v[64:67], v[184:187], v[216:219], v[64:67]
	s_setprio 0
	s_barrier
	s_add_i32 s34, s79, s48
	v_lshl_add_u64 v[220:221], v[220:221], 0, s[6:7]
	s_mov_b32 m0, s34
	ds_read_b128 v[188:191], v158 offset:49152
	ds_read_b128 v[192:195], v158 offset:50176
	ds_read_b128 v[196:199], v158 offset:51200
	ds_read_b128 v[200:203], v158 offset:52224
	ds_read_b128 v[204:207], v158 offset:53248
	ds_read_b128 v[208:211], v158 offset:54272
	ds_read_b128 v[212:215], v158 offset:55296
	ds_read_b128 v[216:219], v158 offset:56320
	global_load_lds_dwordx4 v[220:221], off
	s_add_i32 m0, s34, 0x2000
	s_add_u32 s34, s38, 0x40080
	v_lshl_add_u64 v[220:221], v[222:223], 0, s[6:7]
	s_addc_u32 s35, s39, 0
	s_add_i32 s38, s81, s48
	global_load_lds_dwordx4 v[220:221], off
	v_lshl_add_u64 v[220:221], s[34:35], 0, v[136:137]
	s_mov_b32 m0, s38
	s_nop 0
	global_load_lds_dwordx4 v[220:221], off
	v_lshl_add_u64 v[220:221], s[34:35], 0, v[132:133]
	s_add_i32 m0, s38, 0x2000
	s_nop 0
	global_load_lds_dwordx4 v[220:221], off
	v_lshl_add_u64 v[220:221], v[224:225], 0, s[6:7]
	s_mov_b32 m0, s12
	s_nop 0
	global_load_lds_dwordx4 v[220:221], off
	v_lshl_add_u64 v[220:221], v[226:227], 0, s[6:7]
	s_mov_b32 m0, s13
	s_nop 0
	global_load_lds_dwordx4 v[220:221], off
	s_waitcnt vmcnt(8)
	s_waitcnt lgkmcnt(0)
	s_barrier
	s_setprio 1
	s_waitcnt lgkmcnt(0)
	v_mfma_f32_16x16x32_bf16 v[60:63], v[148:151], v[188:191], v[60:63]
	v_mfma_f32_16x16x32_bf16 v[56:59], v[164:167], v[188:191], v[56:59]
	v_mfma_f32_16x16x32_bf16 v[44:47], v[148:151], v[196:199], v[44:47]
	v_mfma_f32_16x16x32_bf16 v[40:43], v[164:167], v[196:199], v[40:43]
	v_mfma_f32_16x16x32_bf16 v[28:31], v[148:151], v[204:207], v[28:31]
	v_mfma_f32_16x16x32_bf16 v[24:27], v[164:167], v[204:207], v[24:27]
	v_mfma_f32_16x16x32_bf16 v[12:15], v[148:151], v[212:215], v[12:15]
	v_mfma_f32_16x16x32_bf16 v[8:11], v[164:167], v[212:215], v[8:11]
	v_mfma_f32_16x16x32_bf16 v[60:63], v[160:163], v[192:195], v[60:63]
	v_mfma_f32_16x16x32_bf16 v[56:59], v[168:171], v[192:195], v[56:59]
	v_mfma_f32_16x16x32_bf16 v[44:47], v[160:163], v[200:203], v[44:47]
	v_mfma_f32_16x16x32_bf16 v[40:43], v[168:171], v[200:203], v[40:43]
	v_mfma_f32_16x16x32_bf16 v[28:31], v[160:163], v[208:211], v[28:31]
	v_mfma_f32_16x16x32_bf16 v[24:27], v[168:171], v[208:211], v[24:27]
	v_mfma_f32_16x16x32_bf16 v[12:15], v[160:163], v[216:219], v[12:15]
	v_mfma_f32_16x16x32_bf16 v[8:11], v[168:171], v[216:219], v[8:11]
	s_setprio 0
	s_setprio 1
	v_mfma_f32_16x16x32_bf16 v[52:55], v[172:175], v[188:191], v[52:55]
	v_mfma_f32_16x16x32_bf16 v[48:51], v[180:183], v[188:191], v[48:51]
	v_mfma_f32_16x16x32_bf16 v[36:39], v[172:175], v[196:199], v[36:39]
	v_mfma_f32_16x16x32_bf16 v[32:35], v[180:183], v[196:199], v[32:35]
	v_mfma_f32_16x16x32_bf16 v[20:23], v[172:175], v[204:207], v[20:23]
	v_mfma_f32_16x16x32_bf16 v[16:19], v[180:183], v[204:207], v[16:19]
	v_mfma_f32_16x16x32_bf16 v[4:7], v[172:175], v[212:215], v[4:7]
	v_mfma_f32_16x16x32_bf16 v[0:3], v[180:183], v[212:215], v[0:3]
	v_mfma_f32_16x16x32_bf16 v[52:55], v[176:179], v[192:195], v[52:55]
	v_mfma_f32_16x16x32_bf16 v[48:51], v[184:187], v[192:195], v[48:51]
	v_mfma_f32_16x16x32_bf16 v[36:39], v[176:179], v[200:203], v[36:39]
	v_mfma_f32_16x16x32_bf16 v[32:35], v[184:187], v[200:203], v[32:35]
	v_mfma_f32_16x16x32_bf16 v[20:23], v[176:179], v[208:211], v[20:23]
	v_mfma_f32_16x16x32_bf16 v[16:19], v[184:187], v[208:211], v[16:19]
	v_mfma_f32_16x16x32_bf16 v[4:7], v[176:179], v[216:219], v[4:7]
	v_mfma_f32_16x16x32_bf16 v[0:3], v[184:187], v[216:219], v[0:3]
	s_setprio 0
	s_barrier
	s_add_i32 s77, s77, 2
	s_add_u32 s36, s36, 0x100
	s_addc_u32 s37, s37, 0
	s_add_u32 s66, s66, 0x100
	s_addc_u32 s67, s67, 0

.LBB0_1556:
	s_ashr_i32 s29, s28, 31
	s_lshl_b64 s[12:13], s[28:29], 19
	s_add_u32 s30, s20, s12
	s_addc_u32 s31, s21, s13
	s_and_b64 s[12:13], s[6:7], exec
	s_cselect_b32 s12, s31, s41
	s_cselect_b32 s13, s30, s40
	s_ashr_i32 s27, s26, 31
	s_lshl_b64 s[34:35], s[26:27], 19
	s_add_u32 s36, s3, s34
	s_addc_u32 s37, s46, s35
	s_and_b64 s[34:35], s[6:7], exec
	s_cselect_b32 s27, s37, s43
	s_cselect_b32 s29, s36, s42
	s_add_u32 s40, s40, 0x40080
	s_addc_u32 s41, s41, 0
	s_add_u32 s39, s42, 0x100
	s_addc_u32 s61, s43, 0
	s_mov_b32 s62, -2
	s_waitcnt lgkmcnt(0)
	s_cmp_lg_u32 s60, 1
	s_cselect_b32 s100, s99, 0
	s_cmp_lg_u32 s100, 0
	s_cbranch_scc0 .Lmy_nobar2_16
	s_barrier
.Lmy_nobar2_16:
	ds_read_b128 v[146:149], v153
	ds_read_b128 v[158:161], v153 offset:1024
	ds_read_b128 v[162:165], v153 offset:2048
	ds_read_b128 v[166:169], v153 offset:3072
	ds_read_b128 v[170:173], v154
	ds_read_b128 v[174:177], v154 offset:1024
	ds_read_b128 v[178:181], v154 offset:2048
	ds_read_b128 v[182:185], v154 offset:3072
	s_add_u32 s34, s40, 0xfffc0080
	s_addc_u32 s35, s41, -1
	s_cmp_eq_u32 s62, 12
	s_cselect_b32 s45, s12, s35
	s_cselect_b32 s44, s13, s34
	s_cselect_b32 s43, s27, s61
	s_cselect_b32 s42, s29, s39
	v_lshl_add_u64 v[218:219], s[40:41], 0, v[138:139]
	s_add_i32 m0, s48, 0xc000
	ds_read_b128 v[186:189], v155
	ds_read_b128 v[190:193], v155 offset:1024
	ds_read_b128 v[194:197], v155 offset:2048
	ds_read_b128 v[198:201], v155 offset:3072
	ds_read_b128 v[202:205], v155 offset:4096
	ds_read_b128 v[206:209], v155 offset:5120
	ds_read_b128 v[210:213], v155 offset:6144
	ds_read_b128 v[214:217], v155 offset:7168
	global_load_lds_dwordx4 v[218:219], off
	v_lshl_add_u64 v[218:219], s[40:41], 0, v[140:141]
	s_add_i32 m0, s48, 0xe000
	s_nop 0
	global_load_lds_dwordx4 v[218:219], off
	s_waitcnt vmcnt(8)
	s_waitcnt lgkmcnt(0)
	s_barrier
	s_setprio 1
	s_waitcnt lgkmcnt(0)
	v_mfma_f32_16x16x32_bf16 v[124:127], v[146:149], v[186:189], 0
	v_mfma_f32_16x16x32_bf16 v[120:123], v[162:165], v[186:189], 0
	v_mfma_f32_16x16x32_bf16 v[108:111], v[146:149], v[194:197], 0
	v_mfma_f32_16x16x32_bf16 v[104:107], v[162:165], v[194:197], 0
	v_mfma_f32_16x16x32_bf16 v[92:95], v[146:149], v[202:205], 0
	v_mfma_f32_16x16x32_bf16 v[88:91], v[162:165], v[202:205], 0
	v_mfma_f32_16x16x32_bf16 v[76:79], v[146:149], v[210:213], 0
	v_mfma_f32_16x16x32_bf16 v[72:75], v[162:165], v[210:213], 0
	v_mfma_f32_16x16x32_bf16 v[124:127], v[158:161], v[190:193], v[124:127]
	v_mfma_f32_16x16x32_bf16 v[120:123], v[166:169], v[190:193], v[120:123]
	v_mfma_f32_16x16x32_bf16 v[108:111], v[158:161], v[198:201], v[108:111]
	v_mfma_f32_16x16x32_bf16 v[104:107], v[166:169], v[198:201], v[104:107]
	v_mfma_f32_16x16x32_bf16 v[92:95], v[158:161], v[206:209], v[92:95]
	v_mfma_f32_16x16x32_bf16 v[88:91], v[166:169], v[206:209], v[88:91]
	v_mfma_f32_16x16x32_bf16 v[76:79], v[158:161], v[214:217], v[76:79]
	v_mfma_f32_16x16x32_bf16 v[72:75], v[166:169], v[214:217], v[72:75]
	s_setprio 0
	s_setprio 1
	v_mfma_f32_16x16x32_bf16 v[116:119], v[170:173], v[186:189], 0
	v_mfma_f32_16x16x32_bf16 v[112:115], v[178:181], v[186:189], 0
	v_mfma_f32_16x16x32_bf16 v[100:103], v[170:173], v[194:197], 0
	v_mfma_f32_16x16x32_bf16 v[96:99], v[178:181], v[194:197], 0
	v_mfma_f32_16x16x32_bf16 v[84:87], v[170:173], v[202:205], 0
	v_mfma_f32_16x16x32_bf16 v[80:83], v[178:181], v[202:205], 0
	v_mfma_f32_16x16x32_bf16 v[68:71], v[170:173], v[210:213], 0
	v_mfma_f32_16x16x32_bf16 v[64:67], v[178:181], v[210:213], 0
	v_mfma_f32_16x16x32_bf16 v[116:119], v[174:177], v[190:193], v[116:119]
	v_mfma_f32_16x16x32_bf16 v[112:115], v[182:185], v[190:193], v[112:115]
	v_mfma_f32_16x16x32_bf16 v[100:103], v[174:177], v[198:201], v[100:103]
	v_mfma_f32_16x16x32_bf16 v[96:99], v[182:185], v[198:201], v[96:99]
	v_mfma_f32_16x16x32_bf16 v[84:87], v[174:177], v[206:209], v[84:87]
	v_mfma_f32_16x16x32_bf16 v[80:83], v[182:185], v[206:209], v[80:83]
	v_mfma_f32_16x16x32_bf16 v[68:71], v[174:177], v[214:217], v[68:71]
	v_mfma_f32_16x16x32_bf16 v[64:67], v[182:185], v[214:217], v[64:67]
	s_setprio 0
	s_barrier
	s_add_i32 s34, s58, s47
	v_lshl_add_u64 v[218:219], s[42:43], 0, v[132:133]
	s_mov_b32 m0, s34
	ds_read_b128 v[186:189], v155 offset:16384
	ds_read_b128 v[190:193], v155 offset:17408
	ds_read_b128 v[194:197], v155 offset:18432
	ds_read_b128 v[198:201], v155 offset:19456
	ds_read_b128 v[202:205], v155 offset:20480
	ds_read_b128 v[206:209], v155 offset:21504
	ds_read_b128 v[210:213], v155 offset:22528
	ds_read_b128 v[214:217], v155 offset:23552
	global_load_lds_dwordx4 v[218:219], off
	s_add_i32 m0, s34, 0x2000
	s_add_u32 s34, s42, 0x40000
	v_lshl_add_u64 v[220:221], s[42:43], 0, v[136:137]
	s_addc_u32 s35, s43, 0
	s_add_i32 s63, s59, s47
	global_load_lds_dwordx4 v[220:221], off
	v_lshl_add_u64 v[222:223], s[34:35], 0, v[132:133]
	s_mov_b32 m0, s63
	v_lshl_add_u64 v[224:225], s[44:45], 0, v[134:135]
	global_load_lds_dwordx4 v[222:223], off
	v_lshl_add_u64 v[222:223], s[34:35], 0, v[136:137]
	s_add_i32 m0, s63, 0x2000
	s_nop 0
	global_load_lds_dwordx4 v[222:223], off
	v_lshl_add_u64 v[222:223], s[44:45], 0, v[130:131]
	s_mov_b32 m0, s48
	s_nop 0
	global_load_lds_dwordx4 v[222:223], off
	s_mov_b32 m0, s49
	s_nop 0
	global_load_lds_dwordx4 v[224:225], off
	s_waitcnt vmcnt(8)
	s_waitcnt lgkmcnt(0)
	s_barrier
	s_setprio 1
	s_waitcnt lgkmcnt(0)
	v_mfma_f32_16x16x32_bf16 v[60:63], v[146:149], v[186:189], 0
	v_mfma_f32_16x16x32_bf16 v[56:59], v[162:165], v[186:189], 0
	v_mfma_f32_16x16x32_bf16 v[44:47], v[146:149], v[194:197], 0
	v_mfma_f32_16x16x32_bf16 v[40:43], v[162:165], v[194:197], 0
	v_mfma_f32_16x16x32_bf16 v[28:31], v[146:149], v[202:205], 0
	v_mfma_f32_16x16x32_bf16 v[24:27], v[162:165], v[202:205], 0
	v_mfma_f32_16x16x32_bf16 v[12:15], v[146:149], v[210:213], 0
	v_mfma_f32_16x16x32_bf16 v[8:11], v[162:165], v[210:213], 0
	v_mfma_f32_16x16x32_bf16 v[60:63], v[158:161], v[190:193], v[60:63]
	v_mfma_f32_16x16x32_bf16 v[56:59], v[166:169], v[190:193], v[56:59]
	v_mfma_f32_16x16x32_bf16 v[44:47], v[158:161], v[198:201], v[44:47]
	v_mfma_f32_16x16x32_bf16 v[40:43], v[166:169], v[198:201], v[40:43]
	v_mfma_f32_16x16x32_bf16 v[28:31], v[158:161], v[206:209], v[28:31]
	v_mfma_f32_16x16x32_bf16 v[24:27], v[166:169], v[206:209], v[24:27]
	v_mfma_f32_16x16x32_bf16 v[12:15], v[158:161], v[214:217], v[12:15]
	v_mfma_f32_16x16x32_bf16 v[8:11], v[166:169], v[214:217], v[8:11]
	s_setprio 0
	s_setprio 1
	v_mfma_f32_16x16x32_bf16 v[52:55], v[170:173], v[186:189], 0
	v_mfma_f32_16x16x32_bf16 v[48:51], v[178:181], v[186:189], 0
	v_mfma_f32_16x16x32_bf16 v[36:39], v[170:173], v[194:197], 0
	v_mfma_f32_16x16x32_bf16 v[32:35], v[178:181], v[194:197], 0
	v_mfma_f32_16x16x32_bf16 v[20:23], v[170:173], v[202:205], 0
	v_mfma_f32_16x16x32_bf16 v[16:19], v[178:181], v[202:205], 0
	v_mfma_f32_16x16x32_bf16 v[4:7], v[170:173], v[210:213], 0
	v_mfma_f32_16x16x32_bf16 v[0:3], v[178:181], v[210:213], 0
	v_mfma_f32_16x16x32_bf16 v[52:55], v[174:177], v[190:193], v[52:55]
	v_mfma_f32_16x16x32_bf16 v[48:51], v[182:185], v[190:193], v[48:51]
	v_mfma_f32_16x16x32_bf16 v[36:39], v[174:177], v[198:201], v[36:39]
	v_mfma_f32_16x16x32_bf16 v[32:35], v[182:185], v[198:201], v[32:35]
	v_mfma_f32_16x16x32_bf16 v[20:23], v[174:177], v[206:209], v[20:23]
	v_mfma_f32_16x16x32_bf16 v[16:19], v[182:185], v[206:209], v[16:19]
	v_mfma_f32_16x16x32_bf16 v[4:7], v[174:177], v[214:217], v[4:7]
	v_mfma_f32_16x16x32_bf16 v[0:3], v[182:185], v[214:217], v[0:3]
	s_setprio 0
	s_barrier
	s_add_i32 s63, 0, 0x18000
	s_add_i32 s64, 0, 0x1c000
	v_add_u32_e32 v166, s63, v151
	v_add_u32_e32 v182, s64, v151
	ds_read_b128 v[146:149], v166
	ds_read_b128 v[158:161], v166 offset:1024
	ds_read_b128 v[162:165], v166 offset:2048
	ds_read_b128 v[166:169], v166 offset:3072
	ds_read_b128 v[170:173], v182
	ds_read_b128 v[174:177], v182 offset:1024
	ds_read_b128 v[178:181], v182 offset:2048
	ds_read_b128 v[182:185], v182 offset:3072
	s_add_u32 s34, s44, 0x40000
	s_addc_u32 s35, s45, 0
	s_mov_b32 m0, s50
	v_lshl_add_u64 v[226:227], s[34:35], 0, v[130:131]
	ds_read_b128 v[186:189], v155 offset:32768
	ds_read_b128 v[190:193], v155 offset:33792
	ds_read_b128 v[194:197], v155 offset:34816
	ds_read_b128 v[198:201], v155 offset:35840
	ds_read_b128 v[202:205], v155 offset:36864
	ds_read_b128 v[206:209], v155 offset:37888
	ds_read_b128 v[210:213], v155 offset:38912
	ds_read_b128 v[214:217], v155 offset:39936
	global_load_lds_dwordx4 v[226:227], off
	v_lshl_add_u64 v[226:227], s[34:35], 0, v[134:135]
	s_mov_b32 m0, s51
	s_nop 0
	global_load_lds_dwordx4 v[226:227], off
	s_waitcnt vmcnt(8)
	s_waitcnt lgkmcnt(0)
	s_barrier
	s_setprio 1
	s_waitcnt lgkmcnt(0)
	v_mfma_f32_16x16x32_bf16 v[124:127], v[146:149], v[186:189], v[124:127]
	v_mfma_f32_16x16x32_bf16 v[120:123], v[162:165], v[186:189], v[120:123]
	v_mfma_f32_16x16x32_bf16 v[108:111], v[146:149], v[194:197], v[108:111]
	v_mfma_f32_16x16x32_bf16 v[104:107], v[162:165], v[194:197], v[104:107]
	v_mfma_f32_16x16x32_bf16 v[92:95], v[146:149], v[202:205], v[92:95]
	v_mfma_f32_16x16x32_bf16 v[88:91], v[162:165], v[202:205], v[88:91]
	v_mfma_f32_16x16x32_bf16 v[76:79], v[146:149], v[210:213], v[76:79]
	v_mfma_f32_16x16x32_bf16 v[72:75], v[162:165], v[210:213], v[72:75]
	v_mfma_f32_16x16x32_bf16 v[124:127], v[158:161], v[190:193], v[124:127]
	v_mfma_f32_16x16x32_bf16 v[120:123], v[166:169], v[190:193], v[120:123]
	v_mfma_f32_16x16x32_bf16 v[108:111], v[158:161], v[198:201], v[108:111]
	v_mfma_f32_16x16x32_bf16 v[104:107], v[166:169], v[198:201], v[104:107]
	v_mfma_f32_16x16x32_bf16 v[92:95], v[158:161], v[206:209], v[92:95]
	v_mfma_f32_16x16x32_bf16 v[88:91], v[166:169], v[206:209], v[88:91]
	v_mfma_f32_16x16x32_bf16 v[76:79], v[158:161], v[214:217], v[76:79]
	v_mfma_f32_16x16x32_bf16 v[72:75], v[166:169], v[214:217], v[72:75]
	s_setprio 0
	s_setprio 1
	v_mfma_f32_16x16x32_bf16 v[116:119], v[170:173], v[186:189], v[116:119]
	v_mfma_f32_16x16x32_bf16 v[112:115], v[178:181], v[186:189], v[112:115]
	v_mfma_f32_16x16x32_bf16 v[100:103], v[170:173], v[194:197], v[100:103]
	v_mfma_f32_16x16x32_bf16 v[96:99], v[178:181], v[194:197], v[96:99]
	v_mfma_f32_16x16x32_bf16 v[84:87], v[170:173], v[202:205], v[84:87]
	v_mfma_f32_16x16x32_bf16 v[80:83], v[178:181], v[202:205], v[80:83]
	v_mfma_f32_16x16x32_bf16 v[68:71], v[170:173], v[210:213], v[68:71]
	v_mfma_f32_16x16x32_bf16 v[64:67], v[178:181], v[210:213], v[64:67]
	v_mfma_f32_16x16x32_bf16 v[116:119], v[174:177], v[190:193], v[116:119]
	v_mfma_f32_16x16x32_bf16 v[112:115], v[182:185], v[190:193], v[112:115]
	v_mfma_f32_16x16x32_bf16 v[100:103], v[174:177], v[198:201], v[100:103]
	v_mfma_f32_16x16x32_bf16 v[96:99], v[182:185], v[198:201], v[96:99]
	v_mfma_f32_16x16x32_bf16 v[84:87], v[174:177], v[206:209], v[84:87]
	v_mfma_f32_16x16x32_bf16 v[80:83], v[182:185], v[206:209], v[80:83]
	v_mfma_f32_16x16x32_bf16 v[68:71], v[174:177], v[214:217], v[68:71]
	v_mfma_f32_16x16x32_bf16 v[64:67], v[182:185], v[214:217], v[64:67]
	s_setprio 0
	s_barrier
	s_add_i32 s34, s63, s47
	v_lshl_add_u64 v[218:219], v[218:219], 0, s[10:11]
	s_mov_b32 m0, s34
	ds_read_b128 v[186:189], v155 offset:49152
	ds_read_b128 v[190:193], v155 offset:50176
	ds_read_b128 v[194:197], v155 offset:51200
	ds_read_b128 v[198:201], v155 offset:52224
	ds_read_b128 v[202:205], v155 offset:53248
	ds_read_b128 v[206:209], v155 offset:54272
	ds_read_b128 v[210:213], v155 offset:55296
	ds_read_b128 v[214:217], v155 offset:56320
	global_load_lds_dwordx4 v[218:219], off
	s_add_i32 m0, s34, 0x2000
	s_add_u32 s34, s42, 0x40080
	v_lshl_add_u64 v[218:219], v[220:221], 0, s[10:11]
	s_addc_u32 s35, s43, 0
	s_add_i32 s42, s64, s47
	global_load_lds_dwordx4 v[218:219], off
	v_lshl_add_u64 v[218:219], s[34:35], 0, v[132:133]
	s_mov_b32 m0, s42
	s_nop 0
	global_load_lds_dwordx4 v[218:219], off
	v_lshl_add_u64 v[218:219], s[34:35], 0, v[136:137]
	s_add_i32 m0, s42, 0x2000
	s_nop 0
	global_load_lds_dwordx4 v[218:219], off
	v_lshl_add_u64 v[218:219], v[222:223], 0, s[10:11]
	s_mov_b32 m0, s53
	s_nop 0
	global_load_lds_dwordx4 v[218:219], off
	v_lshl_add_u64 v[218:219], v[224:225], 0, s[10:11]
	s_mov_b32 m0, s54
	s_nop 0
	global_load_lds_dwordx4 v[218:219], off
	s_waitcnt vmcnt(8)
	s_waitcnt lgkmcnt(0)
	s_barrier
	s_setprio 1
	s_waitcnt lgkmcnt(0)
	v_mfma_f32_16x16x32_bf16 v[60:63], v[146:149], v[186:189], v[60:63]
	v_mfma_f32_16x16x32_bf16 v[56:59], v[162:165], v[186:189], v[56:59]
	v_mfma_f32_16x16x32_bf16 v[44:47], v[146:149], v[194:197], v[44:47]
	v_mfma_f32_16x16x32_bf16 v[40:43], v[162:165], v[194:197], v[40:43]
	v_mfma_f32_16x16x32_bf16 v[28:31], v[146:149], v[202:205], v[28:31]
	v_mfma_f32_16x16x32_bf16 v[24:27], v[162:165], v[202:205], v[24:27]
	v_mfma_f32_16x16x32_bf16 v[12:15], v[146:149], v[210:213], v[12:15]
	v_mfma_f32_16x16x32_bf16 v[8:11], v[162:165], v[210:213], v[8:11]
	v_mfma_f32_16x16x32_bf16 v[60:63], v[158:161], v[190:193], v[60:63]
	v_mfma_f32_16x16x32_bf16 v[56:59], v[166:169], v[190:193], v[56:59]
	v_mfma_f32_16x16x32_bf16 v[44:47], v[158:161], v[198:201], v[44:47]
	v_mfma_f32_16x16x32_bf16 v[40:43], v[166:169], v[198:201], v[40:43]
	v_mfma_f32_16x16x32_bf16 v[28:31], v[158:161], v[206:209], v[28:31]
	v_mfma_f32_16x16x32_bf16 v[24:27], v[166:169], v[206:209], v[24:27]
	v_mfma_f32_16x16x32_bf16 v[12:15], v[158:161], v[214:217], v[12:15]
	v_mfma_f32_16x16x32_bf16 v[8:11], v[166:169], v[214:217], v[8:11]
	s_setprio 0
	s_setprio 1
	v_mfma_f32_16x16x32_bf16 v[52:55], v[170:173], v[186:189], v[52:55]
	v_mfma_f32_16x16x32_bf16 v[48:51], v[178:181], v[186:189], v[48:51]
	v_mfma_f32_16x16x32_bf16 v[36:39], v[170:173], v[194:197], v[36:39]
	v_mfma_f32_16x16x32_bf16 v[32:35], v[178:181], v[194:197], v[32:35]
	v_mfma_f32_16x16x32_bf16 v[20:23], v[170:173], v[202:205], v[20:23]
	v_mfma_f32_16x16x32_bf16 v[16:19], v[178:181], v[202:205], v[16:19]
	v_mfma_f32_16x16x32_bf16 v[4:7], v[170:173], v[210:213], v[4:7]
	v_mfma_f32_16x16x32_bf16 v[0:3], v[178:181], v[210:213], v[0:3]
	v_mfma_f32_16x16x32_bf16 v[52:55], v[174:177], v[190:193], v[52:55]
	v_mfma_f32_16x16x32_bf16 v[48:51], v[182:185], v[190:193], v[48:51]
	v_mfma_f32_16x16x32_bf16 v[36:39], v[174:177], v[198:201], v[36:39]
	v_mfma_f32_16x16x32_bf16 v[32:35], v[182:185], v[198:201], v[32:35]
	v_mfma_f32_16x16x32_bf16 v[20:23], v[174:177], v[206:209], v[20:23]
	v_mfma_f32_16x16x32_bf16 v[16:19], v[182:185], v[206:209], v[16:19]
	v_mfma_f32_16x16x32_bf16 v[4:7], v[174:177], v[214:217], v[4:7]
	v_mfma_f32_16x16x32_bf16 v[0:3], v[182:185], v[214:217], v[0:3]
	s_setprio 0
	s_barrier
	s_add_i32 s62, s62, 2
	s_add_u32 s40, s40, 0x100
	s_addc_u32 s41, s41, 0
	s_add_u32 s39, s39, 0x100
	s_addc_u32 s61, s61, 0

.LBB0_1646:
	s_ashr_i32 s23, s22, 31
	s_lshl_b64 s[26:27], s[22:23], 19
	s_add_u32 s26, s14, s26
	s_addc_u32 s27, s15, s27
	s_and_b64 s[28:29], s[4:5], exec
	s_cselect_b32 s23, s27, s37
	s_cselect_b32 s58, s26, s36
	s_ashr_i32 s11, s10, 31
	s_lshl_b64 s[28:29], s[10:11], 19
	s_add_u32 s28, s45, s28
	s_addc_u32 s29, s46, s29
	s_and_b64 s[34:35], s[4:5], exec
	s_cselect_b32 s11, s29, s39
	s_cselect_b32 s59, s28, s38
	s_add_u32 s36, s36, 0x40080
	s_addc_u32 s37, s37, 0
	s_add_u32 s60, s38, 0x100
	s_addc_u32 s61, s39, 0
	s_mov_b32 s62, -2
	s_cmp_lg_u32 s56, 1
	s_cselect_b32 s100, s99, 0
	s_cmp_lg_u32 s100, 0
	s_cbranch_scc0 .Lmy_nobar2_17
	s_barrier
.Lmy_nobar2_17:
	ds_read_b128 v[146:149], v154
	ds_read_b128 v[158:161], v154 offset:1024
	ds_read_b128 v[162:165], v154 offset:2048
	ds_read_b128 v[166:169], v154 offset:3072
	ds_read_b128 v[170:173], v155
	ds_read_b128 v[174:177], v155 offset:1024
	ds_read_b128 v[178:181], v155 offset:2048
	ds_read_b128 v[182:185], v155 offset:3072
	s_add_u32 s34, s36, 0xfffc0080
	s_addc_u32 s35, s37, -1
	s_cmp_eq_u32 s62, 12
	s_cselect_b32 s41, s23, s35
	s_cselect_b32 s40, s58, s34
	s_cselect_b32 s39, s11, s61
	s_cselect_b32 s38, s59, s60
	v_lshl_add_u64 v[218:219], s[36:37], 0, v[138:139]
	s_add_i32 m0, s31, 0xc000
	ds_read_b128 v[186:189], v157
	ds_read_b128 v[190:193], v157 offset:1024
	ds_read_b128 v[194:197], v157 offset:2048
	ds_read_b128 v[198:201], v157 offset:3072
	ds_read_b128 v[202:205], v157 offset:4096
	ds_read_b128 v[206:209], v157 offset:5120
	ds_read_b128 v[210:213], v157 offset:6144
	ds_read_b128 v[214:217], v157 offset:7168
	global_load_lds_dwordx4 v[218:219], off
	v_lshl_add_u64 v[218:219], s[36:37], 0, v[140:141]
	s_add_i32 m0, s31, 0xe000
	s_nop 0
	global_load_lds_dwordx4 v[218:219], off
	s_waitcnt vmcnt(8)
	s_waitcnt lgkmcnt(0)
	s_barrier
	s_setprio 1
	s_waitcnt lgkmcnt(0)
	v_mfma_f32_16x16x32_bf16 v[124:127], v[146:149], v[186:189], 0
	v_mfma_f32_16x16x32_bf16 v[120:123], v[162:165], v[186:189], 0
	v_mfma_f32_16x16x32_bf16 v[108:111], v[146:149], v[194:197], 0
	v_mfma_f32_16x16x32_bf16 v[104:107], v[162:165], v[194:197], 0
	v_mfma_f32_16x16x32_bf16 v[92:95], v[146:149], v[202:205], 0
	v_mfma_f32_16x16x32_bf16 v[88:91], v[162:165], v[202:205], 0
	v_mfma_f32_16x16x32_bf16 v[76:79], v[146:149], v[210:213], 0
	v_mfma_f32_16x16x32_bf16 v[72:75], v[162:165], v[210:213], 0
	v_mfma_f32_16x16x32_bf16 v[124:127], v[158:161], v[190:193], v[124:127]
	v_mfma_f32_16x16x32_bf16 v[120:123], v[166:169], v[190:193], v[120:123]
	v_mfma_f32_16x16x32_bf16 v[108:111], v[158:161], v[198:201], v[108:111]
	v_mfma_f32_16x16x32_bf16 v[104:107], v[166:169], v[198:201], v[104:107]
	v_mfma_f32_16x16x32_bf16 v[92:95], v[158:161], v[206:209], v[92:95]
	v_mfma_f32_16x16x32_bf16 v[88:91], v[166:169], v[206:209], v[88:91]
	v_mfma_f32_16x16x32_bf16 v[76:79], v[158:161], v[214:217], v[76:79]
	v_mfma_f32_16x16x32_bf16 v[72:75], v[166:169], v[214:217], v[72:75]
	s_setprio 0
	s_setprio 1
	v_mfma_f32_16x16x32_bf16 v[116:119], v[170:173], v[186:189], 0
	v_mfma_f32_16x16x32_bf16 v[112:115], v[178:181], v[186:189], 0
	v_mfma_f32_16x16x32_bf16 v[100:103], v[170:173], v[194:197], 0
	v_mfma_f32_16x16x32_bf16 v[96:99], v[178:181], v[194:197], 0
	v_mfma_f32_16x16x32_bf16 v[84:87], v[170:173], v[202:205], 0
	v_mfma_f32_16x16x32_bf16 v[80:83], v[178:181], v[202:205], 0
	v_mfma_f32_16x16x32_bf16 v[68:71], v[170:173], v[210:213], 0
	v_mfma_f32_16x16x32_bf16 v[64:67], v[178:181], v[210:213], 0
	v_mfma_f32_16x16x32_bf16 v[116:119], v[174:177], v[190:193], v[116:119]
	v_mfma_f32_16x16x32_bf16 v[112:115], v[182:185], v[190:193], v[112:115]
	v_mfma_f32_16x16x32_bf16 v[100:103], v[174:177], v[198:201], v[100:103]
	v_mfma_f32_16x16x32_bf16 v[96:99], v[182:185], v[198:201], v[96:99]
	v_mfma_f32_16x16x32_bf16 v[84:87], v[174:177], v[206:209], v[84:87]
	v_mfma_f32_16x16x32_bf16 v[80:83], v[182:185], v[206:209], v[80:83]
	v_mfma_f32_16x16x32_bf16 v[68:71], v[174:177], v[214:217], v[68:71]
	v_mfma_f32_16x16x32_bf16 v[64:67], v[182:185], v[214:217], v[64:67]
	s_setprio 0
	s_barrier
	s_add_i32 s34, s53, s44
	v_lshl_add_u64 v[218:219], s[38:39], 0, v[134:135]
	s_mov_b32 m0, s34
	ds_read_b128 v[186:189], v157 offset:16384
	ds_read_b128 v[190:193], v157 offset:17408
	ds_read_b128 v[194:197], v157 offset:18432
	ds_read_b128 v[198:201], v157 offset:19456
	ds_read_b128 v[202:205], v157 offset:20480
	ds_read_b128 v[206:209], v157 offset:21504
	ds_read_b128 v[210:213], v157 offset:22528
	ds_read_b128 v[214:217], v157 offset:23552
	global_load_lds_dwordx4 v[218:219], off
	s_add_i32 m0, s34, 0x2000
	s_add_u32 s34, s38, 0x40000
	v_lshl_add_u64 v[220:221], s[38:39], 0, v[130:131]
	s_addc_u32 s35, s39, 0
	s_add_i32 s63, s54, s44
	global_load_lds_dwordx4 v[220:221], off
	v_lshl_add_u64 v[222:223], s[34:35], 0, v[134:135]
	s_mov_b32 m0, s63
	v_lshl_add_u64 v[224:225], s[40:41], 0, v[132:133]
	global_load_lds_dwordx4 v[222:223], off
	v_lshl_add_u64 v[222:223], s[34:35], 0, v[130:131]
	s_add_i32 m0, s63, 0x2000
	s_nop 0
	global_load_lds_dwordx4 v[222:223], off
	v_lshl_add_u64 v[222:223], s[40:41], 0, v[136:137]
	s_mov_b32 m0, s31
	s_nop 0
	global_load_lds_dwordx4 v[222:223], off
	s_mov_b32 m0, s48
	s_nop 0
	global_load_lds_dwordx4 v[224:225], off
	s_waitcnt vmcnt(8)
	s_waitcnt lgkmcnt(0)
	s_barrier
	s_setprio 1
	s_waitcnt lgkmcnt(0)
	v_mfma_f32_16x16x32_bf16 v[60:63], v[146:149], v[186:189], 0
	v_mfma_f32_16x16x32_bf16 v[56:59], v[162:165], v[186:189], 0
	v_mfma_f32_16x16x32_bf16 v[44:47], v[146:149], v[194:197], 0
	v_mfma_f32_16x16x32_bf16 v[40:43], v[162:165], v[194:197], 0
	v_mfma_f32_16x16x32_bf16 v[28:31], v[146:149], v[202:205], 0
	v_mfma_f32_16x16x32_bf16 v[24:27], v[162:165], v[202:205], 0
	v_mfma_f32_16x16x32_bf16 v[12:15], v[146:149], v[210:213], 0
	v_mfma_f32_16x16x32_bf16 v[8:11], v[162:165], v[210:213], 0
	v_mfma_f32_16x16x32_bf16 v[60:63], v[158:161], v[190:193], v[60:63]
	v_mfma_f32_16x16x32_bf16 v[56:59], v[166:169], v[190:193], v[56:59]
	v_mfma_f32_16x16x32_bf16 v[44:47], v[158:161], v[198:201], v[44:47]
	v_mfma_f32_16x16x32_bf16 v[40:43], v[166:169], v[198:201], v[40:43]
	v_mfma_f32_16x16x32_bf16 v[28:31], v[158:161], v[206:209], v[28:31]
	v_mfma_f32_16x16x32_bf16 v[24:27], v[166:169], v[206:209], v[24:27]
	v_mfma_f32_16x16x32_bf16 v[12:15], v[158:161], v[214:217], v[12:15]
	v_mfma_f32_16x16x32_bf16 v[8:11], v[166:169], v[214:217], v[8:11]
	s_setprio 0
	s_setprio 1
	v_mfma_f32_16x16x32_bf16 v[52:55], v[170:173], v[186:189], 0
	v_mfma_f32_16x16x32_bf16 v[48:51], v[178:181], v[186:189], 0
	v_mfma_f32_16x16x32_bf16 v[36:39], v[170:173], v[194:197], 0
	v_mfma_f32_16x16x32_bf16 v[32:35], v[178:181], v[194:197], 0
	v_mfma_f32_16x16x32_bf16 v[20:23], v[170:173], v[202:205], 0
	v_mfma_f32_16x16x32_bf16 v[16:19], v[178:181], v[202:205], 0
	v_mfma_f32_16x16x32_bf16 v[4:7], v[170:173], v[210:213], 0
	v_mfma_f32_16x16x32_bf16 v[0:3], v[178:181], v[210:213], 0
	v_mfma_f32_16x16x32_bf16 v[52:55], v[174:177], v[190:193], v[52:55]
	v_mfma_f32_16x16x32_bf16 v[48:51], v[182:185], v[190:193], v[48:51]
	v_mfma_f32_16x16x32_bf16 v[36:39], v[174:177], v[198:201], v[36:39]
	v_mfma_f32_16x16x32_bf16 v[32:35], v[182:185], v[198:201], v[32:35]
	v_mfma_f32_16x16x32_bf16 v[20:23], v[174:177], v[206:209], v[20:23]
	v_mfma_f32_16x16x32_bf16 v[16:19], v[182:185], v[206:209], v[16:19]
	v_mfma_f32_16x16x32_bf16 v[4:7], v[174:177], v[214:217], v[4:7]
	v_mfma_f32_16x16x32_bf16 v[0:3], v[182:185], v[214:217], v[0:3]
	s_setprio 0
	s_barrier
	s_add_i32 s63, 0, 0x18000
	s_add_i32 s64, 0, 0x1c000
	v_add_u32_e32 v166, s63, v151
	v_add_u32_e32 v182, s64, v151
	ds_read_b128 v[146:149], v166
	ds_read_b128 v[158:161], v166 offset:1024
	ds_read_b128 v[162:165], v166 offset:2048
	ds_read_b128 v[166:169], v166 offset:3072
	ds_read_b128 v[170:173], v182
	ds_read_b128 v[174:177], v182 offset:1024
	ds_read_b128 v[178:181], v182 offset:2048
	ds_read_b128 v[182:185], v182 offset:3072
	s_add_u32 s34, s40, 0x40000
	s_addc_u32 s35, s41, 0
	s_mov_b32 m0, s49
	v_lshl_add_u64 v[226:227], s[34:35], 0, v[136:137]
	ds_read_b128 v[186:189], v157 offset:32768
	ds_read_b128 v[190:193], v157 offset:33792
	ds_read_b128 v[194:197], v157 offset:34816
	ds_read_b128 v[198:201], v157 offset:35840
	ds_read_b128 v[202:205], v157 offset:36864
	ds_read_b128 v[206:209], v157 offset:37888
	ds_read_b128 v[210:213], v157 offset:38912
	ds_read_b128 v[214:217], v157 offset:39936
	global_load_lds_dwordx4 v[226:227], off
	v_lshl_add_u64 v[226:227], s[34:35], 0, v[132:133]
	s_mov_b32 m0, s50
	s_nop 0
	global_load_lds_dwordx4 v[226:227], off
	s_waitcnt vmcnt(8)
	s_waitcnt lgkmcnt(0)
	s_barrier
	s_setprio 1
	s_waitcnt lgkmcnt(0)
	v_mfma_f32_16x16x32_bf16 v[124:127], v[146:149], v[186:189], v[124:127]
	v_mfma_f32_16x16x32_bf16 v[120:123], v[162:165], v[186:189], v[120:123]
	v_mfma_f32_16x16x32_bf16 v[108:111], v[146:149], v[194:197], v[108:111]
	v_mfma_f32_16x16x32_bf16 v[104:107], v[162:165], v[194:197], v[104:107]
	v_mfma_f32_16x16x32_bf16 v[92:95], v[146:149], v[202:205], v[92:95]
	v_mfma_f32_16x16x32_bf16 v[88:91], v[162:165], v[202:205], v[88:91]
	v_mfma_f32_16x16x32_bf16 v[76:79], v[146:149], v[210:213], v[76:79]
	v_mfma_f32_16x16x32_bf16 v[72:75], v[162:165], v[210:213], v[72:75]
	v_mfma_f32_16x16x32_bf16 v[124:127], v[158:161], v[190:193], v[124:127]
	v_mfma_f32_16x16x32_bf16 v[120:123], v[166:169], v[190:193], v[120:123]
	v_mfma_f32_16x16x32_bf16 v[108:111], v[158:161], v[198:201], v[108:111]
	v_mfma_f32_16x16x32_bf16 v[104:107], v[166:169], v[198:201], v[104:107]
	v_mfma_f32_16x16x32_bf16 v[92:95], v[158:161], v[206:209], v[92:95]
	v_mfma_f32_16x16x32_bf16 v[88:91], v[166:169], v[206:209], v[88:91]
	v_mfma_f32_16x16x32_bf16 v[76:79], v[158:161], v[214:217], v[76:79]
	v_mfma_f32_16x16x32_bf16 v[72:75], v[166:169], v[214:217], v[72:75]
	s_setprio 0
	s_setprio 1
	v_mfma_f32_16x16x32_bf16 v[116:119], v[170:173], v[186:189], v[116:119]
	v_mfma_f32_16x16x32_bf16 v[112:115], v[178:181], v[186:189], v[112:115]
	v_mfma_f32_16x16x32_bf16 v[100:103], v[170:173], v[194:197], v[100:103]
	v_mfma_f32_16x16x32_bf16 v[96:99], v[178:181], v[194:197], v[96:99]
	v_mfma_f32_16x16x32_bf16 v[84:87], v[170:173], v[202:205], v[84:87]
	v_mfma_f32_16x16x32_bf16 v[80:83], v[178:181], v[202:205], v[80:83]
	v_mfma_f32_16x16x32_bf16 v[68:71], v[170:173], v[210:213], v[68:71]
	v_mfma_f32_16x16x32_bf16 v[64:67], v[178:181], v[210:213], v[64:67]
	v_mfma_f32_16x16x32_bf16 v[116:119], v[174:177], v[190:193], v[116:119]
	v_mfma_f32_16x16x32_bf16 v[112:115], v[182:185], v[190:193], v[112:115]
	v_mfma_f32_16x16x32_bf16 v[100:103], v[174:177], v[198:201], v[100:103]
	v_mfma_f32_16x16x32_bf16 v[96:99], v[182:185], v[198:201], v[96:99]
	v_mfma_f32_16x16x32_bf16 v[84:87], v[174:177], v[206:209], v[84:87]
	v_mfma_f32_16x16x32_bf16 v[80:83], v[182:185], v[206:209], v[80:83]
	v_mfma_f32_16x16x32_bf16 v[68:71], v[174:177], v[214:217], v[68:71]
	v_mfma_f32_16x16x32_bf16 v[64:67], v[182:185], v[214:217], v[64:67]
	s_setprio 0
	s_barrier
	s_add_i32 s34, s63, s44
	v_lshl_add_u64 v[218:219], v[218:219], 0, s[6:7]
	s_mov_b32 m0, s34
	ds_read_b128 v[186:189], v157 offset:49152
	ds_read_b128 v[190:193], v157 offset:50176
	ds_read_b128 v[194:197], v157 offset:51200
	ds_read_b128 v[198:201], v157 offset:52224
	ds_read_b128 v[202:205], v157 offset:53248
	ds_read_b128 v[206:209], v157 offset:54272
	ds_read_b128 v[210:213], v157 offset:55296
	ds_read_b128 v[214:217], v157 offset:56320
	global_load_lds_dwordx4 v[218:219], off
	s_add_i32 m0, s34, 0x2000
	s_add_u32 s34, s38, 0x40080
	v_lshl_add_u64 v[218:219], v[220:221], 0, s[6:7]
	s_addc_u32 s35, s39, 0
	s_add_i32 s38, s64, s44
	global_load_lds_dwordx4 v[218:219], off
	v_lshl_add_u64 v[218:219], s[34:35], 0, v[134:135]
	s_mov_b32 m0, s38
	s_nop 0
	global_load_lds_dwordx4 v[218:219], off
	v_lshl_add_u64 v[218:219], s[34:35], 0, v[130:131]
	s_add_i32 m0, s38, 0x2000
	s_nop 0
	global_load_lds_dwordx4 v[218:219], off
	v_lshl_add_u64 v[218:219], v[222:223], 0, s[6:7]
	s_mov_b32 m0, s51
	s_nop 0
	global_load_lds_dwordx4 v[218:219], off
	v_lshl_add_u64 v[218:219], v[224:225], 0, s[6:7]
	s_mov_b32 m0, s52
	s_nop 0
	global_load_lds_dwordx4 v[218:219], off
	s_waitcnt vmcnt(8)
	s_waitcnt lgkmcnt(0)
	s_barrier
	s_setprio 1
	s_waitcnt lgkmcnt(0)
	v_mfma_f32_16x16x32_bf16 v[60:63], v[146:149], v[186:189], v[60:63]
	v_mfma_f32_16x16x32_bf16 v[56:59], v[162:165], v[186:189], v[56:59]
	v_mfma_f32_16x16x32_bf16 v[44:47], v[146:149], v[194:197], v[44:47]
	v_mfma_f32_16x16x32_bf16 v[40:43], v[162:165], v[194:197], v[40:43]
	v_mfma_f32_16x16x32_bf16 v[28:31], v[146:149], v[202:205], v[28:31]
	v_mfma_f32_16x16x32_bf16 v[24:27], v[162:165], v[202:205], v[24:27]
	v_mfma_f32_16x16x32_bf16 v[12:15], v[146:149], v[210:213], v[12:15]
	v_mfma_f32_16x16x32_bf16 v[8:11], v[162:165], v[210:213], v[8:11]
	v_mfma_f32_16x16x32_bf16 v[60:63], v[158:161], v[190:193], v[60:63]
	v_mfma_f32_16x16x32_bf16 v[56:59], v[166:169], v[190:193], v[56:59]
	v_mfma_f32_16x16x32_bf16 v[44:47], v[158:161], v[198:201], v[44:47]
	v_mfma_f32_16x16x32_bf16 v[40:43], v[166:169], v[198:201], v[40:43]
	v_mfma_f32_16x16x32_bf16 v[28:31], v[158:161], v[206:209], v[28:31]
	v_mfma_f32_16x16x32_bf16 v[24:27], v[166:169], v[206:209], v[24:27]
	v_mfma_f32_16x16x32_bf16 v[12:15], v[158:161], v[214:217], v[12:15]
	v_mfma_f32_16x16x32_bf16 v[8:11], v[166:169], v[214:217], v[8:11]
	s_setprio 0
	s_setprio 1
	v_mfma_f32_16x16x32_bf16 v[52:55], v[170:173], v[186:189], v[52:55]
	v_mfma_f32_16x16x32_bf16 v[48:51], v[178:181], v[186:189], v[48:51]
	v_mfma_f32_16x16x32_bf16 v[36:39], v[170:173], v[194:197], v[36:39]
	v_mfma_f32_16x16x32_bf16 v[32:35], v[178:181], v[194:197], v[32:35]
	v_mfma_f32_16x16x32_bf16 v[20:23], v[170:173], v[202:205], v[20:23]
	v_mfma_f32_16x16x32_bf16 v[16:19], v[178:181], v[202:205], v[16:19]
	v_mfma_f32_16x16x32_bf16 v[4:7], v[170:173], v[210:213], v[4:7]
	v_mfma_f32_16x16x32_bf16 v[0:3], v[178:181], v[210:213], v[0:3]
	v_mfma_f32_16x16x32_bf16 v[52:55], v[174:177], v[190:193], v[52:55]
	v_mfma_f32_16x16x32_bf16 v[48:51], v[182:185], v[190:193], v[48:51]
	v_mfma_f32_16x16x32_bf16 v[36:39], v[174:177], v[198:201], v[36:39]
	v_mfma_f32_16x16x32_bf16 v[32:35], v[182:185], v[198:201], v[32:35]
	v_mfma_f32_16x16x32_bf16 v[20:23], v[174:177], v[206:209], v[20:23]
	v_mfma_f32_16x16x32_bf16 v[16:19], v[182:185], v[206:209], v[16:19]
	v_mfma_f32_16x16x32_bf16 v[4:7], v[174:177], v[214:217], v[4:7]
	v_mfma_f32_16x16x32_bf16 v[0:3], v[182:185], v[214:217], v[0:3]
	s_setprio 0
	s_barrier
	s_add_i32 s62, s62, 2
	s_add_u32 s36, s36, 0x100
	s_addc_u32 s37, s37, 0
	s_add_u32 s60, s60, 0x100
	s_addc_u32 s61, s61, 0

.LBB0_1732:
	s_add_u32 s30, s30, 0xb0080
	s_addc_u32 s31, s31, 0
	s_add_u32 s13, s36, 0x100
	s_addc_u32 s57, s37, 0
	s_mov_b32 s58, -2
	s_waitcnt lgkmcnt(0)
	s_cmp_lg_u32 s54, 1
	s_cselect_b32 s100, s99, 0
	s_cmp_lg_u32 s100, 0
	s_cbranch_scc0 .Lmy_nobar2_18
	s_barrier
.Lmy_nobar2_18:
	ds_read_b128 v[146:149], v153
	ds_read_b128 v[158:161], v153 offset:1024
	ds_read_b128 v[162:165], v153 offset:2048
	ds_read_b128 v[166:169], v153 offset:3072
	ds_read_b128 v[170:173], v154
	ds_read_b128 v[174:177], v154 offset:1024
	ds_read_b128 v[178:181], v154 offset:2048
	ds_read_b128 v[182:185], v154 offset:3072
	s_add_u32 s34, s30, 0xfff50080
	s_addc_u32 s35, s31, -1
	s_cmp_eq_u32 s58, 40
	s_cselect_b32 s39, s1, s35
	s_cselect_b32 s38, s0, s34
	s_cselect_b32 s37, s29, s57
	s_cselect_b32 s36, s28, s13
	v_lshl_add_u64 v[218:219], s[30:31], 0, v[138:139]
	s_add_i32 m0, s42, 0xc000
	ds_read_b128 v[186:189], v155
	ds_read_b128 v[190:193], v155 offset:1024
	ds_read_b128 v[194:197], v155 offset:2048
	ds_read_b128 v[198:201], v155 offset:3072
	ds_read_b128 v[202:205], v155 offset:4096
	ds_read_b128 v[206:209], v155 offset:5120
	ds_read_b128 v[210:213], v155 offset:6144
	ds_read_b128 v[214:217], v155 offset:7168
	global_load_lds_dwordx4 v[218:219], off
	v_lshl_add_u64 v[218:219], s[30:31], 0, v[140:141]
	s_add_i32 m0, s42, 0xe000
	s_nop 0
	global_load_lds_dwordx4 v[218:219], off
	s_waitcnt vmcnt(8)
	s_waitcnt lgkmcnt(0)
	s_barrier
	s_setprio 1
	s_waitcnt lgkmcnt(0)
	v_mfma_f32_16x16x32_bf16 v[124:127], v[146:149], v[186:189], 0
	v_mfma_f32_16x16x32_bf16 v[120:123], v[162:165], v[186:189], 0
	v_mfma_f32_16x16x32_bf16 v[108:111], v[146:149], v[194:197], 0
	v_mfma_f32_16x16x32_bf16 v[104:107], v[162:165], v[194:197], 0
	v_mfma_f32_16x16x32_bf16 v[92:95], v[146:149], v[202:205], 0
	v_mfma_f32_16x16x32_bf16 v[88:91], v[162:165], v[202:205], 0
	v_mfma_f32_16x16x32_bf16 v[76:79], v[146:149], v[210:213], 0
	v_mfma_f32_16x16x32_bf16 v[72:75], v[162:165], v[210:213], 0
	v_mfma_f32_16x16x32_bf16 v[124:127], v[158:161], v[190:193], v[124:127]
	v_mfma_f32_16x16x32_bf16 v[120:123], v[166:169], v[190:193], v[120:123]
	v_mfma_f32_16x16x32_bf16 v[108:111], v[158:161], v[198:201], v[108:111]
	v_mfma_f32_16x16x32_bf16 v[104:107], v[166:169], v[198:201], v[104:107]
	v_mfma_f32_16x16x32_bf16 v[92:95], v[158:161], v[206:209], v[92:95]
	v_mfma_f32_16x16x32_bf16 v[88:91], v[166:169], v[206:209], v[88:91]
	v_mfma_f32_16x16x32_bf16 v[76:79], v[158:161], v[214:217], v[76:79]
	v_mfma_f32_16x16x32_bf16 v[72:75], v[166:169], v[214:217], v[72:75]
	s_setprio 0
	s_setprio 1
	v_mfma_f32_16x16x32_bf16 v[116:119], v[170:173], v[186:189], 0
	v_mfma_f32_16x16x32_bf16 v[112:115], v[178:181], v[186:189], 0
	v_mfma_f32_16x16x32_bf16 v[100:103], v[170:173], v[194:197], 0
	v_mfma_f32_16x16x32_bf16 v[96:99], v[178:181], v[194:197], 0
	v_mfma_f32_16x16x32_bf16 v[84:87], v[170:173], v[202:205], 0
	v_mfma_f32_16x16x32_bf16 v[80:83], v[178:181], v[202:205], 0
	v_mfma_f32_16x16x32_bf16 v[68:71], v[170:173], v[210:213], 0
	v_mfma_f32_16x16x32_bf16 v[64:67], v[178:181], v[210:213], 0
	v_mfma_f32_16x16x32_bf16 v[116:119], v[174:177], v[190:193], v[116:119]
	v_mfma_f32_16x16x32_bf16 v[112:115], v[182:185], v[190:193], v[112:115]
	v_mfma_f32_16x16x32_bf16 v[100:103], v[174:177], v[198:201], v[100:103]
	v_mfma_f32_16x16x32_bf16 v[96:99], v[182:185], v[198:201], v[96:99]
	v_mfma_f32_16x16x32_bf16 v[84:87], v[174:177], v[206:209], v[84:87]
	v_mfma_f32_16x16x32_bf16 v[80:83], v[182:185], v[206:209], v[80:83]
	v_mfma_f32_16x16x32_bf16 v[68:71], v[174:177], v[214:217], v[68:71]
	v_mfma_f32_16x16x32_bf16 v[64:67], v[182:185], v[214:217], v[64:67]
	s_setprio 0
	s_barrier
	s_add_i32 s34, s52, s41
	v_lshl_add_u64 v[218:219], s[36:37], 0, v[132:133]
	s_mov_b32 m0, s34
	ds_read_b128 v[186:189], v155 offset:16384
	ds_read_b128 v[190:193], v155 offset:17408
	ds_read_b128 v[194:197], v155 offset:18432
	ds_read_b128 v[198:201], v155 offset:19456
	ds_read_b128 v[202:205], v155 offset:20480
	ds_read_b128 v[206:209], v155 offset:21504
	ds_read_b128 v[210:213], v155 offset:22528
	ds_read_b128 v[214:217], v155 offset:23552
	global_load_lds_dwordx4 v[218:219], off
	s_add_i32 m0, s34, 0x2000
	s_add_u32 s34, s36, 0xb0000
	v_lshl_add_u64 v[220:221], s[36:37], 0, v[136:137]
	s_addc_u32 s35, s37, 0
	s_add_i32 s59, s53, s41
	global_load_lds_dwordx4 v[220:221], off
	v_lshl_add_u64 v[222:223], s[34:35], 0, v[132:133]
	s_mov_b32 m0, s59
	v_lshl_add_u64 v[224:225], s[38:39], 0, v[134:135]
	global_load_lds_dwordx4 v[222:223], off
	v_lshl_add_u64 v[222:223], s[34:35], 0, v[136:137]
	s_add_i32 m0, s59, 0x2000
	s_nop 0
	global_load_lds_dwordx4 v[222:223], off
	v_lshl_add_u64 v[222:223], s[38:39], 0, v[130:131]
	s_mov_b32 m0, s42
	s_nop 0
	global_load_lds_dwordx4 v[222:223], off
	s_mov_b32 m0, s43
	s_nop 0
	global_load_lds_dwordx4 v[224:225], off
	s_waitcnt vmcnt(8)
	s_waitcnt lgkmcnt(0)
	s_barrier
	s_setprio 1
	s_waitcnt lgkmcnt(0)
	v_mfma_f32_16x16x32_bf16 v[60:63], v[146:149], v[186:189], 0
	v_mfma_f32_16x16x32_bf16 v[56:59], v[162:165], v[186:189], 0
	v_mfma_f32_16x16x32_bf16 v[44:47], v[146:149], v[194:197], 0
	v_mfma_f32_16x16x32_bf16 v[40:43], v[162:165], v[194:197], 0
	v_mfma_f32_16x16x32_bf16 v[28:31], v[146:149], v[202:205], 0
	v_mfma_f32_16x16x32_bf16 v[24:27], v[162:165], v[202:205], 0
	v_mfma_f32_16x16x32_bf16 v[12:15], v[146:149], v[210:213], 0
	v_mfma_f32_16x16x32_bf16 v[8:11], v[162:165], v[210:213], 0
	v_mfma_f32_16x16x32_bf16 v[60:63], v[158:161], v[190:193], v[60:63]
	v_mfma_f32_16x16x32_bf16 v[56:59], v[166:169], v[190:193], v[56:59]
	v_mfma_f32_16x16x32_bf16 v[44:47], v[158:161], v[198:201], v[44:47]
	v_mfma_f32_16x16x32_bf16 v[40:43], v[166:169], v[198:201], v[40:43]
	v_mfma_f32_16x16x32_bf16 v[28:31], v[158:161], v[206:209], v[28:31]
	v_mfma_f32_16x16x32_bf16 v[24:27], v[166:169], v[206:209], v[24:27]
	v_mfma_f32_16x16x32_bf16 v[12:15], v[158:161], v[214:217], v[12:15]
	v_mfma_f32_16x16x32_bf16 v[8:11], v[166:169], v[214:217], v[8:11]
	s_setprio 0
	s_setprio 1
	v_mfma_f32_16x16x32_bf16 v[52:55], v[170:173], v[186:189], 0
	v_mfma_f32_16x16x32_bf16 v[48:51], v[178:181], v[186:189], 0
	v_mfma_f32_16x16x32_bf16 v[36:39], v[170:173], v[194:197], 0
	v_mfma_f32_16x16x32_bf16 v[32:35], v[178:181], v[194:197], 0
	v_mfma_f32_16x16x32_bf16 v[20:23], v[170:173], v[202:205], 0
	v_mfma_f32_16x16x32_bf16 v[16:19], v[178:181], v[202:205], 0
	v_mfma_f32_16x16x32_bf16 v[4:7], v[170:173], v[210:213], 0
	v_mfma_f32_16x16x32_bf16 v[0:3], v[178:181], v[210:213], 0
	v_mfma_f32_16x16x32_bf16 v[52:55], v[174:177], v[190:193], v[52:55]
	v_mfma_f32_16x16x32_bf16 v[48:51], v[182:185], v[190:193], v[48:51]
	v_mfma_f32_16x16x32_bf16 v[36:39], v[174:177], v[198:201], v[36:39]
	v_mfma_f32_16x16x32_bf16 v[32:35], v[182:185], v[198:201], v[32:35]
	v_mfma_f32_16x16x32_bf16 v[20:23], v[174:177], v[206:209], v[20:23]
	v_mfma_f32_16x16x32_bf16 v[16:19], v[182:185], v[206:209], v[16:19]
	v_mfma_f32_16x16x32_bf16 v[4:7], v[174:177], v[214:217], v[4:7]
	v_mfma_f32_16x16x32_bf16 v[0:3], v[182:185], v[214:217], v[0:3]
	s_setprio 0
	s_barrier
	s_add_i32 s59, 0, 0x18000
	s_add_i32 s60, 0, 0x1c000
	v_add_u32_e32 v166, s59, v151
	v_add_u32_e32 v182, s60, v151
	ds_read_b128 v[146:149], v166
	ds_read_b128 v[158:161], v166 offset:1024
	ds_read_b128 v[162:165], v166 offset:2048
	ds_read_b128 v[166:169], v166 offset:3072
	ds_read_b128 v[170:173], v182
	ds_read_b128 v[174:177], v182 offset:1024
	ds_read_b128 v[178:181], v182 offset:2048
	ds_read_b128 v[182:185], v182 offset:3072
	s_add_u32 s34, s38, 0xb0000
	s_addc_u32 s35, s39, 0
	s_mov_b32 m0, s44
	v_lshl_add_u64 v[226:227], s[34:35], 0, v[130:131]
	ds_read_b128 v[186:189], v155 offset:32768
	ds_read_b128 v[190:193], v155 offset:33792
	ds_read_b128 v[194:197], v155 offset:34816
	ds_read_b128 v[198:201], v155 offset:35840
	ds_read_b128 v[202:205], v155 offset:36864
	ds_read_b128 v[206:209], v155 offset:37888
	ds_read_b128 v[210:213], v155 offset:38912
	ds_read_b128 v[214:217], v155 offset:39936
	global_load_lds_dwordx4 v[226:227], off
	v_lshl_add_u64 v[226:227], s[34:35], 0, v[134:135]
	s_mov_b32 m0, s45
	s_nop 0
	global_load_lds_dwordx4 v[226:227], off
	s_waitcnt vmcnt(8)
	s_waitcnt lgkmcnt(0)
	s_barrier
	s_setprio 1
	s_waitcnt lgkmcnt(0)
	v_mfma_f32_16x16x32_bf16 v[124:127], v[146:149], v[186:189], v[124:127]
	v_mfma_f32_16x16x32_bf16 v[120:123], v[162:165], v[186:189], v[120:123]
	v_mfma_f32_16x16x32_bf16 v[108:111], v[146:149], v[194:197], v[108:111]
	v_mfma_f32_16x16x32_bf16 v[104:107], v[162:165], v[194:197], v[104:107]
	v_mfma_f32_16x16x32_bf16 v[92:95], v[146:149], v[202:205], v[92:95]
	v_mfma_f32_16x16x32_bf16 v[88:91], v[162:165], v[202:205], v[88:91]
	v_mfma_f32_16x16x32_bf16 v[76:79], v[146:149], v[210:213], v[76:79]
	v_mfma_f32_16x16x32_bf16 v[72:75], v[162:165], v[210:213], v[72:75]
	v_mfma_f32_16x16x32_bf16 v[124:127], v[158:161], v[190:193], v[124:127]
	v_mfma_f32_16x16x32_bf16 v[120:123], v[166:169], v[190:193], v[120:123]
	v_mfma_f32_16x16x32_bf16 v[108:111], v[158:161], v[198:201], v[108:111]
	v_mfma_f32_16x16x32_bf16 v[104:107], v[166:169], v[198:201], v[104:107]
	v_mfma_f32_16x16x32_bf16 v[92:95], v[158:161], v[206:209], v[92:95]
	v_mfma_f32_16x16x32_bf16 v[88:91], v[166:169], v[206:209], v[88:91]
	v_mfma_f32_16x16x32_bf16 v[76:79], v[158:161], v[214:217], v[76:79]
	v_mfma_f32_16x16x32_bf16 v[72:75], v[166:169], v[214:217], v[72:75]
	s_setprio 0
	s_setprio 1
	v_mfma_f32_16x16x32_bf16 v[116:119], v[170:173], v[186:189], v[116:119]
	v_mfma_f32_16x16x32_bf16 v[112:115], v[178:181], v[186:189], v[112:115]
	v_mfma_f32_16x16x32_bf16 v[100:103], v[170:173], v[194:197], v[100:103]
	v_mfma_f32_16x16x32_bf16 v[96:99], v[178:181], v[194:197], v[96:99]
	v_mfma_f32_16x16x32_bf16 v[84:87], v[170:173], v[202:205], v[84:87]
	v_mfma_f32_16x16x32_bf16 v[80:83], v[178:181], v[202:205], v[80:83]
	v_mfma_f32_16x16x32_bf16 v[68:71], v[170:173], v[210:213], v[68:71]
	v_mfma_f32_16x16x32_bf16 v[64:67], v[178:181], v[210:213], v[64:67]
	v_mfma_f32_16x16x32_bf16 v[116:119], v[174:177], v[190:193], v[116:119]
	v_mfma_f32_16x16x32_bf16 v[112:115], v[182:185], v[190:193], v[112:115]
	v_mfma_f32_16x16x32_bf16 v[100:103], v[174:177], v[198:201], v[100:103]
	v_mfma_f32_16x16x32_bf16 v[96:99], v[182:185], v[198:201], v[96:99]
	v_mfma_f32_16x16x32_bf16 v[84:87], v[174:177], v[206:209], v[84:87]
	v_mfma_f32_16x16x32_bf16 v[80:83], v[182:185], v[206:209], v[80:83]
	v_mfma_f32_16x16x32_bf16 v[68:71], v[174:177], v[214:217], v[68:71]
	v_mfma_f32_16x16x32_bf16 v[64:67], v[182:185], v[214:217], v[64:67]
	s_setprio 0
	s_barrier
	s_add_i32 s34, s59, s41
	v_lshl_add_u64 v[218:219], v[218:219], 0, s[22:23]
	s_mov_b32 m0, s34
	ds_read_b128 v[186:189], v155 offset:49152
	ds_read_b128 v[190:193], v155 offset:50176
	ds_read_b128 v[194:197], v155 offset:51200
	ds_read_b128 v[198:201], v155 offset:52224
	ds_read_b128 v[202:205], v155 offset:53248
	ds_read_b128 v[206:209], v155 offset:54272
	ds_read_b128 v[210:213], v155 offset:55296
	ds_read_b128 v[214:217], v155 offset:56320
	global_load_lds_dwordx4 v[218:219], off
	s_add_i32 m0, s34, 0x2000
	s_add_u32 s34, s36, 0xb0080
	v_lshl_add_u64 v[218:219], v[220:221], 0, s[22:23]
	s_addc_u32 s35, s37, 0
	s_add_i32 s36, s60, s41
	global_load_lds_dwordx4 v[218:219], off
	v_lshl_add_u64 v[218:219], s[34:35], 0, v[132:133]
	s_mov_b32 m0, s36
	s_nop 0
	global_load_lds_dwordx4 v[218:219], off
	v_lshl_add_u64 v[218:219], s[34:35], 0, v[136:137]
	s_add_i32 m0, s36, 0x2000
	s_nop 0
	global_load_lds_dwordx4 v[218:219], off
	v_lshl_add_u64 v[218:219], v[222:223], 0, s[22:23]
	s_mov_b32 m0, s47
	s_nop 0
	global_load_lds_dwordx4 v[218:219], off
	v_lshl_add_u64 v[218:219], v[224:225], 0, s[22:23]
	s_mov_b32 m0, s48
	s_nop 0
	global_load_lds_dwordx4 v[218:219], off
	s_waitcnt vmcnt(8)
	s_waitcnt lgkmcnt(0)
	s_barrier
	s_setprio 1
	s_waitcnt lgkmcnt(0)
	v_mfma_f32_16x16x32_bf16 v[60:63], v[146:149], v[186:189], v[60:63]
	v_mfma_f32_16x16x32_bf16 v[56:59], v[162:165], v[186:189], v[56:59]
	v_mfma_f32_16x16x32_bf16 v[44:47], v[146:149], v[194:197], v[44:47]
	v_mfma_f32_16x16x32_bf16 v[40:43], v[162:165], v[194:197], v[40:43]
	v_mfma_f32_16x16x32_bf16 v[28:31], v[146:149], v[202:205], v[28:31]
	v_mfma_f32_16x16x32_bf16 v[24:27], v[162:165], v[202:205], v[24:27]
	v_mfma_f32_16x16x32_bf16 v[12:15], v[146:149], v[210:213], v[12:15]
	v_mfma_f32_16x16x32_bf16 v[8:11], v[162:165], v[210:213], v[8:11]
	v_mfma_f32_16x16x32_bf16 v[60:63], v[158:161], v[190:193], v[60:63]
	v_mfma_f32_16x16x32_bf16 v[56:59], v[166:169], v[190:193], v[56:59]
	v_mfma_f32_16x16x32_bf16 v[44:47], v[158:161], v[198:201], v[44:47]
	v_mfma_f32_16x16x32_bf16 v[40:43], v[166:169], v[198:201], v[40:43]
	v_mfma_f32_16x16x32_bf16 v[28:31], v[158:161], v[206:209], v[28:31]
	v_mfma_f32_16x16x32_bf16 v[24:27], v[166:169], v[206:209], v[24:27]
	v_mfma_f32_16x16x32_bf16 v[12:15], v[158:161], v[214:217], v[12:15]
	v_mfma_f32_16x16x32_bf16 v[8:11], v[166:169], v[214:217], v[8:11]
	s_setprio 0
	s_setprio 1
	v_mfma_f32_16x16x32_bf16 v[52:55], v[170:173], v[186:189], v[52:55]
	v_mfma_f32_16x16x32_bf16 v[48:51], v[178:181], v[186:189], v[48:51]
	v_mfma_f32_16x16x32_bf16 v[36:39], v[170:173], v[194:197], v[36:39]
	v_mfma_f32_16x16x32_bf16 v[32:35], v[178:181], v[194:197], v[32:35]
	v_mfma_f32_16x16x32_bf16 v[20:23], v[170:173], v[202:205], v[20:23]
	v_mfma_f32_16x16x32_bf16 v[16:19], v[178:181], v[202:205], v[16:19]
	v_mfma_f32_16x16x32_bf16 v[4:7], v[170:173], v[210:213], v[4:7]
	v_mfma_f32_16x16x32_bf16 v[0:3], v[178:181], v[210:213], v[0:3]
	v_mfma_f32_16x16x32_bf16 v[52:55], v[174:177], v[190:193], v[52:55]
	v_mfma_f32_16x16x32_bf16 v[48:51], v[182:185], v[190:193], v[48:51]
	v_mfma_f32_16x16x32_bf16 v[36:39], v[174:177], v[198:201], v[36:39]
	v_mfma_f32_16x16x32_bf16 v[32:35], v[182:185], v[198:201], v[32:35]
	v_mfma_f32_16x16x32_bf16 v[20:23], v[174:177], v[206:209], v[20:23]
	v_mfma_f32_16x16x32_bf16 v[16:19], v[182:185], v[206:209], v[16:19]
	v_mfma_f32_16x16x32_bf16 v[4:7], v[174:177], v[214:217], v[4:7]
	v_mfma_f32_16x16x32_bf16 v[0:3], v[182:185], v[214:217], v[0:3]
	s_setprio 0
	s_barrier
	s_add_i32 s58, s58, 2
	s_add_u32 s30, s30, 0x100
	s_addc_u32 s31, s31, 0
	s_add_u32 s13, s13, 0x100
	s_addc_u32 s57, s57, 0

.LBB0_1825:
	s_ashr_i32 s37, s36, 31
	s_lshl_b64 s[12:13], s[36:37], 19
	s_add_u32 s38, s14, s12
	s_addc_u32 s39, s15, s13
	s_and_b64 s[12:13], s[4:5], exec
	s_cselect_b32 s7, s39, s43
	s_cselect_b32 s8, s38, s42
	s_ashr_i32 s31, s30, 31
	s_lshl_b64 s[12:13], s[30:31], 19
	s_add_u32 s40, s51, s12
	s_addc_u32 s41, s52, s13
	s_and_b64 s[12:13], s[4:5], exec
	s_cselect_b32 s12, s41, s45
	s_cselect_b32 s13, s40, s44
	s_add_u32 s42, s42, 0x40080
	s_addc_u32 s43, s43, 0
	s_add_u32 s31, s44, 0x100
	s_addc_u32 s37, s45, 0
	s_mov_b32 s65, -2
	s_waitcnt lgkmcnt(0)
	s_cmp_lg_u32 s63, 1
	s_cselect_b32 s100, s99, 0
	s_cmp_lg_u32 s100, 0
	s_cbranch_scc0 .Lmy_nobar2_19
	s_barrier
.Lmy_nobar2_19:
	ds_read_b128 v[150:153], v157
	ds_read_b128 v[160:163], v157 offset:1024
	ds_read_b128 v[164:167], v157 offset:2048
	ds_read_b128 v[168:171], v157 offset:3072
	ds_read_b128 v[172:175], v158
	ds_read_b128 v[176:179], v158 offset:1024
	ds_read_b128 v[180:183], v158 offset:2048
	ds_read_b128 v[184:187], v158 offset:3072
	s_add_u32 s34, s42, 0xfffc0080
	s_addc_u32 s35, s43, -1
	s_cmp_eq_u32 s65, 12
	s_cselect_b32 s47, s7, s35
	s_cselect_b32 s46, s8, s34
	s_cselect_b32 s45, s12, s37
	s_cselect_b32 s44, s13, s31
	v_lshl_add_u64 v[220:221], s[42:43], 0, v[142:143]
	s_add_i32 m0, s53, 0xc000
	ds_read_b128 v[188:191], v159
	ds_read_b128 v[192:195], v159 offset:1024
	ds_read_b128 v[196:199], v159 offset:2048
	ds_read_b128 v[200:203], v159 offset:3072
	ds_read_b128 v[204:207], v159 offset:4096
	ds_read_b128 v[208:211], v159 offset:5120
	ds_read_b128 v[212:215], v159 offset:6144
	ds_read_b128 v[216:219], v159 offset:7168
	global_load_lds_dwordx4 v[220:221], off
	v_lshl_add_u64 v[220:221], s[42:43], 0, v[144:145]
	s_add_i32 m0, s53, 0xe000
	s_nop 0
	global_load_lds_dwordx4 v[220:221], off
	s_waitcnt vmcnt(8)
	s_waitcnt lgkmcnt(0)
	s_barrier
	s_setprio 1
	s_waitcnt lgkmcnt(0)
	v_mfma_f32_16x16x32_bf16 v[124:127], v[150:153], v[188:191], 0
	v_mfma_f32_16x16x32_bf16 v[120:123], v[164:167], v[188:191], 0
	v_mfma_f32_16x16x32_bf16 v[108:111], v[150:153], v[196:199], 0
	v_mfma_f32_16x16x32_bf16 v[104:107], v[164:167], v[196:199], 0
	v_mfma_f32_16x16x32_bf16 v[92:95], v[150:153], v[204:207], 0
	v_mfma_f32_16x16x32_bf16 v[88:91], v[164:167], v[204:207], 0
	v_mfma_f32_16x16x32_bf16 v[76:79], v[150:153], v[212:215], 0
	v_mfma_f32_16x16x32_bf16 v[72:75], v[164:167], v[212:215], 0
	v_mfma_f32_16x16x32_bf16 v[124:127], v[160:163], v[192:195], v[124:127]
	v_mfma_f32_16x16x32_bf16 v[120:123], v[168:171], v[192:195], v[120:123]
	v_mfma_f32_16x16x32_bf16 v[108:111], v[160:163], v[200:203], v[108:111]
	v_mfma_f32_16x16x32_bf16 v[104:107], v[168:171], v[200:203], v[104:107]
	v_mfma_f32_16x16x32_bf16 v[92:95], v[160:163], v[208:211], v[92:95]
	v_mfma_f32_16x16x32_bf16 v[88:91], v[168:171], v[208:211], v[88:91]
	v_mfma_f32_16x16x32_bf16 v[76:79], v[160:163], v[216:219], v[76:79]
	v_mfma_f32_16x16x32_bf16 v[72:75], v[168:171], v[216:219], v[72:75]
	s_setprio 0
	s_setprio 1
	v_mfma_f32_16x16x32_bf16 v[116:119], v[172:175], v[188:191], 0
	v_mfma_f32_16x16x32_bf16 v[112:115], v[180:183], v[188:191], 0
	v_mfma_f32_16x16x32_bf16 v[100:103], v[172:175], v[196:199], 0
	v_mfma_f32_16x16x32_bf16 v[96:99], v[180:183], v[196:199], 0
	v_mfma_f32_16x16x32_bf16 v[84:87], v[172:175], v[204:207], 0
	v_mfma_f32_16x16x32_bf16 v[80:83], v[180:183], v[204:207], 0
	v_mfma_f32_16x16x32_bf16 v[68:71], v[172:175], v[212:215], 0
	v_mfma_f32_16x16x32_bf16 v[64:67], v[180:183], v[212:215], 0
	v_mfma_f32_16x16x32_bf16 v[116:119], v[176:179], v[192:195], v[116:119]
	v_mfma_f32_16x16x32_bf16 v[112:115], v[184:187], v[192:195], v[112:115]
	v_mfma_f32_16x16x32_bf16 v[100:103], v[176:179], v[200:203], v[100:103]
	v_mfma_f32_16x16x32_bf16 v[96:99], v[184:187], v[200:203], v[96:99]
	v_mfma_f32_16x16x32_bf16 v[84:87], v[176:179], v[208:211], v[84:87]
	v_mfma_f32_16x16x32_bf16 v[80:83], v[184:187], v[208:211], v[80:83]
	v_mfma_f32_16x16x32_bf16 v[68:71], v[176:179], v[216:219], v[68:71]
	v_mfma_f32_16x16x32_bf16 v[64:67], v[184:187], v[216:219], v[64:67]
	s_setprio 0
	s_barrier
	s_add_i32 s34, s61, s50
	v_lshl_add_u64 v[220:221], s[44:45], 0, v[134:135]
	s_mov_b32 m0, s34
	ds_read_b128 v[188:191], v159 offset:16384
	ds_read_b128 v[192:195], v159 offset:17408
	ds_read_b128 v[196:199], v159 offset:18432
	ds_read_b128 v[200:203], v159 offset:19456
	ds_read_b128 v[204:207], v159 offset:20480
	ds_read_b128 v[208:211], v159 offset:21504
	ds_read_b128 v[212:215], v159 offset:22528
	ds_read_b128 v[216:219], v159 offset:23552
	global_load_lds_dwordx4 v[220:221], off
	s_add_i32 m0, s34, 0x2000
	s_add_u32 s34, s44, 0x40000
	v_lshl_add_u64 v[222:223], s[44:45], 0, v[138:139]
	s_addc_u32 s35, s45, 0
	s_add_i32 s66, s62, s50
	global_load_lds_dwordx4 v[222:223], off
	v_lshl_add_u64 v[224:225], s[34:35], 0, v[134:135]
	s_mov_b32 m0, s66
	v_lshl_add_u64 v[226:227], s[46:47], 0, v[136:137]
	global_load_lds_dwordx4 v[224:225], off
	v_lshl_add_u64 v[224:225], s[34:35], 0, v[138:139]
	s_add_i32 m0, s66, 0x2000
	s_nop 0
	global_load_lds_dwordx4 v[224:225], off
	v_lshl_add_u64 v[224:225], s[46:47], 0, v[132:133]
	s_mov_b32 m0, s53
	s_nop 0
	global_load_lds_dwordx4 v[224:225], off
	s_mov_b32 m0, s54
	s_nop 0
	global_load_lds_dwordx4 v[226:227], off
	s_waitcnt vmcnt(8)
	s_waitcnt lgkmcnt(0)
	s_barrier
	s_setprio 1
	s_waitcnt lgkmcnt(0)
	v_mfma_f32_16x16x32_bf16 v[60:63], v[150:153], v[188:191], 0
	v_mfma_f32_16x16x32_bf16 v[56:59], v[164:167], v[188:191], 0
	v_mfma_f32_16x16x32_bf16 v[44:47], v[150:153], v[196:199], 0
	v_mfma_f32_16x16x32_bf16 v[40:43], v[164:167], v[196:199], 0
	v_mfma_f32_16x16x32_bf16 v[28:31], v[150:153], v[204:207], 0
	v_mfma_f32_16x16x32_bf16 v[24:27], v[164:167], v[204:207], 0
	v_mfma_f32_16x16x32_bf16 v[12:15], v[150:153], v[212:215], 0
	v_mfma_f32_16x16x32_bf16 v[8:11], v[164:167], v[212:215], 0
	v_mfma_f32_16x16x32_bf16 v[60:63], v[160:163], v[192:195], v[60:63]
	v_mfma_f32_16x16x32_bf16 v[56:59], v[168:171], v[192:195], v[56:59]
	v_mfma_f32_16x16x32_bf16 v[44:47], v[160:163], v[200:203], v[44:47]
	v_mfma_f32_16x16x32_bf16 v[40:43], v[168:171], v[200:203], v[40:43]
	v_mfma_f32_16x16x32_bf16 v[28:31], v[160:163], v[208:211], v[28:31]
	v_mfma_f32_16x16x32_bf16 v[24:27], v[168:171], v[208:211], v[24:27]
	v_mfma_f32_16x16x32_bf16 v[12:15], v[160:163], v[216:219], v[12:15]
	v_mfma_f32_16x16x32_bf16 v[8:11], v[168:171], v[216:219], v[8:11]
	s_setprio 0
	s_setprio 1
	v_mfma_f32_16x16x32_bf16 v[52:55], v[172:175], v[188:191], 0
	v_mfma_f32_16x16x32_bf16 v[48:51], v[180:183], v[188:191], 0
	v_mfma_f32_16x16x32_bf16 v[36:39], v[172:175], v[196:199], 0
	v_mfma_f32_16x16x32_bf16 v[32:35], v[180:183], v[196:199], 0
	v_mfma_f32_16x16x32_bf16 v[20:23], v[172:175], v[204:207], 0
	v_mfma_f32_16x16x32_bf16 v[16:19], v[180:183], v[204:207], 0
	v_mfma_f32_16x16x32_bf16 v[4:7], v[172:175], v[212:215], 0
	v_mfma_f32_16x16x32_bf16 v[0:3], v[180:183], v[212:215], 0
	v_mfma_f32_16x16x32_bf16 v[52:55], v[176:179], v[192:195], v[52:55]
	v_mfma_f32_16x16x32_bf16 v[48:51], v[184:187], v[192:195], v[48:51]
	v_mfma_f32_16x16x32_bf16 v[36:39], v[176:179], v[200:203], v[36:39]
	v_mfma_f32_16x16x32_bf16 v[32:35], v[184:187], v[200:203], v[32:35]
	v_mfma_f32_16x16x32_bf16 v[20:23], v[176:179], v[208:211], v[20:23]
	v_mfma_f32_16x16x32_bf16 v[16:19], v[184:187], v[208:211], v[16:19]
	v_mfma_f32_16x16x32_bf16 v[4:7], v[176:179], v[216:219], v[4:7]
	v_mfma_f32_16x16x32_bf16 v[0:3], v[184:187], v[216:219], v[0:3]
	s_setprio 0
	s_barrier
	s_add_i32 s66, 0, 0x18000
	v_add_u32_e32 v140, s66, v154
	s_add_i32 s67, 0, 0x1c000
	ds_read_b128 v[150:153], v140
	ds_read_b128 v[160:163], v140 offset:1024
	ds_read_b128 v[164:167], v140 offset:2048
	ds_read_b128 v[168:171], v140 offset:3072
	v_add_u32_e32 v140, s67, v154
	ds_read_b128 v[172:175], v140
	ds_read_b128 v[176:179], v140 offset:1024
	ds_read_b128 v[180:183], v140 offset:2048
	ds_read_b128 v[184:187], v140 offset:3072
	s_add_u32 s34, s46, 0x40000
	s_addc_u32 s35, s47, 0
	s_mov_b32 m0, s55
	v_lshl_add_u64 v[228:229], s[34:35], 0, v[132:133]
	ds_read_b128 v[188:191], v159 offset:32768
	ds_read_b128 v[192:195], v159 offset:33792
	ds_read_b128 v[196:199], v159 offset:34816
	ds_read_b128 v[200:203], v159 offset:35840
	ds_read_b128 v[204:207], v159 offset:36864
	ds_read_b128 v[208:211], v159 offset:37888
	ds_read_b128 v[212:215], v159 offset:38912
	ds_read_b128 v[216:219], v159 offset:39936
	global_load_lds_dwordx4 v[228:229], off
	v_lshl_add_u64 v[228:229], s[34:35], 0, v[136:137]
	s_mov_b32 m0, s56
	s_nop 0
	global_load_lds_dwordx4 v[228:229], off
	s_waitcnt vmcnt(8)
	s_waitcnt lgkmcnt(0)
	s_barrier
	s_setprio 1
	s_waitcnt lgkmcnt(0)
	v_mfma_f32_16x16x32_bf16 v[124:127], v[150:153], v[188:191], v[124:127]
	v_mfma_f32_16x16x32_bf16 v[120:123], v[164:167], v[188:191], v[120:123]
	v_mfma_f32_16x16x32_bf16 v[108:111], v[150:153], v[196:199], v[108:111]
	v_mfma_f32_16x16x32_bf16 v[104:107], v[164:167], v[196:199], v[104:107]
	v_mfma_f32_16x16x32_bf16 v[92:95], v[150:153], v[204:207], v[92:95]
	v_mfma_f32_16x16x32_bf16 v[88:91], v[164:167], v[204:207], v[88:91]
	v_mfma_f32_16x16x32_bf16 v[76:79], v[150:153], v[212:215], v[76:79]
	v_mfma_f32_16x16x32_bf16 v[72:75], v[164:167], v[212:215], v[72:75]
	v_mfma_f32_16x16x32_bf16 v[124:127], v[160:163], v[192:195], v[124:127]
	v_mfma_f32_16x16x32_bf16 v[120:123], v[168:171], v[192:195], v[120:123]
	v_mfma_f32_16x16x32_bf16 v[108:111], v[160:163], v[200:203], v[108:111]
	v_mfma_f32_16x16x32_bf16 v[104:107], v[168:171], v[200:203], v[104:107]
	v_mfma_f32_16x16x32_bf16 v[92:95], v[160:163], v[208:211], v[92:95]
	v_mfma_f32_16x16x32_bf16 v[88:91], v[168:171], v[208:211], v[88:91]
	v_mfma_f32_16x16x32_bf16 v[76:79], v[160:163], v[216:219], v[76:79]
	v_mfma_f32_16x16x32_bf16 v[72:75], v[168:171], v[216:219], v[72:75]
	s_setprio 0
	s_setprio 1
	v_mfma_f32_16x16x32_bf16 v[116:119], v[172:175], v[188:191], v[116:119]
	v_mfma_f32_16x16x32_bf16 v[112:115], v[180:183], v[188:191], v[112:115]
	v_mfma_f32_16x16x32_bf16 v[100:103], v[172:175], v[196:199], v[100:103]
	v_mfma_f32_16x16x32_bf16 v[96:99], v[180:183], v[196:199], v[96:99]
	v_mfma_f32_16x16x32_bf16 v[84:87], v[172:175], v[204:207], v[84:87]
	v_mfma_f32_16x16x32_bf16 v[80:83], v[180:183], v[204:207], v[80:83]
	v_mfma_f32_16x16x32_bf16 v[68:71], v[172:175], v[212:215], v[68:71]
	v_mfma_f32_16x16x32_bf16 v[64:67], v[180:183], v[212:215], v[64:67]
	v_mfma_f32_16x16x32_bf16 v[116:119], v[176:179], v[192:195], v[116:119]
	v_mfma_f32_16x16x32_bf16 v[112:115], v[184:187], v[192:195], v[112:115]
	v_mfma_f32_16x16x32_bf16 v[100:103], v[176:179], v[200:203], v[100:103]
	v_mfma_f32_16x16x32_bf16 v[96:99], v[184:187], v[200:203], v[96:99]
	v_mfma_f32_16x16x32_bf16 v[84:87], v[176:179], v[208:211], v[84:87]
	v_mfma_f32_16x16x32_bf16 v[80:83], v[184:187], v[208:211], v[80:83]
	v_mfma_f32_16x16x32_bf16 v[68:71], v[176:179], v[216:219], v[68:71]
	v_mfma_f32_16x16x32_bf16 v[64:67], v[184:187], v[216:219], v[64:67]
	s_setprio 0
	s_barrier
	s_add_i32 s34, s66, s50
	v_lshl_add_u64 v[220:221], v[220:221], 0, s[26:27]
	s_mov_b32 m0, s34
	ds_read_b128 v[188:191], v159 offset:49152
	ds_read_b128 v[192:195], v159 offset:50176
	ds_read_b128 v[196:199], v159 offset:51200
	ds_read_b128 v[200:203], v159 offset:52224
	ds_read_b128 v[204:207], v159 offset:53248
	ds_read_b128 v[208:211], v159 offset:54272
	ds_read_b128 v[212:215], v159 offset:55296
	ds_read_b128 v[216:219], v159 offset:56320
	global_load_lds_dwordx4 v[220:221], off
	s_add_i32 m0, s34, 0x2000
	s_add_u32 s34, s44, 0x40080
	v_lshl_add_u64 v[220:221], v[222:223], 0, s[26:27]
	s_addc_u32 s35, s45, 0
	s_add_i32 s44, s67, s50
	global_load_lds_dwordx4 v[220:221], off
	v_lshl_add_u64 v[220:221], s[34:35], 0, v[134:135]
	s_mov_b32 m0, s44
	s_nop 0
	global_load_lds_dwordx4 v[220:221], off
	v_lshl_add_u64 v[220:221], s[34:35], 0, v[138:139]
	s_add_i32 m0, s44, 0x2000
	s_nop 0
	global_load_lds_dwordx4 v[220:221], off
	v_lshl_add_u64 v[220:221], v[224:225], 0, s[26:27]
	s_mov_b32 m0, s58
	s_nop 0
	global_load_lds_dwordx4 v[220:221], off
	v_lshl_add_u64 v[220:221], v[226:227], 0, s[26:27]
	s_mov_b32 m0, s59
	s_nop 0
	global_load_lds_dwordx4 v[220:221], off
	s_waitcnt vmcnt(8)
	s_waitcnt lgkmcnt(0)
	s_barrier
	s_setprio 1
	s_waitcnt lgkmcnt(0)
	v_mfma_f32_16x16x32_bf16 v[60:63], v[150:153], v[188:191], v[60:63]
	v_mfma_f32_16x16x32_bf16 v[56:59], v[164:167], v[188:191], v[56:59]
	v_mfma_f32_16x16x32_bf16 v[44:47], v[150:153], v[196:199], v[44:47]
	v_mfma_f32_16x16x32_bf16 v[40:43], v[164:167], v[196:199], v[40:43]
	v_mfma_f32_16x16x32_bf16 v[28:31], v[150:153], v[204:207], v[28:31]
	v_mfma_f32_16x16x32_bf16 v[24:27], v[164:167], v[204:207], v[24:27]
	v_mfma_f32_16x16x32_bf16 v[12:15], v[150:153], v[212:215], v[12:15]
	v_mfma_f32_16x16x32_bf16 v[8:11], v[164:167], v[212:215], v[8:11]
	v_mfma_f32_16x16x32_bf16 v[60:63], v[160:163], v[192:195], v[60:63]
	v_mfma_f32_16x16x32_bf16 v[56:59], v[168:171], v[192:195], v[56:59]
	v_mfma_f32_16x16x32_bf16 v[44:47], v[160:163], v[200:203], v[44:47]
	v_mfma_f32_16x16x32_bf16 v[40:43], v[168:171], v[200:203], v[40:43]
	v_mfma_f32_16x16x32_bf16 v[28:31], v[160:163], v[208:211], v[28:31]
	v_mfma_f32_16x16x32_bf16 v[24:27], v[168:171], v[208:211], v[24:27]
	v_mfma_f32_16x16x32_bf16 v[12:15], v[160:163], v[216:219], v[12:15]
	v_mfma_f32_16x16x32_bf16 v[8:11], v[168:171], v[216:219], v[8:11]
	s_setprio 0
	s_setprio 1
	v_mfma_f32_16x16x32_bf16 v[52:55], v[172:175], v[188:191], v[52:55]
	v_mfma_f32_16x16x32_bf16 v[48:51], v[180:183], v[188:191], v[48:51]
	v_mfma_f32_16x16x32_bf16 v[36:39], v[172:175], v[196:199], v[36:39]
	v_mfma_f32_16x16x32_bf16 v[32:35], v[180:183], v[196:199], v[32:35]
	v_mfma_f32_16x16x32_bf16 v[20:23], v[172:175], v[204:207], v[20:23]
	v_mfma_f32_16x16x32_bf16 v[16:19], v[180:183], v[204:207], v[16:19]
	v_mfma_f32_16x16x32_bf16 v[4:7], v[172:175], v[212:215], v[4:7]
	v_mfma_f32_16x16x32_bf16 v[0:3], v[180:183], v[212:215], v[0:3]
	v_mfma_f32_16x16x32_bf16 v[52:55], v[176:179], v[192:195], v[52:55]
	v_mfma_f32_16x16x32_bf16 v[48:51], v[184:187], v[192:195], v[48:51]
	v_mfma_f32_16x16x32_bf16 v[36:39], v[176:179], v[200:203], v[36:39]
	v_mfma_f32_16x16x32_bf16 v[32:35], v[184:187], v[200:203], v[32:35]
	v_mfma_f32_16x16x32_bf16 v[20:23], v[176:179], v[208:211], v[20:23]
	v_mfma_f32_16x16x32_bf16 v[16:19], v[184:187], v[208:211], v[16:19]
	v_mfma_f32_16x16x32_bf16 v[4:7], v[176:179], v[216:219], v[4:7]
	v_mfma_f32_16x16x32_bf16 v[0:3], v[184:187], v[216:219], v[0:3]
	s_setprio 0
	s_barrier
	s_add_i32 s65, s65, 2
	s_add_u32 s42, s42, 0x100
	s_addc_u32 s43, s43, 0
	s_add_u32 s31, s31, 0x100
	s_addc_u32 s37, s37, 0

.LBB0_2000:
	s_ashr_i32 s27, s26, 31
	s_lshl_b64 s[12:13], s[26:27], 19
	s_add_u32 s28, s20, s12
	s_addc_u32 s29, s21, s13
	s_and_b64 s[12:13], s[6:7], exec
	s_cselect_b32 s12, s29, s39
	s_cselect_b32 s13, s28, s38
	s_ashr_i32 s25, s24, 31
	s_lshl_b64 s[30:31], s[24:25], 19
	s_add_u32 s30, s3, s30
	s_addc_u32 s31, s44, s31
	s_and_b64 s[34:35], s[6:7], exec
	s_cselect_b32 s25, s31, s41
	s_cselect_b32 s27, s30, s40
	s_add_u32 s38, s38, 0x40080
	s_addc_u32 s39, s39, 0
	s_add_u32 s37, s40, 0x100
	s_addc_u32 s59, s41, 0
	s_mov_b32 s60, -2
	s_waitcnt lgkmcnt(0)
	s_cmp_lg_u32 s58, 1
	s_cselect_b32 s100, s99, 0
	s_cmp_lg_u32 s100, 0
	s_cbranch_scc0 .Lmy_nobar2_21
	s_barrier
.Lmy_nobar2_21:
	ds_read_b128 v[146:149], v153
	ds_read_b128 v[158:161], v153 offset:1024
	ds_read_b128 v[162:165], v153 offset:2048
	ds_read_b128 v[166:169], v153 offset:3072
	ds_read_b128 v[170:173], v154
	ds_read_b128 v[174:177], v154 offset:1024
	ds_read_b128 v[178:181], v154 offset:2048
	ds_read_b128 v[182:185], v154 offset:3072
	s_add_u32 s34, s38, 0xfffc0080
	s_addc_u32 s35, s39, -1
	s_cmp_eq_u32 s60, 12
	s_cselect_b32 s43, s12, s35
	s_cselect_b32 s42, s13, s34
	s_cselect_b32 s41, s25, s59
	s_cselect_b32 s40, s27, s37
	v_lshl_add_u64 v[218:219], s[38:39], 0, v[138:139]
	s_add_i32 m0, s46, 0xc000
	ds_read_b128 v[186:189], v155
	ds_read_b128 v[190:193], v155 offset:1024
	ds_read_b128 v[194:197], v155 offset:2048
	ds_read_b128 v[198:201], v155 offset:3072
	ds_read_b128 v[202:205], v155 offset:4096
	ds_read_b128 v[206:209], v155 offset:5120
	ds_read_b128 v[210:213], v155 offset:6144
	ds_read_b128 v[214:217], v155 offset:7168
	global_load_lds_dwordx4 v[218:219], off
	v_lshl_add_u64 v[218:219], s[38:39], 0, v[140:141]
	s_add_i32 m0, s46, 0xe000
	s_nop 0
	global_load_lds_dwordx4 v[218:219], off
	s_waitcnt vmcnt(8)
	s_waitcnt lgkmcnt(0)
	s_barrier
	s_setprio 1
	s_waitcnt lgkmcnt(0)
	v_mfma_f32_16x16x32_bf16 v[124:127], v[146:149], v[186:189], 0
	v_mfma_f32_16x16x32_bf16 v[120:123], v[162:165], v[186:189], 0
	v_mfma_f32_16x16x32_bf16 v[108:111], v[146:149], v[194:197], 0
	v_mfma_f32_16x16x32_bf16 v[104:107], v[162:165], v[194:197], 0
	v_mfma_f32_16x16x32_bf16 v[92:95], v[146:149], v[202:205], 0
	v_mfma_f32_16x16x32_bf16 v[88:91], v[162:165], v[202:205], 0
	v_mfma_f32_16x16x32_bf16 v[76:79], v[146:149], v[210:213], 0
	v_mfma_f32_16x16x32_bf16 v[72:75], v[162:165], v[210:213], 0
	v_mfma_f32_16x16x32_bf16 v[124:127], v[158:161], v[190:193], v[124:127]
	v_mfma_f32_16x16x32_bf16 v[120:123], v[166:169], v[190:193], v[120:123]
	v_mfma_f32_16x16x32_bf16 v[108:111], v[158:161], v[198:201], v[108:111]
	v_mfma_f32_16x16x32_bf16 v[104:107], v[166:169], v[198:201], v[104:107]
	v_mfma_f32_16x16x32_bf16 v[92:95], v[158:161], v[206:209], v[92:95]
	v_mfma_f32_16x16x32_bf16 v[88:91], v[166:169], v[206:209], v[88:91]
	v_mfma_f32_16x16x32_bf16 v[76:79], v[158:161], v[214:217], v[76:79]
	v_mfma_f32_16x16x32_bf16 v[72:75], v[166:169], v[214:217], v[72:75]
	s_setprio 0
	s_setprio 1
	v_mfma_f32_16x16x32_bf16 v[116:119], v[170:173], v[186:189], 0
	v_mfma_f32_16x16x32_bf16 v[112:115], v[178:181], v[186:189], 0
	v_mfma_f32_16x16x32_bf16 v[100:103], v[170:173], v[194:197], 0
	v_mfma_f32_16x16x32_bf16 v[96:99], v[178:181], v[194:197], 0
	v_mfma_f32_16x16x32_bf16 v[84:87], v[170:173], v[202:205], 0
	v_mfma_f32_16x16x32_bf16 v[80:83], v[178:181], v[202:205], 0
	v_mfma_f32_16x16x32_bf16 v[68:71], v[170:173], v[210:213], 0
	v_mfma_f32_16x16x32_bf16 v[64:67], v[178:181], v[210:213], 0
	v_mfma_f32_16x16x32_bf16 v[116:119], v[174:177], v[190:193], v[116:119]
	v_mfma_f32_16x16x32_bf16 v[112:115], v[182:185], v[190:193], v[112:115]
	v_mfma_f32_16x16x32_bf16 v[100:103], v[174:177], v[198:201], v[100:103]
	v_mfma_f32_16x16x32_bf16 v[96:99], v[182:185], v[198:201], v[96:99]
	v_mfma_f32_16x16x32_bf16 v[84:87], v[174:177], v[206:209], v[84:87]
	v_mfma_f32_16x16x32_bf16 v[80:83], v[182:185], v[206:209], v[80:83]
	v_mfma_f32_16x16x32_bf16 v[68:71], v[174:177], v[214:217], v[68:71]
	v_mfma_f32_16x16x32_bf16 v[64:67], v[182:185], v[214:217], v[64:67]
	s_setprio 0
	s_barrier
	s_add_i32 s34, s56, s45
	v_lshl_add_u64 v[218:219], s[40:41], 0, v[132:133]
	s_mov_b32 m0, s34
	ds_read_b128 v[186:189], v155 offset:16384
	ds_read_b128 v[190:193], v155 offset:17408
	ds_read_b128 v[194:197], v155 offset:18432
	ds_read_b128 v[198:201], v155 offset:19456
	ds_read_b128 v[202:205], v155 offset:20480
	ds_read_b128 v[206:209], v155 offset:21504
	ds_read_b128 v[210:213], v155 offset:22528
	ds_read_b128 v[214:217], v155 offset:23552
	global_load_lds_dwordx4 v[218:219], off
	s_add_i32 m0, s34, 0x2000
	s_add_u32 s34, s40, 0x40000
	v_lshl_add_u64 v[220:221], s[40:41], 0, v[136:137]
	s_addc_u32 s35, s41, 0
	s_add_i32 s61, s57, s45
	global_load_lds_dwordx4 v[220:221], off
	v_lshl_add_u64 v[222:223], s[34:35], 0, v[132:133]
	s_mov_b32 m0, s61
	v_lshl_add_u64 v[224:225], s[42:43], 0, v[134:135]
	global_load_lds_dwordx4 v[222:223], off
	v_lshl_add_u64 v[222:223], s[34:35], 0, v[136:137]
	s_add_i32 m0, s61, 0x2000
	s_nop 0
	global_load_lds_dwordx4 v[222:223], off
	v_lshl_add_u64 v[222:223], s[42:43], 0, v[130:131]
	s_mov_b32 m0, s46
	s_nop 0
	global_load_lds_dwordx4 v[222:223], off
	s_mov_b32 m0, s47
	s_nop 0
	global_load_lds_dwordx4 v[224:225], off
	s_waitcnt vmcnt(8)
	s_waitcnt lgkmcnt(0)
	s_barrier
	s_setprio 1
	s_waitcnt lgkmcnt(0)
	v_mfma_f32_16x16x32_bf16 v[60:63], v[146:149], v[186:189], 0
	v_mfma_f32_16x16x32_bf16 v[56:59], v[162:165], v[186:189], 0
	v_mfma_f32_16x16x32_bf16 v[44:47], v[146:149], v[194:197], 0
	v_mfma_f32_16x16x32_bf16 v[40:43], v[162:165], v[194:197], 0
	v_mfma_f32_16x16x32_bf16 v[28:31], v[146:149], v[202:205], 0
	v_mfma_f32_16x16x32_bf16 v[24:27], v[162:165], v[202:205], 0
	v_mfma_f32_16x16x32_bf16 v[12:15], v[146:149], v[210:213], 0
	v_mfma_f32_16x16x32_bf16 v[8:11], v[162:165], v[210:213], 0
	v_mfma_f32_16x16x32_bf16 v[60:63], v[158:161], v[190:193], v[60:63]
	v_mfma_f32_16x16x32_bf16 v[56:59], v[166:169], v[190:193], v[56:59]
	v_mfma_f32_16x16x32_bf16 v[44:47], v[158:161], v[198:201], v[44:47]
	v_mfma_f32_16x16x32_bf16 v[40:43], v[166:169], v[198:201], v[40:43]
	v_mfma_f32_16x16x32_bf16 v[28:31], v[158:161], v[206:209], v[28:31]
	v_mfma_f32_16x16x32_bf16 v[24:27], v[166:169], v[206:209], v[24:27]
	v_mfma_f32_16x16x32_bf16 v[12:15], v[158:161], v[214:217], v[12:15]
	v_mfma_f32_16x16x32_bf16 v[8:11], v[166:169], v[214:217], v[8:11]
	s_setprio 0
	s_setprio 1
	v_mfma_f32_16x16x32_bf16 v[52:55], v[170:173], v[186:189], 0
	v_mfma_f32_16x16x32_bf16 v[48:51], v[178:181], v[186:189], 0
	v_mfma_f32_16x16x32_bf16 v[36:39], v[170:173], v[194:197], 0
	v_mfma_f32_16x16x32_bf16 v[32:35], v[178:181], v[194:197], 0
	v_mfma_f32_16x16x32_bf16 v[20:23], v[170:173], v[202:205], 0
	v_mfma_f32_16x16x32_bf16 v[16:19], v[178:181], v[202:205], 0
	v_mfma_f32_16x16x32_bf16 v[4:7], v[170:173], v[210:213], 0
	v_mfma_f32_16x16x32_bf16 v[0:3], v[178:181], v[210:213], 0
	v_mfma_f32_16x16x32_bf16 v[52:55], v[174:177], v[190:193], v[52:55]
	v_mfma_f32_16x16x32_bf16 v[48:51], v[182:185], v[190:193], v[48:51]
	v_mfma_f32_16x16x32_bf16 v[36:39], v[174:177], v[198:201], v[36:39]
	v_mfma_f32_16x16x32_bf16 v[32:35], v[182:185], v[198:201], v[32:35]
	v_mfma_f32_16x16x32_bf16 v[20:23], v[174:177], v[206:209], v[20:23]
	v_mfma_f32_16x16x32_bf16 v[16:19], v[182:185], v[206:209], v[16:19]
	v_mfma_f32_16x16x32_bf16 v[4:7], v[174:177], v[214:217], v[4:7]
	v_mfma_f32_16x16x32_bf16 v[0:3], v[182:185], v[214:217], v[0:3]
	s_setprio 0
	s_barrier
	s_add_i32 s61, 0, 0x18000
	v_add_u32_e32 v157, s61, v151
	s_add_i32 s62, 0, 0x1c000
	ds_read_b128 v[146:149], v157
	ds_read_b128 v[158:161], v157 offset:1024
	ds_read_b128 v[162:165], v157 offset:2048
	ds_read_b128 v[166:169], v157 offset:3072
	v_add_u32_e32 v157, s62, v151
	ds_read_b128 v[170:173], v157
	ds_read_b128 v[174:177], v157 offset:1024
	ds_read_b128 v[178:181], v157 offset:2048
	ds_read_b128 v[182:185], v157 offset:3072
	s_add_u32 s34, s42, 0x40000
	s_addc_u32 s35, s43, 0
	s_mov_b32 m0, s48
	v_lshl_add_u64 v[226:227], s[34:35], 0, v[130:131]
	ds_read_b128 v[186:189], v155 offset:32768
	ds_read_b128 v[190:193], v155 offset:33792
	ds_read_b128 v[194:197], v155 offset:34816
	ds_read_b128 v[198:201], v155 offset:35840
	ds_read_b128 v[202:205], v155 offset:36864
	ds_read_b128 v[206:209], v155 offset:37888
	ds_read_b128 v[210:213], v155 offset:38912
	ds_read_b128 v[214:217], v155 offset:39936
	global_load_lds_dwordx4 v[226:227], off
	v_lshl_add_u64 v[226:227], s[34:35], 0, v[134:135]
	s_mov_b32 m0, s49
	s_nop 0
	global_load_lds_dwordx4 v[226:227], off
	s_waitcnt vmcnt(8)
	s_waitcnt lgkmcnt(0)
	s_barrier
	s_setprio 1
	s_waitcnt lgkmcnt(0)
	v_mfma_f32_16x16x32_bf16 v[124:127], v[146:149], v[186:189], v[124:127]
	v_mfma_f32_16x16x32_bf16 v[120:123], v[162:165], v[186:189], v[120:123]
	v_mfma_f32_16x16x32_bf16 v[108:111], v[146:149], v[194:197], v[108:111]
	v_mfma_f32_16x16x32_bf16 v[104:107], v[162:165], v[194:197], v[104:107]
	v_mfma_f32_16x16x32_bf16 v[92:95], v[146:149], v[202:205], v[92:95]
	v_mfma_f32_16x16x32_bf16 v[88:91], v[162:165], v[202:205], v[88:91]
	v_mfma_f32_16x16x32_bf16 v[76:79], v[146:149], v[210:213], v[76:79]
	v_mfma_f32_16x16x32_bf16 v[72:75], v[162:165], v[210:213], v[72:75]
	v_mfma_f32_16x16x32_bf16 v[124:127], v[158:161], v[190:193], v[124:127]
	v_mfma_f32_16x16x32_bf16 v[120:123], v[166:169], v[190:193], v[120:123]
	v_mfma_f32_16x16x32_bf16 v[108:111], v[158:161], v[198:201], v[108:111]
	v_mfma_f32_16x16x32_bf16 v[104:107], v[166:169], v[198:201], v[104:107]
	v_mfma_f32_16x16x32_bf16 v[92:95], v[158:161], v[206:209], v[92:95]
	v_mfma_f32_16x16x32_bf16 v[88:91], v[166:169], v[206:209], v[88:91]
	v_mfma_f32_16x16x32_bf16 v[76:79], v[158:161], v[214:217], v[76:79]
	v_mfma_f32_16x16x32_bf16 v[72:75], v[166:169], v[214:217], v[72:75]
	s_setprio 0
	s_setprio 1
	v_mfma_f32_16x16x32_bf16 v[116:119], v[170:173], v[186:189], v[116:119]
	v_mfma_f32_16x16x32_bf16 v[112:115], v[178:181], v[186:189], v[112:115]
	v_mfma_f32_16x16x32_bf16 v[100:103], v[170:173], v[194:197], v[100:103]
	v_mfma_f32_16x16x32_bf16 v[96:99], v[178:181], v[194:197], v[96:99]
	v_mfma_f32_16x16x32_bf16 v[84:87], v[170:173], v[202:205], v[84:87]
	v_mfma_f32_16x16x32_bf16 v[80:83], v[178:181], v[202:205], v[80:83]
	v_mfma_f32_16x16x32_bf16 v[68:71], v[170:173], v[210:213], v[68:71]
	v_mfma_f32_16x16x32_bf16 v[64:67], v[178:181], v[210:213], v[64:67]
	v_mfma_f32_16x16x32_bf16 v[116:119], v[174:177], v[190:193], v[116:119]
	v_mfma_f32_16x16x32_bf16 v[112:115], v[182:185], v[190:193], v[112:115]
	v_mfma_f32_16x16x32_bf16 v[100:103], v[174:177], v[198:201], v[100:103]
	v_mfma_f32_16x16x32_bf16 v[96:99], v[182:185], v[198:201], v[96:99]
	v_mfma_f32_16x16x32_bf16 v[84:87], v[174:177], v[206:209], v[84:87]
	v_mfma_f32_16x16x32_bf16 v[80:83], v[182:185], v[206:209], v[80:83]
	v_mfma_f32_16x16x32_bf16 v[68:71], v[174:177], v[214:217], v[68:71]
	v_mfma_f32_16x16x32_bf16 v[64:67], v[182:185], v[214:217], v[64:67]
	s_setprio 0
	s_barrier
	s_add_i32 s34, s61, s45
	v_lshl_add_u64 v[218:219], v[218:219], 0, s[10:11]
	s_mov_b32 m0, s34
	ds_read_b128 v[186:189], v155 offset:49152
	ds_read_b128 v[190:193], v155 offset:50176
	ds_read_b128 v[194:197], v155 offset:51200
	ds_read_b128 v[198:201], v155 offset:52224
	ds_read_b128 v[202:205], v155 offset:53248
	ds_read_b128 v[206:209], v155 offset:54272
	ds_read_b128 v[210:213], v155 offset:55296
	ds_read_b128 v[214:217], v155 offset:56320
	global_load_lds_dwordx4 v[218:219], off
	s_add_i32 m0, s34, 0x2000
	s_add_u32 s34, s40, 0x40080
	v_lshl_add_u64 v[218:219], v[220:221], 0, s[10:11]
	s_addc_u32 s35, s41, 0
	s_add_i32 s40, s62, s45
	global_load_lds_dwordx4 v[218:219], off
	v_lshl_add_u64 v[218:219], s[34:35], 0, v[132:133]
	s_mov_b32 m0, s40
	s_nop 0
	global_load_lds_dwordx4 v[218:219], off
	v_lshl_add_u64 v[218:219], s[34:35], 0, v[136:137]
	s_add_i32 m0, s40, 0x2000
	s_nop 0
	global_load_lds_dwordx4 v[218:219], off
	v_lshl_add_u64 v[218:219], v[222:223], 0, s[10:11]
	s_mov_b32 m0, s51
	s_nop 0
	global_load_lds_dwordx4 v[218:219], off
	v_lshl_add_u64 v[218:219], v[224:225], 0, s[10:11]
	s_mov_b32 m0, s52
	s_nop 0
	global_load_lds_dwordx4 v[218:219], off
	s_waitcnt vmcnt(8)
	s_waitcnt lgkmcnt(0)
	s_barrier
	s_setprio 1
	s_waitcnt lgkmcnt(0)
	v_mfma_f32_16x16x32_bf16 v[60:63], v[146:149], v[186:189], v[60:63]
	v_mfma_f32_16x16x32_bf16 v[56:59], v[162:165], v[186:189], v[56:59]
	v_mfma_f32_16x16x32_bf16 v[44:47], v[146:149], v[194:197], v[44:47]
	v_mfma_f32_16x16x32_bf16 v[40:43], v[162:165], v[194:197], v[40:43]
	v_mfma_f32_16x16x32_bf16 v[28:31], v[146:149], v[202:205], v[28:31]
	v_mfma_f32_16x16x32_bf16 v[24:27], v[162:165], v[202:205], v[24:27]
	v_mfma_f32_16x16x32_bf16 v[12:15], v[146:149], v[210:213], v[12:15]
	v_mfma_f32_16x16x32_bf16 v[8:11], v[162:165], v[210:213], v[8:11]
	v_mfma_f32_16x16x32_bf16 v[60:63], v[158:161], v[190:193], v[60:63]
	v_mfma_f32_16x16x32_bf16 v[56:59], v[166:169], v[190:193], v[56:59]
	v_mfma_f32_16x16x32_bf16 v[44:47], v[158:161], v[198:201], v[44:47]
	v_mfma_f32_16x16x32_bf16 v[40:43], v[166:169], v[198:201], v[40:43]
	v_mfma_f32_16x16x32_bf16 v[28:31], v[158:161], v[206:209], v[28:31]
	v_mfma_f32_16x16x32_bf16 v[24:27], v[166:169], v[206:209], v[24:27]
	v_mfma_f32_16x16x32_bf16 v[12:15], v[158:161], v[214:217], v[12:15]
	v_mfma_f32_16x16x32_bf16 v[8:11], v[166:169], v[214:217], v[8:11]
	s_setprio 0
	s_setprio 1
	v_mfma_f32_16x16x32_bf16 v[52:55], v[170:173], v[186:189], v[52:55]
	v_mfma_f32_16x16x32_bf16 v[48:51], v[178:181], v[186:189], v[48:51]
	v_mfma_f32_16x16x32_bf16 v[36:39], v[170:173], v[194:197], v[36:39]
	v_mfma_f32_16x16x32_bf16 v[32:35], v[178:181], v[194:197], v[32:35]
	v_mfma_f32_16x16x32_bf16 v[20:23], v[170:173], v[202:205], v[20:23]
	v_mfma_f32_16x16x32_bf16 v[16:19], v[178:181], v[202:205], v[16:19]
	v_mfma_f32_16x16x32_bf16 v[4:7], v[170:173], v[210:213], v[4:7]
	v_mfma_f32_16x16x32_bf16 v[0:3], v[178:181], v[210:213], v[0:3]
	v_mfma_f32_16x16x32_bf16 v[52:55], v[174:177], v[190:193], v[52:55]
	v_mfma_f32_16x16x32_bf16 v[48:51], v[182:185], v[190:193], v[48:51]
	v_mfma_f32_16x16x32_bf16 v[36:39], v[174:177], v[198:201], v[36:39]
	v_mfma_f32_16x16x32_bf16 v[32:35], v[182:185], v[198:201], v[32:35]
	v_mfma_f32_16x16x32_bf16 v[20:23], v[174:177], v[206:209], v[20:23]
	v_mfma_f32_16x16x32_bf16 v[16:19], v[182:185], v[206:209], v[16:19]
	v_mfma_f32_16x16x32_bf16 v[4:7], v[174:177], v[214:217], v[4:7]
	v_mfma_f32_16x16x32_bf16 v[0:3], v[182:185], v[214:217], v[0:3]
	s_setprio 0
	s_barrier
	s_add_i32 s60, s60, 2
	s_add_u32 s38, s38, 0x100
	s_addc_u32 s39, s39, 0
	s_add_u32 s37, s37, 0x100
	s_addc_u32 s59, s59, 0

.LBB0_2090:
	s_ashr_i32 s19, s18, 31
	s_lshl_b64 s[20:21], s[18:19], 19
	s_add_u32 s20, s14, s20
	s_addc_u32 s21, s15, s21
	s_and_b64 s[22:23], s[4:5], exec
	s_cselect_b32 s19, s21, s27
	s_cselect_b32 s52, s20, s26
	s_ashr_i32 s11, s10, 31
	s_lshl_b64 s[22:23], s[10:11], 19
	s_add_u32 s22, s39, s22
	s_addc_u32 s23, s40, s23
	s_and_b64 s[30:31], s[4:5], exec
	s_cselect_b32 s11, s23, s29
	s_cselect_b32 s53, s22, s28
	s_add_u32 s26, s26, 0x40080
	s_addc_u32 s27, s27, 0
	s_add_u32 s54, s28, 0x100
	s_addc_u32 s55, s29, 0
	s_mov_b32 s56, -2
	s_cmp_lg_u32 s50, 1
	s_cselect_b32 s100, s99, 0
	s_cmp_lg_u32 s100, 0
	s_cbranch_scc0 .Lmy_nobar2_22
	s_barrier
.Lmy_nobar2_22:
	ds_read_b128 v[146:149], v153
	ds_read_b128 v[156:159], v153 offset:1024
	ds_read_b128 v[160:163], v153 offset:2048
	ds_read_b128 v[164:167], v153 offset:3072
	ds_read_b128 v[168:171], v154
	ds_read_b128 v[172:175], v154 offset:1024
	ds_read_b128 v[176:179], v154 offset:2048
	ds_read_b128 v[180:183], v154 offset:3072
	s_add_u32 s28, s26, 0xfffc0080
	s_addc_u32 s29, s27, -1
	s_cmp_eq_u32 s56, 12
	s_cselect_b32 s31, s19, s29
	s_cselect_b32 s30, s52, s28
	s_cselect_b32 s29, s11, s55
	s_cselect_b32 s28, s53, s54
	v_lshl_add_u64 v[216:217], s[26:27], 0, v[138:139]
	s_add_i32 m0, s25, 0xc000
	ds_read_b128 v[184:187], v155
	ds_read_b128 v[188:191], v155 offset:1024
	ds_read_b128 v[192:195], v155 offset:2048
	ds_read_b128 v[196:199], v155 offset:3072
	ds_read_b128 v[200:203], v155 offset:4096
	ds_read_b128 v[204:207], v155 offset:5120
	ds_read_b128 v[208:211], v155 offset:6144
	ds_read_b128 v[212:215], v155 offset:7168
	global_load_lds_dwordx4 v[216:217], off
	v_lshl_add_u64 v[216:217], s[26:27], 0, v[140:141]
	s_add_i32 m0, s25, 0xe000
	s_nop 0
	global_load_lds_dwordx4 v[216:217], off
	s_waitcnt vmcnt(8)
	s_waitcnt lgkmcnt(0)
	s_barrier
	s_setprio 1
	s_waitcnt lgkmcnt(0)
	v_mfma_f32_16x16x32_bf16 v[124:127], v[146:149], v[184:187], 0
	v_mfma_f32_16x16x32_bf16 v[120:123], v[160:163], v[184:187], 0
	v_mfma_f32_16x16x32_bf16 v[108:111], v[146:149], v[192:195], 0
	v_mfma_f32_16x16x32_bf16 v[104:107], v[160:163], v[192:195], 0
	v_mfma_f32_16x16x32_bf16 v[92:95], v[146:149], v[200:203], 0
	v_mfma_f32_16x16x32_bf16 v[88:91], v[160:163], v[200:203], 0
	v_mfma_f32_16x16x32_bf16 v[76:79], v[146:149], v[208:211], 0
	v_mfma_f32_16x16x32_bf16 v[72:75], v[160:163], v[208:211], 0
	v_mfma_f32_16x16x32_bf16 v[124:127], v[156:159], v[188:191], v[124:127]
	v_mfma_f32_16x16x32_bf16 v[120:123], v[164:167], v[188:191], v[120:123]
	v_mfma_f32_16x16x32_bf16 v[108:111], v[156:159], v[196:199], v[108:111]
	v_mfma_f32_16x16x32_bf16 v[104:107], v[164:167], v[196:199], v[104:107]
	v_mfma_f32_16x16x32_bf16 v[92:95], v[156:159], v[204:207], v[92:95]
	v_mfma_f32_16x16x32_bf16 v[88:91], v[164:167], v[204:207], v[88:91]
	v_mfma_f32_16x16x32_bf16 v[76:79], v[156:159], v[212:215], v[76:79]
	v_mfma_f32_16x16x32_bf16 v[72:75], v[164:167], v[212:215], v[72:75]
	s_setprio 0
	s_setprio 1
	v_mfma_f32_16x16x32_bf16 v[116:119], v[168:171], v[184:187], 0
	v_mfma_f32_16x16x32_bf16 v[112:115], v[176:179], v[184:187], 0
	v_mfma_f32_16x16x32_bf16 v[100:103], v[168:171], v[192:195], 0
	v_mfma_f32_16x16x32_bf16 v[96:99], v[176:179], v[192:195], 0
	v_mfma_f32_16x16x32_bf16 v[84:87], v[168:171], v[200:203], 0
	v_mfma_f32_16x16x32_bf16 v[80:83], v[176:179], v[200:203], 0
	v_mfma_f32_16x16x32_bf16 v[68:71], v[168:171], v[208:211], 0
	v_mfma_f32_16x16x32_bf16 v[64:67], v[176:179], v[208:211], 0
	v_mfma_f32_16x16x32_bf16 v[116:119], v[172:175], v[188:191], v[116:119]
	v_mfma_f32_16x16x32_bf16 v[112:115], v[180:183], v[188:191], v[112:115]
	v_mfma_f32_16x16x32_bf16 v[100:103], v[172:175], v[196:199], v[100:103]
	v_mfma_f32_16x16x32_bf16 v[96:99], v[180:183], v[196:199], v[96:99]
	v_mfma_f32_16x16x32_bf16 v[84:87], v[172:175], v[204:207], v[84:87]
	v_mfma_f32_16x16x32_bf16 v[80:83], v[180:183], v[204:207], v[80:83]
	v_mfma_f32_16x16x32_bf16 v[68:71], v[172:175], v[212:215], v[68:71]
	v_mfma_f32_16x16x32_bf16 v[64:67], v[180:183], v[212:215], v[64:67]
	s_setprio 0
	s_barrier
	s_add_i32 s34, s47, s38
	v_lshl_add_u64 v[216:217], s[28:29], 0, v[134:135]
	s_mov_b32 m0, s34
	ds_read_b128 v[184:187], v155 offset:16384
	ds_read_b128 v[188:191], v155 offset:17408
	ds_read_b128 v[192:195], v155 offset:18432
	ds_read_b128 v[196:199], v155 offset:19456
	ds_read_b128 v[200:203], v155 offset:20480
	ds_read_b128 v[204:207], v155 offset:21504
	ds_read_b128 v[208:211], v155 offset:22528
	ds_read_b128 v[212:215], v155 offset:23552
	global_load_lds_dwordx4 v[216:217], off
	s_add_i32 m0, s34, 0x2000
	s_add_u32 s34, s28, 0x40000
	v_lshl_add_u64 v[218:219], s[28:29], 0, v[130:131]
	s_addc_u32 s35, s29, 0
	s_add_i32 s57, s48, s38
	global_load_lds_dwordx4 v[218:219], off
	v_lshl_add_u64 v[220:221], s[34:35], 0, v[134:135]
	s_mov_b32 m0, s57
	v_lshl_add_u64 v[222:223], s[30:31], 0, v[132:133]
	global_load_lds_dwordx4 v[220:221], off
	v_lshl_add_u64 v[220:221], s[34:35], 0, v[130:131]
	s_add_i32 m0, s57, 0x2000
	s_nop 0
	global_load_lds_dwordx4 v[220:221], off
	v_lshl_add_u64 v[220:221], s[30:31], 0, v[136:137]
	s_mov_b32 m0, s25
	s_nop 0
	global_load_lds_dwordx4 v[220:221], off
	s_mov_b32 m0, s42
	s_nop 0
	global_load_lds_dwordx4 v[222:223], off
	s_waitcnt vmcnt(8)
	s_waitcnt lgkmcnt(0)
	s_barrier
	s_setprio 1
	s_waitcnt lgkmcnt(0)
	v_mfma_f32_16x16x32_bf16 v[60:63], v[146:149], v[184:187], 0
	v_mfma_f32_16x16x32_bf16 v[56:59], v[160:163], v[184:187], 0
	v_mfma_f32_16x16x32_bf16 v[44:47], v[146:149], v[192:195], 0
	v_mfma_f32_16x16x32_bf16 v[40:43], v[160:163], v[192:195], 0
	v_mfma_f32_16x16x32_bf16 v[28:31], v[146:149], v[200:203], 0
	v_mfma_f32_16x16x32_bf16 v[24:27], v[160:163], v[200:203], 0
	v_mfma_f32_16x16x32_bf16 v[12:15], v[146:149], v[208:211], 0
	v_mfma_f32_16x16x32_bf16 v[8:11], v[160:163], v[208:211], 0
	v_mfma_f32_16x16x32_bf16 v[60:63], v[156:159], v[188:191], v[60:63]
	v_mfma_f32_16x16x32_bf16 v[56:59], v[164:167], v[188:191], v[56:59]
	v_mfma_f32_16x16x32_bf16 v[44:47], v[156:159], v[196:199], v[44:47]
	v_mfma_f32_16x16x32_bf16 v[40:43], v[164:167], v[196:199], v[40:43]
	v_mfma_f32_16x16x32_bf16 v[28:31], v[156:159], v[204:207], v[28:31]
	v_mfma_f32_16x16x32_bf16 v[24:27], v[164:167], v[204:207], v[24:27]
	v_mfma_f32_16x16x32_bf16 v[12:15], v[156:159], v[212:215], v[12:15]
	v_mfma_f32_16x16x32_bf16 v[8:11], v[164:167], v[212:215], v[8:11]
	s_setprio 0
	s_setprio 1
	v_mfma_f32_16x16x32_bf16 v[52:55], v[168:171], v[184:187], 0
	v_mfma_f32_16x16x32_bf16 v[48:51], v[176:179], v[184:187], 0
	v_mfma_f32_16x16x32_bf16 v[36:39], v[168:171], v[192:195], 0
	v_mfma_f32_16x16x32_bf16 v[32:35], v[176:179], v[192:195], 0
	v_mfma_f32_16x16x32_bf16 v[20:23], v[168:171], v[200:203], 0
	v_mfma_f32_16x16x32_bf16 v[16:19], v[176:179], v[200:203], 0
	v_mfma_f32_16x16x32_bf16 v[4:7], v[168:171], v[208:211], 0
	v_mfma_f32_16x16x32_bf16 v[0:3], v[176:179], v[208:211], 0
	v_mfma_f32_16x16x32_bf16 v[52:55], v[172:175], v[188:191], v[52:55]
	v_mfma_f32_16x16x32_bf16 v[48:51], v[180:183], v[188:191], v[48:51]
	v_mfma_f32_16x16x32_bf16 v[36:39], v[172:175], v[196:199], v[36:39]
	v_mfma_f32_16x16x32_bf16 v[32:35], v[180:183], v[196:199], v[32:35]
	v_mfma_f32_16x16x32_bf16 v[20:23], v[172:175], v[204:207], v[20:23]
	v_mfma_f32_16x16x32_bf16 v[16:19], v[180:183], v[204:207], v[16:19]
	v_mfma_f32_16x16x32_bf16 v[4:7], v[172:175], v[212:215], v[4:7]
	v_mfma_f32_16x16x32_bf16 v[0:3], v[180:183], v[212:215], v[0:3]
	s_setprio 0
	s_barrier
	s_add_i32 s34, 0, 0x18000
	s_add_i32 s35, 0, 0x1c000
	v_add_u32_e32 v164, s34, v150
	v_add_u32_e32 v180, s35, v150
	ds_read_b128 v[146:149], v164
	ds_read_b128 v[156:159], v164 offset:1024
	ds_read_b128 v[160:163], v164 offset:2048
	ds_read_b128 v[164:167], v164 offset:3072
	ds_read_b128 v[168:171], v180
	ds_read_b128 v[172:175], v180 offset:1024
	ds_read_b128 v[176:179], v180 offset:2048
	ds_read_b128 v[180:183], v180 offset:3072
	s_add_u32 s30, s30, 0x40000
	s_addc_u32 s31, s31, 0
	s_mov_b32 m0, s43
	v_lshl_add_u64 v[224:225], s[30:31], 0, v[136:137]
	ds_read_b128 v[184:187], v155 offset:32768
	ds_read_b128 v[188:191], v155 offset:33792
	ds_read_b128 v[192:195], v155 offset:34816
	ds_read_b128 v[196:199], v155 offset:35840
	ds_read_b128 v[200:203], v155 offset:36864
	ds_read_b128 v[204:207], v155 offset:37888
	ds_read_b128 v[208:211], v155 offset:38912
	ds_read_b128 v[212:215], v155 offset:39936
	global_load_lds_dwordx4 v[224:225], off
	v_lshl_add_u64 v[224:225], s[30:31], 0, v[132:133]
	s_mov_b32 m0, s44
	s_nop 0
	global_load_lds_dwordx4 v[224:225], off
	s_waitcnt vmcnt(8)
	s_waitcnt lgkmcnt(0)
	s_barrier
	s_setprio 1
	s_waitcnt lgkmcnt(0)
	v_mfma_f32_16x16x32_bf16 v[124:127], v[146:149], v[184:187], v[124:127]
	v_mfma_f32_16x16x32_bf16 v[120:123], v[160:163], v[184:187], v[120:123]
	v_mfma_f32_16x16x32_bf16 v[108:111], v[146:149], v[192:195], v[108:111]
	v_mfma_f32_16x16x32_bf16 v[104:107], v[160:163], v[192:195], v[104:107]
	v_mfma_f32_16x16x32_bf16 v[92:95], v[146:149], v[200:203], v[92:95]
	v_mfma_f32_16x16x32_bf16 v[88:91], v[160:163], v[200:203], v[88:91]
	v_mfma_f32_16x16x32_bf16 v[76:79], v[146:149], v[208:211], v[76:79]
	v_mfma_f32_16x16x32_bf16 v[72:75], v[160:163], v[208:211], v[72:75]
	v_mfma_f32_16x16x32_bf16 v[124:127], v[156:159], v[188:191], v[124:127]
	v_mfma_f32_16x16x32_bf16 v[120:123], v[164:167], v[188:191], v[120:123]
	v_mfma_f32_16x16x32_bf16 v[108:111], v[156:159], v[196:199], v[108:111]
	v_mfma_f32_16x16x32_bf16 v[104:107], v[164:167], v[196:199], v[104:107]
	v_mfma_f32_16x16x32_bf16 v[92:95], v[156:159], v[204:207], v[92:95]
	v_mfma_f32_16x16x32_bf16 v[88:91], v[164:167], v[204:207], v[88:91]
	v_mfma_f32_16x16x32_bf16 v[76:79], v[156:159], v[212:215], v[76:79]
	v_mfma_f32_16x16x32_bf16 v[72:75], v[164:167], v[212:215], v[72:75]
	s_setprio 0
	s_setprio 1
	v_mfma_f32_16x16x32_bf16 v[116:119], v[168:171], v[184:187], v[116:119]
	v_mfma_f32_16x16x32_bf16 v[112:115], v[176:179], v[184:187], v[112:115]
	v_mfma_f32_16x16x32_bf16 v[100:103], v[168:171], v[192:195], v[100:103]
	v_mfma_f32_16x16x32_bf16 v[96:99], v[176:179], v[192:195], v[96:99]
	v_mfma_f32_16x16x32_bf16 v[84:87], v[168:171], v[200:203], v[84:87]
	v_mfma_f32_16x16x32_bf16 v[80:83], v[176:179], v[200:203], v[80:83]
	v_mfma_f32_16x16x32_bf16 v[68:71], v[168:171], v[208:211], v[68:71]
	v_mfma_f32_16x16x32_bf16 v[64:67], v[176:179], v[208:211], v[64:67]
	v_mfma_f32_16x16x32_bf16 v[116:119], v[172:175], v[188:191], v[116:119]
	v_mfma_f32_16x16x32_bf16 v[112:115], v[180:183], v[188:191], v[112:115]
	v_mfma_f32_16x16x32_bf16 v[100:103], v[172:175], v[196:199], v[100:103]
	v_mfma_f32_16x16x32_bf16 v[96:99], v[180:183], v[196:199], v[96:99]
	v_mfma_f32_16x16x32_bf16 v[84:87], v[172:175], v[204:207], v[84:87]
	v_mfma_f32_16x16x32_bf16 v[80:83], v[180:183], v[204:207], v[80:83]
	v_mfma_f32_16x16x32_bf16 v[68:71], v[172:175], v[212:215], v[68:71]
	v_mfma_f32_16x16x32_bf16 v[64:67], v[180:183], v[212:215], v[64:67]
	s_setprio 0
	s_barrier
	s_add_i32 s30, s34, s38
	v_lshl_add_u64 v[216:217], v[216:217], 0, s[6:7]
	s_mov_b32 m0, s30
	ds_read_b128 v[184:187], v155 offset:49152
	ds_read_b128 v[188:191], v155 offset:50176
	ds_read_b128 v[192:195], v155 offset:51200
	ds_read_b128 v[196:199], v155 offset:52224
	ds_read_b128 v[200:203], v155 offset:53248
	ds_read_b128 v[204:207], v155 offset:54272
	ds_read_b128 v[208:211], v155 offset:55296
	ds_read_b128 v[212:215], v155 offset:56320
	global_load_lds_dwordx4 v[216:217], off
	s_add_i32 m0, s30, 0x2000
	s_add_u32 s28, s28, 0x40080
	v_lshl_add_u64 v[216:217], v[218:219], 0, s[6:7]
	s_addc_u32 s29, s29, 0
	s_add_i32 s30, s35, s38
	global_load_lds_dwordx4 v[216:217], off
	v_lshl_add_u64 v[216:217], s[28:29], 0, v[134:135]
	s_mov_b32 m0, s30
	s_nop 0
	global_load_lds_dwordx4 v[216:217], off
	v_lshl_add_u64 v[216:217], s[28:29], 0, v[130:131]
	s_add_i32 m0, s30, 0x2000
	s_nop 0
	global_load_lds_dwordx4 v[216:217], off
	v_lshl_add_u64 v[216:217], v[220:221], 0, s[6:7]
	s_mov_b32 m0, s45
	s_nop 0
	global_load_lds_dwordx4 v[216:217], off
	v_lshl_add_u64 v[216:217], v[222:223], 0, s[6:7]
	s_mov_b32 m0, s46
	s_nop 0
	global_load_lds_dwordx4 v[216:217], off
	s_waitcnt vmcnt(8)
	s_waitcnt lgkmcnt(0)
	s_barrier
	s_setprio 1
	s_waitcnt lgkmcnt(0)
	v_mfma_f32_16x16x32_bf16 v[60:63], v[146:149], v[184:187], v[60:63]
	v_mfma_f32_16x16x32_bf16 v[56:59], v[160:163], v[184:187], v[56:59]
	v_mfma_f32_16x16x32_bf16 v[44:47], v[146:149], v[192:195], v[44:47]
	v_mfma_f32_16x16x32_bf16 v[40:43], v[160:163], v[192:195], v[40:43]
	v_mfma_f32_16x16x32_bf16 v[28:31], v[146:149], v[200:203], v[28:31]
	v_mfma_f32_16x16x32_bf16 v[24:27], v[160:163], v[200:203], v[24:27]
	v_mfma_f32_16x16x32_bf16 v[12:15], v[146:149], v[208:211], v[12:15]
	v_mfma_f32_16x16x32_bf16 v[8:11], v[160:163], v[208:211], v[8:11]
	v_mfma_f32_16x16x32_bf16 v[60:63], v[156:159], v[188:191], v[60:63]
	v_mfma_f32_16x16x32_bf16 v[56:59], v[164:167], v[188:191], v[56:59]
	v_mfma_f32_16x16x32_bf16 v[44:47], v[156:159], v[196:199], v[44:47]
	v_mfma_f32_16x16x32_bf16 v[40:43], v[164:167], v[196:199], v[40:43]
	v_mfma_f32_16x16x32_bf16 v[28:31], v[156:159], v[204:207], v[28:31]
	v_mfma_f32_16x16x32_bf16 v[24:27], v[164:167], v[204:207], v[24:27]
	v_mfma_f32_16x16x32_bf16 v[12:15], v[156:159], v[212:215], v[12:15]
	v_mfma_f32_16x16x32_bf16 v[8:11], v[164:167], v[212:215], v[8:11]
	s_setprio 0
	s_setprio 1
	v_mfma_f32_16x16x32_bf16 v[52:55], v[168:171], v[184:187], v[52:55]
	v_mfma_f32_16x16x32_bf16 v[48:51], v[176:179], v[184:187], v[48:51]
	v_mfma_f32_16x16x32_bf16 v[36:39], v[168:171], v[192:195], v[36:39]
	v_mfma_f32_16x16x32_bf16 v[32:35], v[176:179], v[192:195], v[32:35]
	v_mfma_f32_16x16x32_bf16 v[20:23], v[168:171], v[200:203], v[20:23]
	v_mfma_f32_16x16x32_bf16 v[16:19], v[176:179], v[200:203], v[16:19]
	v_mfma_f32_16x16x32_bf16 v[4:7], v[168:171], v[208:211], v[4:7]
	v_mfma_f32_16x16x32_bf16 v[0:3], v[176:179], v[208:211], v[0:3]
	v_mfma_f32_16x16x32_bf16 v[52:55], v[172:175], v[188:191], v[52:55]
	v_mfma_f32_16x16x32_bf16 v[48:51], v[180:183], v[188:191], v[48:51]
	v_mfma_f32_16x16x32_bf16 v[36:39], v[172:175], v[196:199], v[36:39]
	v_mfma_f32_16x16x32_bf16 v[32:35], v[180:183], v[196:199], v[32:35]
	v_mfma_f32_16x16x32_bf16 v[20:23], v[172:175], v[204:207], v[20:23]
	v_mfma_f32_16x16x32_bf16 v[16:19], v[180:183], v[204:207], v[16:19]
	v_mfma_f32_16x16x32_bf16 v[4:7], v[172:175], v[212:215], v[4:7]
	v_mfma_f32_16x16x32_bf16 v[0:3], v[180:183], v[212:215], v[0:3]
	s_setprio 0
	s_barrier
	s_add_i32 s56, s56, 2
	s_add_u32 s26, s26, 0x100
	s_addc_u32 s27, s27, 0
	s_add_u32 s54, s54, 0x100
	s_addc_u32 s55, s55, 0

.LBB0_2173:
	s_add_u32 s28, s28, 0xb0080
	s_addc_u32 s29, s29, 0
	s_add_u32 s54, s30, 0x100
	s_addc_u32 s55, s31, 0
	s_mov_b32 s56, -2
	s_cmp_lg_u32 s45, 1
	s_cselect_b32 s100, s99, 0
	s_cmp_lg_u32 s100, 0
	s_cbranch_scc0 .Lmy_nobar2_23
	s_barrier
.Lmy_nobar2_23:
	ds_read_b128 v[144:147], v153
	ds_read_b128 v[156:159], v153 offset:1024
	ds_read_b128 v[160:163], v153 offset:2048
	ds_read_b128 v[164:167], v153 offset:3072
	ds_read_b128 v[168:171], v154
	ds_read_b128 v[172:175], v154 offset:1024
	ds_read_b128 v[176:179], v154 offset:2048
	ds_read_b128 v[180:183], v154 offset:3072
	s_add_u32 s30, s28, 0xfff50080
	s_addc_u32 s31, s29, -1
	s_cmp_eq_u32 s56, 40
	s_cselect_b32 s37, s1, s31
	s_cselect_b32 s36, s0, s30
	s_cselect_b32 s31, s27, s55
	s_cselect_b32 s30, s26, s54
	v_lshl_add_u64 v[148:149], s[28:29], 0, v[128:129]
	s_add_i32 m0, s41, 0xc000
	ds_read_b128 v[184:187], v155
	ds_read_b128 v[188:191], v155 offset:1024
	ds_read_b128 v[192:195], v155 offset:2048
	ds_read_b128 v[196:199], v155 offset:3072
	ds_read_b128 v[200:203], v155 offset:4096
	ds_read_b128 v[204:207], v155 offset:5120
	ds_read_b128 v[208:211], v155 offset:6144
	ds_read_b128 v[212:215], v155 offset:7168
	global_load_lds_dwordx4 v[148:149], off
	v_lshl_add_u64 v[148:149], s[28:29], 0, v[138:139]
	s_add_i32 m0, s41, 0xe000
	s_nop 0
	global_load_lds_dwordx4 v[148:149], off
	s_waitcnt vmcnt(8)
	s_waitcnt lgkmcnt(0)
	s_barrier
	s_setprio 1
	s_waitcnt lgkmcnt(0)
	v_mfma_f32_16x16x32_bf16 v[124:127], v[144:147], v[184:187], 0
	v_mfma_f32_16x16x32_bf16 v[120:123], v[160:163], v[184:187], 0
	v_mfma_f32_16x16x32_bf16 v[108:111], v[144:147], v[192:195], 0
	v_mfma_f32_16x16x32_bf16 v[104:107], v[160:163], v[192:195], 0
	v_mfma_f32_16x16x32_bf16 v[92:95], v[144:147], v[200:203], 0
	v_mfma_f32_16x16x32_bf16 v[88:91], v[160:163], v[200:203], 0
	v_mfma_f32_16x16x32_bf16 v[76:79], v[144:147], v[208:211], 0
	v_mfma_f32_16x16x32_bf16 v[72:75], v[160:163], v[208:211], 0
	v_mfma_f32_16x16x32_bf16 v[124:127], v[156:159], v[188:191], v[124:127]
	v_mfma_f32_16x16x32_bf16 v[120:123], v[164:167], v[188:191], v[120:123]
	v_mfma_f32_16x16x32_bf16 v[108:111], v[156:159], v[196:199], v[108:111]
	v_mfma_f32_16x16x32_bf16 v[104:107], v[164:167], v[196:199], v[104:107]
	v_mfma_f32_16x16x32_bf16 v[92:95], v[156:159], v[204:207], v[92:95]
	v_mfma_f32_16x16x32_bf16 v[88:91], v[164:167], v[204:207], v[88:91]
	v_mfma_f32_16x16x32_bf16 v[76:79], v[156:159], v[212:215], v[76:79]
	v_mfma_f32_16x16x32_bf16 v[72:75], v[164:167], v[212:215], v[72:75]
	s_setprio 0
	s_setprio 1
	v_mfma_f32_16x16x32_bf16 v[116:119], v[168:171], v[184:187], 0
	v_mfma_f32_16x16x32_bf16 v[112:115], v[176:179], v[184:187], 0
	v_mfma_f32_16x16x32_bf16 v[100:103], v[168:171], v[192:195], 0
	v_mfma_f32_16x16x32_bf16 v[96:99], v[176:179], v[192:195], 0
	v_mfma_f32_16x16x32_bf16 v[84:87], v[168:171], v[200:203], 0
	v_mfma_f32_16x16x32_bf16 v[80:83], v[176:179], v[200:203], 0
	v_mfma_f32_16x16x32_bf16 v[68:71], v[168:171], v[208:211], 0
	v_mfma_f32_16x16x32_bf16 v[64:67], v[176:179], v[208:211], 0
	v_mfma_f32_16x16x32_bf16 v[116:119], v[172:175], v[188:191], v[116:119]
	v_mfma_f32_16x16x32_bf16 v[112:115], v[180:183], v[188:191], v[112:115]
	v_mfma_f32_16x16x32_bf16 v[100:103], v[172:175], v[196:199], v[100:103]
	v_mfma_f32_16x16x32_bf16 v[96:99], v[180:183], v[196:199], v[96:99]
	v_mfma_f32_16x16x32_bf16 v[84:87], v[172:175], v[204:207], v[84:87]
	v_mfma_f32_16x16x32_bf16 v[80:83], v[180:183], v[204:207], v[80:83]
	v_mfma_f32_16x16x32_bf16 v[68:71], v[172:175], v[212:215], v[68:71]
	v_mfma_f32_16x16x32_bf16 v[64:67], v[180:183], v[212:215], v[64:67]
	s_setprio 0
	s_barrier
	s_add_i32 s34, s50, s40
	v_lshl_add_u64 v[148:149], s[30:31], 0, v[132:133]
	s_mov_b32 m0, s34
	ds_read_b128 v[184:187], v155 offset:16384
	ds_read_b128 v[188:191], v155 offset:17408
	ds_read_b128 v[192:195], v155 offset:18432
	ds_read_b128 v[196:199], v155 offset:19456
	ds_read_b128 v[200:203], v155 offset:20480
	ds_read_b128 v[204:207], v155 offset:21504
	ds_read_b128 v[208:211], v155 offset:22528
	ds_read_b128 v[212:215], v155 offset:23552
	global_load_lds_dwordx4 v[148:149], off
	s_add_i32 m0, s34, 0x2000
	s_add_u32 s34, s30, 0xb0000
	v_lshl_add_u64 v[216:217], s[30:31], 0, v[136:137]
	s_addc_u32 s35, s31, 0
	s_add_i32 s57, s51, s40
	global_load_lds_dwordx4 v[216:217], off
	v_lshl_add_u64 v[218:219], s[34:35], 0, v[132:133]
	s_mov_b32 m0, s57
	v_lshl_add_u64 v[220:221], s[36:37], 0, v[134:135]
	global_load_lds_dwordx4 v[218:219], off
	v_lshl_add_u64 v[218:219], s[34:35], 0, v[136:137]
	s_add_i32 m0, s57, 0x2000
	s_nop 0
	global_load_lds_dwordx4 v[218:219], off
	v_lshl_add_u64 v[218:219], s[36:37], 0, v[130:131]
	s_mov_b32 m0, s41
	s_nop 0
	global_load_lds_dwordx4 v[218:219], off
	s_mov_b32 m0, s42
	s_nop 0
	global_load_lds_dwordx4 v[220:221], off
	s_waitcnt vmcnt(8)
	s_waitcnt lgkmcnt(0)
	s_barrier
	s_setprio 1
	s_waitcnt lgkmcnt(0)
	v_mfma_f32_16x16x32_bf16 v[60:63], v[144:147], v[184:187], 0
	v_mfma_f32_16x16x32_bf16 v[56:59], v[160:163], v[184:187], 0
	v_mfma_f32_16x16x32_bf16 v[44:47], v[144:147], v[192:195], 0
	v_mfma_f32_16x16x32_bf16 v[40:43], v[160:163], v[192:195], 0
	v_mfma_f32_16x16x32_bf16 v[28:31], v[144:147], v[200:203], 0
	v_mfma_f32_16x16x32_bf16 v[24:27], v[160:163], v[200:203], 0
	v_mfma_f32_16x16x32_bf16 v[12:15], v[144:147], v[208:211], 0
	v_mfma_f32_16x16x32_bf16 v[8:11], v[160:163], v[208:211], 0
	v_mfma_f32_16x16x32_bf16 v[60:63], v[156:159], v[188:191], v[60:63]
	v_mfma_f32_16x16x32_bf16 v[56:59], v[164:167], v[188:191], v[56:59]
	v_mfma_f32_16x16x32_bf16 v[44:47], v[156:159], v[196:199], v[44:47]
	v_mfma_f32_16x16x32_bf16 v[40:43], v[164:167], v[196:199], v[40:43]
	v_mfma_f32_16x16x32_bf16 v[28:31], v[156:159], v[204:207], v[28:31]
	v_mfma_f32_16x16x32_bf16 v[24:27], v[164:167], v[204:207], v[24:27]
	v_mfma_f32_16x16x32_bf16 v[12:15], v[156:159], v[212:215], v[12:15]
	v_mfma_f32_16x16x32_bf16 v[8:11], v[164:167], v[212:215], v[8:11]
	s_setprio 0
	s_setprio 1
	v_mfma_f32_16x16x32_bf16 v[52:55], v[168:171], v[184:187], 0
	v_mfma_f32_16x16x32_bf16 v[48:51], v[176:179], v[184:187], 0
	v_mfma_f32_16x16x32_bf16 v[36:39], v[168:171], v[192:195], 0
	v_mfma_f32_16x16x32_bf16 v[32:35], v[176:179], v[192:195], 0
	v_mfma_f32_16x16x32_bf16 v[20:23], v[168:171], v[200:203], 0
	v_mfma_f32_16x16x32_bf16 v[16:19], v[176:179], v[200:203], 0
	v_mfma_f32_16x16x32_bf16 v[4:7], v[168:171], v[208:211], 0
	v_mfma_f32_16x16x32_bf16 v[0:3], v[176:179], v[208:211], 0
	v_mfma_f32_16x16x32_bf16 v[52:55], v[172:175], v[188:191], v[52:55]
	v_mfma_f32_16x16x32_bf16 v[48:51], v[180:183], v[188:191], v[48:51]
	v_mfma_f32_16x16x32_bf16 v[36:39], v[172:175], v[196:199], v[36:39]
	v_mfma_f32_16x16x32_bf16 v[32:35], v[180:183], v[196:199], v[32:35]
	v_mfma_f32_16x16x32_bf16 v[20:23], v[172:175], v[204:207], v[20:23]
	v_mfma_f32_16x16x32_bf16 v[16:19], v[180:183], v[204:207], v[16:19]
	v_mfma_f32_16x16x32_bf16 v[4:7], v[172:175], v[212:215], v[4:7]
	v_mfma_f32_16x16x32_bf16 v[0:3], v[180:183], v[212:215], v[0:3]
	s_setprio 0
	s_barrier
	s_add_i32 s57, 0, 0x18000
	s_add_i32 s58, 0, 0x1c000
	v_add_u32_e32 v164, s57, v151
	v_add_u32_e32 v180, s58, v151
	ds_read_b128 v[144:147], v164
	ds_read_b128 v[156:159], v164 offset:1024
	ds_read_b128 v[160:163], v164 offset:2048
	ds_read_b128 v[164:167], v164 offset:3072
	ds_read_b128 v[168:171], v180
	ds_read_b128 v[172:175], v180 offset:1024
	ds_read_b128 v[176:179], v180 offset:2048
	ds_read_b128 v[180:183], v180 offset:3072
	s_add_u32 s34, s36, 0xb0000
	s_addc_u32 s35, s37, 0
	s_mov_b32 m0, s43
	v_lshl_add_u64 v[222:223], s[34:35], 0, v[130:131]
	ds_read_b128 v[184:187], v155 offset:32768
	ds_read_b128 v[188:191], v155 offset:33792
	ds_read_b128 v[192:195], v155 offset:34816
	ds_read_b128 v[196:199], v155 offset:35840
	ds_read_b128 v[200:203], v155 offset:36864
	ds_read_b128 v[204:207], v155 offset:37888
	ds_read_b128 v[208:211], v155 offset:38912
	ds_read_b128 v[212:215], v155 offset:39936
	global_load_lds_dwordx4 v[222:223], off
	v_lshl_add_u64 v[222:223], s[34:35], 0, v[134:135]
	s_mov_b32 m0, s44
	s_nop 0
	global_load_lds_dwordx4 v[222:223], off
	s_waitcnt vmcnt(8)
	s_waitcnt lgkmcnt(0)
	s_barrier
	s_setprio 1
	s_waitcnt lgkmcnt(0)
	v_mfma_f32_16x16x32_bf16 v[124:127], v[144:147], v[184:187], v[124:127]
	v_mfma_f32_16x16x32_bf16 v[120:123], v[160:163], v[184:187], v[120:123]
	v_mfma_f32_16x16x32_bf16 v[108:111], v[144:147], v[192:195], v[108:111]
	v_mfma_f32_16x16x32_bf16 v[104:107], v[160:163], v[192:195], v[104:107]
	v_mfma_f32_16x16x32_bf16 v[92:95], v[144:147], v[200:203], v[92:95]
	v_mfma_f32_16x16x32_bf16 v[88:91], v[160:163], v[200:203], v[88:91]
	v_mfma_f32_16x16x32_bf16 v[76:79], v[144:147], v[208:211], v[76:79]
	v_mfma_f32_16x16x32_bf16 v[72:75], v[160:163], v[208:211], v[72:75]
	v_mfma_f32_16x16x32_bf16 v[124:127], v[156:159], v[188:191], v[124:127]
	v_mfma_f32_16x16x32_bf16 v[120:123], v[164:167], v[188:191], v[120:123]
	v_mfma_f32_16x16x32_bf16 v[108:111], v[156:159], v[196:199], v[108:111]
	v_mfma_f32_16x16x32_bf16 v[104:107], v[164:167], v[196:199], v[104:107]
	v_mfma_f32_16x16x32_bf16 v[92:95], v[156:159], v[204:207], v[92:95]
	v_mfma_f32_16x16x32_bf16 v[88:91], v[164:167], v[204:207], v[88:91]
	v_mfma_f32_16x16x32_bf16 v[76:79], v[156:159], v[212:215], v[76:79]
	v_mfma_f32_16x16x32_bf16 v[72:75], v[164:167], v[212:215], v[72:75]
	s_setprio 0
	s_setprio 1
	v_mfma_f32_16x16x32_bf16 v[116:119], v[168:171], v[184:187], v[116:119]
	v_mfma_f32_16x16x32_bf16 v[112:115], v[176:179], v[184:187], v[112:115]
	v_mfma_f32_16x16x32_bf16 v[100:103], v[168:171], v[192:195], v[100:103]
	v_mfma_f32_16x16x32_bf16 v[96:99], v[176:179], v[192:195], v[96:99]
	v_mfma_f32_16x16x32_bf16 v[84:87], v[168:171], v[200:203], v[84:87]
	v_mfma_f32_16x16x32_bf16 v[80:83], v[176:179], v[200:203], v[80:83]
	v_mfma_f32_16x16x32_bf16 v[68:71], v[168:171], v[208:211], v[68:71]
	v_mfma_f32_16x16x32_bf16 v[64:67], v[176:179], v[208:211], v[64:67]
	v_mfma_f32_16x16x32_bf16 v[116:119], v[172:175], v[188:191], v[116:119]
	v_mfma_f32_16x16x32_bf16 v[112:115], v[180:183], v[188:191], v[112:115]
	v_mfma_f32_16x16x32_bf16 v[100:103], v[172:175], v[196:199], v[100:103]
	v_mfma_f32_16x16x32_bf16 v[96:99], v[180:183], v[196:199], v[96:99]
	v_mfma_f32_16x16x32_bf16 v[84:87], v[172:175], v[204:207], v[84:87]
	v_mfma_f32_16x16x32_bf16 v[80:83], v[180:183], v[204:207], v[80:83]
	v_mfma_f32_16x16x32_bf16 v[68:71], v[172:175], v[212:215], v[68:71]
	v_mfma_f32_16x16x32_bf16 v[64:67], v[180:183], v[212:215], v[64:67]
	s_setprio 0
	s_barrier
	s_add_i32 s34, s57, s40
	v_lshl_add_u64 v[148:149], v[148:149], 0, s[8:9]
	s_mov_b32 m0, s34
	ds_read_b128 v[184:187], v155 offset:49152
	ds_read_b128 v[188:191], v155 offset:50176
	ds_read_b128 v[192:195], v155 offset:51200
	ds_read_b128 v[196:199], v155 offset:52224
	ds_read_b128 v[200:203], v155 offset:53248
	ds_read_b128 v[204:207], v155 offset:54272
	ds_read_b128 v[208:211], v155 offset:55296
	ds_read_b128 v[212:215], v155 offset:56320
	global_load_lds_dwordx4 v[148:149], off
	s_add_i32 m0, s34, 0x2000
	s_add_u32 s30, s30, 0xb0080
	v_lshl_add_u64 v[148:149], v[216:217], 0, s[8:9]
	s_addc_u32 s31, s31, 0
	s_add_i32 s34, s58, s40
	global_load_lds_dwordx4 v[148:149], off
	v_lshl_add_u64 v[148:149], s[30:31], 0, v[132:133]
	s_mov_b32 m0, s34
	s_nop 0
	global_load_lds_dwordx4 v[148:149], off
	v_lshl_add_u64 v[148:149], s[30:31], 0, v[136:137]
	s_add_i32 m0, s34, 0x2000
	s_nop 0
	global_load_lds_dwordx4 v[148:149], off
	v_lshl_add_u64 v[148:149], v[218:219], 0, s[8:9]
	s_mov_b32 m0, s46
	s_nop 0
	global_load_lds_dwordx4 v[148:149], off
	v_lshl_add_u64 v[148:149], v[220:221], 0, s[8:9]
	s_mov_b32 m0, s47
	s_nop 0
	global_load_lds_dwordx4 v[148:149], off
	s_waitcnt vmcnt(8)
	s_waitcnt lgkmcnt(0)
	s_barrier
	s_setprio 1
	s_waitcnt lgkmcnt(0)
	v_mfma_f32_16x16x32_bf16 v[60:63], v[144:147], v[184:187], v[60:63]
	v_mfma_f32_16x16x32_bf16 v[56:59], v[160:163], v[184:187], v[56:59]
	v_mfma_f32_16x16x32_bf16 v[44:47], v[144:147], v[192:195], v[44:47]
	v_mfma_f32_16x16x32_bf16 v[40:43], v[160:163], v[192:195], v[40:43]
	v_mfma_f32_16x16x32_bf16 v[28:31], v[144:147], v[200:203], v[28:31]
	v_mfma_f32_16x16x32_bf16 v[24:27], v[160:163], v[200:203], v[24:27]
	v_mfma_f32_16x16x32_bf16 v[12:15], v[144:147], v[208:211], v[12:15]
	v_mfma_f32_16x16x32_bf16 v[8:11], v[160:163], v[208:211], v[8:11]
	v_mfma_f32_16x16x32_bf16 v[60:63], v[156:159], v[188:191], v[60:63]
	v_mfma_f32_16x16x32_bf16 v[56:59], v[164:167], v[188:191], v[56:59]
	v_mfma_f32_16x16x32_bf16 v[44:47], v[156:159], v[196:199], v[44:47]
	v_mfma_f32_16x16x32_bf16 v[40:43], v[164:167], v[196:199], v[40:43]
	v_mfma_f32_16x16x32_bf16 v[28:31], v[156:159], v[204:207], v[28:31]
	v_mfma_f32_16x16x32_bf16 v[24:27], v[164:167], v[204:207], v[24:27]
	v_mfma_f32_16x16x32_bf16 v[12:15], v[156:159], v[212:215], v[12:15]
	v_mfma_f32_16x16x32_bf16 v[8:11], v[164:167], v[212:215], v[8:11]
	s_setprio 0
	s_setprio 1
	v_mfma_f32_16x16x32_bf16 v[52:55], v[168:171], v[184:187], v[52:55]
	v_mfma_f32_16x16x32_bf16 v[48:51], v[176:179], v[184:187], v[48:51]
	v_mfma_f32_16x16x32_bf16 v[36:39], v[168:171], v[192:195], v[36:39]
	v_mfma_f32_16x16x32_bf16 v[32:35], v[176:179], v[192:195], v[32:35]
	v_mfma_f32_16x16x32_bf16 v[20:23], v[168:171], v[200:203], v[20:23]
	v_mfma_f32_16x16x32_bf16 v[16:19], v[176:179], v[200:203], v[16:19]
	v_mfma_f32_16x16x32_bf16 v[4:7], v[168:171], v[208:211], v[4:7]
	v_mfma_f32_16x16x32_bf16 v[0:3], v[176:179], v[208:211], v[0:3]
	v_mfma_f32_16x16x32_bf16 v[52:55], v[172:175], v[188:191], v[52:55]
	v_mfma_f32_16x16x32_bf16 v[48:51], v[180:183], v[188:191], v[48:51]
	v_mfma_f32_16x16x32_bf16 v[36:39], v[172:175], v[196:199], v[36:39]
	v_mfma_f32_16x16x32_bf16 v[32:35], v[180:183], v[196:199], v[32:35]
	v_mfma_f32_16x16x32_bf16 v[20:23], v[172:175], v[204:207], v[20:23]
	v_mfma_f32_16x16x32_bf16 v[16:19], v[180:183], v[204:207], v[16:19]
	v_mfma_f32_16x16x32_bf16 v[4:7], v[172:175], v[212:215], v[4:7]
	v_mfma_f32_16x16x32_bf16 v[0:3], v[180:183], v[212:215], v[0:3]
	s_setprio 0
	s_barrier
	s_add_i32 s56, s56, 2
	s_add_u32 s28, s28, 0x100
	s_addc_u32 s29, s29, 0
	s_add_u32 s54, s54, 0x100
	s_addc_u32 s55, s55, 0
